# residual epilogues: sum-of-squares as two packed fma chains + packed add instead of 8 packed squares and a 15-add scalar tree (40 sites, f32 accumulate unchanged)
# baseline (speedup 1.0000x reference)
; #define PG8_STAGE(bufoff, gbase, voff) do { _Pragma("unroll") for (int _i = 0; _i < 2; ++_i) \
;         __builtin_amdgcn_global_load_lds((const unsigned*)((const char*)(gbase) + (voff)[_i]), (PG8_LAS unsigned*)(lds + (bufoff) + ldsw + _i * 8192), 16, 0, 0); } while (0)
; #define PG8_LDA(dst, b, h) do { _Pragma("unroll") for (int m = 0; m < 4; ++m) _Pragma("unroll") for (int k = 0; k < 2; ++k) dst[m][k] = *(const PG8_LAS bf16x8*)(lds + PG8_SA(b, h) + aoff + m * 2048 + k * 1024); } while (0)
; #define PG8_LDB(dst, b, h) do { _Pragma("unroll") for (int n = 0; n < 2; ++n) _Pragma("unroll") for (int k = 0; k < 2; ++k) dst[n][k] = *(const PG8_LAS bf16x8*)(lds + PG8_SB(b, h) + boff + n * 2048 + k * 1024); } while (0)
; #define PG8_MMA(ai, bj, At, Bt) do { __builtin_amdgcn_s_setprio(1); _Pragma("unroll") for (int m = 0; m < 4; ++m) _Pragma("unroll") for (int n = 0; n < 2; ++n) _Pragma("unroll") for (int k = 0; k < 2; ++k) \
;         acc[ai][bj][m][n] = mma16<F16>(Bt[n][k], At[m][k], acc[ai][bj][m][n]); __builtin_amdgcn_s_setprio(0); } while (0)
; #define PG8_WAIT_V(n) asm volatile("s_waitcnt vmcnt(" #n ")" ::: "memory")
; #define PG8_WAIT_L(n) asm volatile("s_waitcnt lgkmcnt(" #n ")" ::: "memory")
; #define PG8_BAR __builtin_amdgcn_s_barrier()
; #define PG8_SCHED __builtin_amdgcn_sched_barrier(0)
; template <class Epi, class Sched, bool ALIGN_EPI = false, bool SP2 = false, bool F16 = false, bool TOKPERM = false>
; __device__ __forceinline__ void gemm_phase(PG8_LAS unsigned char* lds, const Gemm g, const Sched& S, const Epi& E, int wv) {
;     ...
;             PG8_LDB(B0, 0, 0); PG8_LDB(B1, 0, 1); PG8_SCHED; PG8_LDA(At, 0, 0); PG8_STAGE(PG8_SA(1, 1), a1 + hstep, voffA);
;             PG8_WAIT_V(8); PG8_WAIT_L(0); PG8_BAR; PG8_MMA(0, 0, At, B0); PG8_MMA(0, 1, At, B1); PG8_BAR; PG8_SCHED;
;             PG8_LDA(At, 0, 1); PG8_STAGE(PG8_SB(0, 0), b2, voffB); PG8_STAGE(PG8_SB(0, 1), b2 + hstep, voffB); PG8_STAGE(PG8_SA(0, 0), a2, voffA);
;             PG8_WAIT_V(8); PG8_WAIT_L(0); PG8_BAR; PG8_MMA(1, 0, At, B0); PG8_MMA(1, 1, At, B1); PG8_BAR; PG8_SCHED;
.LBB0_297:
	ds_read_b128 v[166:169], v149
	ds_read_b128 v[170:173], v150
	ds_read_b128 v[174:177], v151
	ds_read_b128 v[178:181], v152
	ds_read_b128 v[182:185], v153
	ds_read_b128 v[186:189], v154
	ds_read_b128 v[190:193], v155
	ds_read_b128 v[194:197], v156
	s_add_u32 s18, s16, 0x100
	s_addc_u32 s19, s17, 0
	s_cmp_eq_u32 s70, 40
	s_cselect_b32 s51, s9, s19
	s_cselect_b32 s50, s8, s18
	s_cselect_b32 s49, s11, s69
	s_cselect_b32 s48, s10, s68
	s_mov_b32 m0, s61
	v_lshl_add_u64 v[232:233], s[16:17], 0, v[138:139]
	ds_read_b128 v[198:201], v147
	ds_read_b128 v[202:205], v147 offset:1024
	ds_read_b128 v[206:209], v147 offset:2048
	ds_read_b128 v[210:213], v147 offset:3072
	ds_read_b128 v[214:217], v147 offset:4096
	ds_read_b128 v[218:221], v147 offset:5120
	ds_read_b128 v[222:225], v147 offset:6144
	ds_read_b128 v[228:231], v147 offset:7168
	global_load_lds_dwordx4 v[232:233], off
	v_lshl_add_u64 v[232:233], s[16:17], 0, v[140:141]
	s_mov_b32 m0, s62
	s_nop 0
	global_load_lds_dwordx4 v[232:233], off
	s_waitcnt vmcnt(8)
	s_waitcnt lgkmcnt(0)
	s_barrier
	s_setprio 1
	s_waitcnt lgkmcnt(0)
	v_mfma_f32_16x16x32_bf16 v[124:127], v[166:169], v[198:201], v[124:127]
	v_mfma_f32_16x16x32_bf16 v[120:123], v[174:177], v[198:201], v[120:123]
	v_mfma_f32_16x16x32_bf16 v[108:111], v[166:169], v[206:209], v[108:111]
	v_mfma_f32_16x16x32_bf16 v[104:107], v[174:177], v[206:209], v[104:107]
	v_mfma_f32_16x16x32_bf16 v[92:95], v[166:169], v[214:217], v[92:95]
	v_mfma_f32_16x16x32_bf16 v[88:91], v[174:177], v[214:217], v[88:91]
	v_mfma_f32_16x16x32_bf16 v[76:79], v[166:169], v[222:225], v[76:79]
	v_mfma_f32_16x16x32_bf16 v[72:75], v[174:177], v[222:225], v[72:75]
	v_mfma_f32_16x16x32_bf16 v[124:127], v[170:173], v[202:205], v[124:127]
	v_mfma_f32_16x16x32_bf16 v[120:123], v[178:181], v[202:205], v[120:123]
	v_mfma_f32_16x16x32_bf16 v[108:111], v[170:173], v[210:213], v[108:111]
	v_mfma_f32_16x16x32_bf16 v[104:107], v[178:181], v[210:213], v[104:107]
	v_mfma_f32_16x16x32_bf16 v[92:95], v[170:173], v[218:221], v[92:95]
	v_mfma_f32_16x16x32_bf16 v[88:91], v[178:181], v[218:221], v[88:91]
	v_mfma_f32_16x16x32_bf16 v[76:79], v[170:173], v[228:231], v[76:79]
	v_mfma_f32_16x16x32_bf16 v[72:75], v[178:181], v[228:231], v[72:75]
	s_setprio 0
	s_setprio 1
	v_mfma_f32_16x16x32_bf16 v[116:119], v[182:185], v[198:201], v[116:119]
	v_mfma_f32_16x16x32_bf16 v[112:115], v[190:193], v[198:201], v[112:115]
	v_mfma_f32_16x16x32_bf16 v[100:103], v[182:185], v[206:209], v[100:103]
	v_mfma_f32_16x16x32_bf16 v[96:99], v[190:193], v[206:209], v[96:99]
	v_mfma_f32_16x16x32_bf16 v[84:87], v[182:185], v[214:217], v[84:87]
	v_mfma_f32_16x16x32_bf16 v[80:83], v[190:193], v[214:217], v[80:83]
	v_mfma_f32_16x16x32_bf16 v[68:71], v[182:185], v[222:225], v[68:71]
	v_mfma_f32_16x16x32_bf16 v[64:67], v[190:193], v[222:225], v[64:67]
	v_mfma_f32_16x16x32_bf16 v[116:119], v[186:189], v[202:205], v[116:119]
	v_mfma_f32_16x16x32_bf16 v[112:115], v[194:197], v[202:205], v[112:115]
	v_mfma_f32_16x16x32_bf16 v[100:103], v[186:189], v[210:213], v[100:103]
	v_mfma_f32_16x16x32_bf16 v[96:99], v[194:197], v[210:213], v[96:99]
	v_mfma_f32_16x16x32_bf16 v[84:87], v[186:189], v[218:221], v[84:87]
	v_mfma_f32_16x16x32_bf16 v[80:83], v[194:197], v[218:221], v[80:83]
	v_mfma_f32_16x16x32_bf16 v[68:71], v[186:189], v[228:231], v[68:71]
	v_mfma_f32_16x16x32_bf16 v[64:67], v[194:197], v[228:231], v[64:67]
	s_setprio 0
	s_barrier
	s_mov_b32 m0, s3
	v_lshl_add_u64 v[232:233], s[48:49], 0, v[130:131]
	s_add_u32 s16, s48, 0xb0000
	ds_read_b128 v[198:201], v147 offset:16384
	ds_read_b128 v[202:205], v147 offset:17408
	ds_read_b128 v[206:209], v147 offset:18432
	ds_read_b128 v[210:213], v147 offset:19456
	ds_read_b128 v[214:217], v147 offset:20480
	ds_read_b128 v[218:221], v147 offset:21504
	ds_read_b128 v[222:225], v147 offset:22528
	ds_read_b128 v[228:231], v147 offset:23552
	global_load_lds_dwordx4 v[232:233], off
	v_lshl_add_u64 v[234:235], s[48:49], 0, v[134:135]
	s_mov_b32 m0, s21
	s_addc_u32 s17, s49, 0
	global_load_lds_dwordx4 v[234:235], off
	v_lshl_add_u64 v[236:237], s[16:17], 0, v[130:131]
	s_mov_b32 m0, s22
	v_lshl_add_u64 v[238:239], s[50:51], 0, v[132:133]
	global_load_lds_dwordx4 v[236:237], off
	v_lshl_add_u64 v[236:237], s[16:17], 0, v[134:135]
	s_mov_b32 m0, s23
	s_nop 0
	global_load_lds_dwordx4 v[236:237], off
	v_lshl_add_u64 v[236:237], s[50:51], 0, v[128:129]
	s_mov_b32 m0, s2
	s_nop 0
	global_load_lds_dwordx4 v[236:237], off
	s_mov_b32 m0, s33
	s_nop 0
	global_load_lds_dwordx4 v[238:239], off
	s_waitcnt vmcnt(8)
	s_waitcnt lgkmcnt(0)
	s_barrier
; #define PG8_STAGE(bufoff, gbase, voff) do { _Pragma("unroll") for (int _i = 0; _i < 2; ++_i) \
;         __builtin_amdgcn_global_load_lds((const unsigned*)((const char*)(gbase) + (voff)[_i]), (PG8_LAS unsigned*)(lds + (bufoff) + ldsw + _i * 8192), 16, 0, 0); } while (0)
; #define PG8_LDA(dst, b, h) do { _Pragma("unroll") for (int m = 0; m < 4; ++m) _Pragma("unroll") for (int k = 0; k < 2; ++k) dst[m][k] = *(const PG8_LAS bf16x8*)(lds + PG8_SA(b, h) + aoff + m * 2048 + k * 1024); } while (0)
; #define PG8_LDB(dst, b, h) do { _Pragma("unroll") for (int n = 0; n < 2; ++n) _Pragma("unroll") for (int k = 0; k < 2; ++k) dst[n][k] = *(const PG8_LAS bf16x8*)(lds + PG8_SB(b, h) + boff + n * 2048 + k * 1024); } while (0)
; #define PG8_MMA(ai, bj, At, Bt) do { __builtin_amdgcn_s_setprio(1); _Pragma("unroll") for (int m = 0; m < 4; ++m) _Pragma("unroll") for (int n = 0; n < 2; ++n) _Pragma("unroll") for (int k = 0; k < 2; ++k) \
;         acc[ai][bj][m][n] = mma16<F16>(Bt[n][k], At[m][k], acc[ai][bj][m][n]); __builtin_amdgcn_s_setprio(0); } while (0)
; #define PG8_WAIT_V(n) asm volatile("s_waitcnt vmcnt(" #n ")" ::: "memory")
; #define PG8_WAIT_L(n) asm volatile("s_waitcnt lgkmcnt(" #n ")" ::: "memory")
; #define PG8_BAR __builtin_amdgcn_s_barrier()
; #define PG8_SCHED __builtin_amdgcn_sched_barrier(0)
; template <class Epi, class Sched, bool ALIGN_EPI = false, bool SP2 = false, bool F16 = false, bool TOKPERM = false>
; __device__ __forceinline__ void gemm_phase(PG8_LAS unsigned char* lds, const Gemm g, const Sched& S, const Epi& E, int wv) {
;     ...
;             PG8_WAIT_V(8); PG8_WAIT_L(0); PG8_BAR; PG8_MMA(1, 0, At, B0); PG8_MMA(1, 1, At, B1); PG8_BAR; PG8_SCHED;
;             PG8_LDB(B0, 1, 0); PG8_LDB(B1, 1, 1); PG8_SCHED; PG8_LDA(At, 1, 0); PG8_STAGE(PG8_SA(0, 1), a2 + hstep, voffA);
;             PG8_WAIT_V(8); PG8_WAIT_L(0); PG8_BAR; PG8_MMA(0, 0, At, B0); PG8_MMA(0, 1, At, B1); PG8_BAR; PG8_SCHED;
	s_setprio 1
	s_waitcnt lgkmcnt(0)
	v_mfma_f32_16x16x32_bf16 v[60:63], v[166:169], v[198:201], v[60:63]
	v_mfma_f32_16x16x32_bf16 v[56:59], v[174:177], v[198:201], v[56:59]
	v_mfma_f32_16x16x32_bf16 v[44:47], v[166:169], v[206:209], v[44:47]
	v_mfma_f32_16x16x32_bf16 v[40:43], v[174:177], v[206:209], v[40:43]
	v_mfma_f32_16x16x32_bf16 v[28:31], v[166:169], v[214:217], v[28:31]
	v_mfma_f32_16x16x32_bf16 v[24:27], v[174:177], v[214:217], v[24:27]
	v_mfma_f32_16x16x32_bf16 v[12:15], v[166:169], v[222:225], v[12:15]
	v_mfma_f32_16x16x32_bf16 v[8:11], v[174:177], v[222:225], v[8:11]
	v_mfma_f32_16x16x32_bf16 v[60:63], v[170:173], v[202:205], v[60:63]
	v_mfma_f32_16x16x32_bf16 v[56:59], v[178:181], v[202:205], v[56:59]
	v_mfma_f32_16x16x32_bf16 v[44:47], v[170:173], v[210:213], v[44:47]
	v_mfma_f32_16x16x32_bf16 v[40:43], v[178:181], v[210:213], v[40:43]
	v_mfma_f32_16x16x32_bf16 v[28:31], v[170:173], v[218:221], v[28:31]
	v_mfma_f32_16x16x32_bf16 v[24:27], v[178:181], v[218:221], v[24:27]
	v_mfma_f32_16x16x32_bf16 v[12:15], v[170:173], v[228:231], v[12:15]
	v_mfma_f32_16x16x32_bf16 v[8:11], v[178:181], v[228:231], v[8:11]
	s_setprio 0
	s_setprio 1
	v_mfma_f32_16x16x32_bf16 v[52:55], v[182:185], v[198:201], v[52:55]
	v_mfma_f32_16x16x32_bf16 v[48:51], v[190:193], v[198:201], v[48:51]
	v_mfma_f32_16x16x32_bf16 v[36:39], v[182:185], v[206:209], v[36:39]
	v_mfma_f32_16x16x32_bf16 v[32:35], v[190:193], v[206:209], v[32:35]
	v_mfma_f32_16x16x32_bf16 v[20:23], v[182:185], v[214:217], v[20:23]
	v_mfma_f32_16x16x32_bf16 v[16:19], v[190:193], v[214:217], v[16:19]
	v_mfma_f32_16x16x32_bf16 v[4:7], v[182:185], v[222:225], v[4:7]
	v_mfma_f32_16x16x32_bf16 v[0:3], v[190:193], v[222:225], v[0:3]
	v_mfma_f32_16x16x32_bf16 v[52:55], v[186:189], v[202:205], v[52:55]
	v_mfma_f32_16x16x32_bf16 v[48:51], v[194:197], v[202:205], v[48:51]
	v_mfma_f32_16x16x32_bf16 v[36:39], v[186:189], v[210:213], v[36:39]
	v_mfma_f32_16x16x32_bf16 v[32:35], v[194:197], v[210:213], v[32:35]
	v_mfma_f32_16x16x32_bf16 v[20:23], v[186:189], v[218:221], v[20:23]
	v_mfma_f32_16x16x32_bf16 v[16:19], v[194:197], v[218:221], v[16:19]
	v_mfma_f32_16x16x32_bf16 v[4:7], v[186:189], v[228:231], v[4:7]
	v_mfma_f32_16x16x32_bf16 v[0:3], v[194:197], v[228:231], v[0:3]
	s_setprio 0
	s_barrier
	ds_read_b128 v[166:169], v157
	ds_read_b128 v[170:173], v158
	ds_read_b128 v[174:177], v159
	ds_read_b128 v[178:181], v160
	ds_read_b128 v[182:185], v161
	ds_read_b128 v[186:189], v162
	ds_read_b128 v[190:193], v163
	ds_read_b128 v[194:197], v164
	s_add_u32 s16, s50, 0xb0000
	s_addc_u32 s17, s51, 0
	s_mov_b32 m0, s36
	v_lshl_add_u64 v[240:241], s[16:17], 0, v[128:129]
	ds_read_b128 v[198:201], v147 offset:32768
	ds_read_b128 v[202:205], v147 offset:33792
	ds_read_b128 v[206:209], v147 offset:34816
	ds_read_b128 v[210:213], v147 offset:35840
	ds_read_b128 v[214:217], v147 offset:36864
	ds_read_b128 v[218:221], v147 offset:37888
	ds_read_b128 v[222:225], v147 offset:38912
	ds_read_b128 v[228:231], v147 offset:39936
	global_load_lds_dwordx4 v[240:241], off
	v_lshl_add_u64 v[240:241], s[16:17], 0, v[132:133]
	s_mov_b32 m0, s37
	s_nop 0
	global_load_lds_dwordx4 v[240:241], off
	s_waitcnt vmcnt(8)
	s_waitcnt lgkmcnt(0)
	s_barrier
	s_setprio 1
	s_waitcnt lgkmcnt(0)
	v_mfma_f32_16x16x32_bf16 v[124:127], v[166:169], v[198:201], v[124:127]
	v_mfma_f32_16x16x32_bf16 v[120:123], v[174:177], v[198:201], v[120:123]
	v_mfma_f32_16x16x32_bf16 v[108:111], v[166:169], v[206:209], v[108:111]
	v_mfma_f32_16x16x32_bf16 v[104:107], v[174:177], v[206:209], v[104:107]
	v_mfma_f32_16x16x32_bf16 v[92:95], v[166:169], v[214:217], v[92:95]
	v_mfma_f32_16x16x32_bf16 v[88:91], v[174:177], v[214:217], v[88:91]
	v_mfma_f32_16x16x32_bf16 v[76:79], v[166:169], v[222:225], v[76:79]
	v_mfma_f32_16x16x32_bf16 v[72:75], v[174:177], v[222:225], v[72:75]
	v_mfma_f32_16x16x32_bf16 v[124:127], v[170:173], v[202:205], v[124:127]
	v_mfma_f32_16x16x32_bf16 v[120:123], v[178:181], v[202:205], v[120:123]
	v_mfma_f32_16x16x32_bf16 v[108:111], v[170:173], v[210:213], v[108:111]
	v_mfma_f32_16x16x32_bf16 v[104:107], v[178:181], v[210:213], v[104:107]
	v_mfma_f32_16x16x32_bf16 v[92:95], v[170:173], v[218:221], v[92:95]
	v_mfma_f32_16x16x32_bf16 v[88:91], v[178:181], v[218:221], v[88:91]
	v_mfma_f32_16x16x32_bf16 v[76:79], v[170:173], v[228:231], v[76:79]
	v_mfma_f32_16x16x32_bf16 v[72:75], v[178:181], v[228:231], v[72:75]
	s_setprio 0
	s_setprio 1
	v_mfma_f32_16x16x32_bf16 v[116:119], v[182:185], v[198:201], v[116:119]
	v_mfma_f32_16x16x32_bf16 v[112:115], v[190:193], v[198:201], v[112:115]
	v_mfma_f32_16x16x32_bf16 v[100:103], v[182:185], v[206:209], v[100:103]
	v_mfma_f32_16x16x32_bf16 v[96:99], v[190:193], v[206:209], v[96:99]
	v_mfma_f32_16x16x32_bf16 v[84:87], v[182:185], v[214:217], v[84:87]
	v_mfma_f32_16x16x32_bf16 v[80:83], v[190:193], v[214:217], v[80:83]
	v_mfma_f32_16x16x32_bf16 v[68:71], v[182:185], v[222:225], v[68:71]
	v_mfma_f32_16x16x32_bf16 v[64:67], v[190:193], v[222:225], v[64:67]
	v_mfma_f32_16x16x32_bf16 v[116:119], v[186:189], v[202:205], v[116:119]
	v_mfma_f32_16x16x32_bf16 v[112:115], v[194:197], v[202:205], v[112:115]
	v_mfma_f32_16x16x32_bf16 v[100:103], v[186:189], v[210:213], v[100:103]
	v_mfma_f32_16x16x32_bf16 v[96:99], v[194:197], v[210:213], v[96:99]
	v_mfma_f32_16x16x32_bf16 v[84:87], v[186:189], v[218:221], v[84:87]
	v_mfma_f32_16x16x32_bf16 v[80:83], v[194:197], v[218:221], v[80:83]
	v_mfma_f32_16x16x32_bf16 v[68:71], v[186:189], v[228:231], v[68:71]
	v_mfma_f32_16x16x32_bf16 v[64:67], v[194:197], v[228:231], v[64:67]
	s_setprio 0
	s_barrier
; #define PG8_STAGE(bufoff, gbase, voff) do { _Pragma("unroll") for (int _i = 0; _i < 2; ++_i) \
;         __builtin_amdgcn_global_load_lds((const unsigned*)((const char*)(gbase) + (voff)[_i]), (PG8_LAS unsigned*)(lds + (bufoff) + ldsw + _i * 8192), 16, 0, 0); } while (0)
; #define PG8_LDA(dst, b, h) do { _Pragma("unroll") for (int m = 0; m < 4; ++m) _Pragma("unroll") for (int k = 0; k < 2; ++k) dst[m][k] = *(const PG8_LAS bf16x8*)(lds + PG8_SA(b, h) + aoff + m * 2048 + k * 1024); } while (0)
; #define PG8_MMA(ai, bj, At, Bt) do { __builtin_amdgcn_s_setprio(1); _Pragma("unroll") for (int m = 0; m < 4; ++m) _Pragma("unroll") for (int n = 0; n < 2; ++n) _Pragma("unroll") for (int k = 0; k < 2; ++k) \
;         acc[ai][bj][m][n] = mma16<F16>(Bt[n][k], At[m][k], acc[ai][bj][m][n]); __builtin_amdgcn_s_setprio(0); } while (0)
; #define PG8_WAIT_V(n) asm volatile("s_waitcnt vmcnt(" #n ")" ::: "memory")
; #define PG8_WAIT_L(n) asm volatile("s_waitcnt lgkmcnt(" #n ")" ::: "memory")
; #define PG8_BAR __builtin_amdgcn_s_barrier()
; #define PG8_SCHED __builtin_amdgcn_sched_barrier(0)
; template <class Epi, class Sched, bool ALIGN_EPI = false, bool SP2 = false, bool F16 = false, bool TOKPERM = false>
; __device__ __forceinline__ void gemm_phase(PG8_LAS unsigned char* lds, const Gemm g, const Sched& S, const Epi& E, int wv) {
;     ...
;             PG8_LDA(At, 1, 1); PG8_STAGE(PG8_SB(1, 0), b3, voffB); PG8_STAGE(PG8_SB(1, 1), b3 + hstep, voffB); PG8_STAGE(PG8_SA(1, 0), a3, voffA);
;             PG8_WAIT_V(8); PG8_WAIT_L(0); PG8_BAR; PG8_MMA(1, 0, At, B0); PG8_MMA(1, 1, At, B1); PG8_BAR; PG8_SCHED;
;   __device__ __forceinline__ void operator()(const pg8::f32x4 (&acc)[2][2][4][2], const pg8::Unit& u, int wr, int wc, int fr, int fq) const {
;     ...
;     const int row0 = u.pm * 256 + wr * 64 + fr + z, colb = u.pn * 256 + wc * 32 + 8 * fq + z;
; #pragma unroll
;     for (int ai = 0; ai < 2; ++ai)
; #pragma unroll
;       for (int m = 0; m < 4; ++m) {
;         const int tok = row0 + ai * 128 + m * 16; float ss = 0.f;
; #pragma unroll
;         for (int bj = 0; bj < 2; ++bj) {
;           const unsigned off = (unsigned)tok * DM + colb + 128 * bj;
;           f8_t n = __builtin_convertvector(*(const h8_t*)(x16 + off), f8_t);
	s_mov_b32 m0, s45
	v_lshl_add_u64 v[232:233], v[232:233], 0, s[12:13]
	s_add_u32 s16, s48, 0xb0080
	ds_read_b128 v[198:201], v147 offset:49152
	ds_read_b128 v[202:205], v147 offset:50176
	ds_read_b128 v[206:209], v147 offset:51200
	ds_read_b128 v[210:213], v147 offset:52224
	ds_read_b128 v[214:217], v147 offset:53248
	ds_read_b128 v[218:221], v147 offset:54272
	ds_read_b128 v[222:225], v147 offset:55296
	ds_read_b128 v[228:231], v147 offset:56320
	global_load_lds_dwordx4 v[232:233], off
	v_lshl_add_u64 v[232:233], v[234:235], 0, s[12:13]
	s_mov_b32 m0, s52
	s_addc_u32 s17, s49, 0
	global_load_lds_dwordx4 v[232:233], off
	v_lshl_add_u64 v[232:233], s[16:17], 0, v[130:131]
	s_mov_b32 m0, s55
	s_nop 0
	global_load_lds_dwordx4 v[232:233], off
	v_lshl_add_u64 v[232:233], s[16:17], 0, v[134:135]
	s_mov_b32 m0, s56
	s_nop 0
	global_load_lds_dwordx4 v[232:233], off
	v_lshl_add_u64 v[232:233], v[236:237], 0, s[12:13]
	s_mov_b32 m0, s53
	s_nop 0
	global_load_lds_dwordx4 v[232:233], off
	v_lshl_add_u64 v[232:233], v[238:239], 0, s[12:13]
	s_mov_b32 m0, s54
	s_nop 0
	global_load_lds_dwordx4 v[232:233], off
	s_waitcnt vmcnt(8)
	s_waitcnt lgkmcnt(0)
	s_barrier
	s_setprio 1
	s_waitcnt lgkmcnt(0)
	v_mfma_f32_16x16x32_bf16 v[60:63], v[166:169], v[198:201], v[60:63]
	v_mfma_f32_16x16x32_bf16 v[56:59], v[174:177], v[198:201], v[56:59]
	v_mfma_f32_16x16x32_bf16 v[44:47], v[166:169], v[206:209], v[44:47]
	v_mfma_f32_16x16x32_bf16 v[40:43], v[174:177], v[206:209], v[40:43]
	v_mfma_f32_16x16x32_bf16 v[28:31], v[166:169], v[214:217], v[28:31]
	v_mfma_f32_16x16x32_bf16 v[24:27], v[174:177], v[214:217], v[24:27]
	v_mfma_f32_16x16x32_bf16 v[12:15], v[166:169], v[222:225], v[12:15]
	v_mfma_f32_16x16x32_bf16 v[8:11], v[174:177], v[222:225], v[8:11]
	v_mfma_f32_16x16x32_bf16 v[60:63], v[170:173], v[202:205], v[60:63]
	v_mfma_f32_16x16x32_bf16 v[56:59], v[178:181], v[202:205], v[56:59]
	v_mfma_f32_16x16x32_bf16 v[44:47], v[170:173], v[210:213], v[44:47]
	v_mfma_f32_16x16x32_bf16 v[40:43], v[178:181], v[210:213], v[40:43]
	v_mfma_f32_16x16x32_bf16 v[28:31], v[170:173], v[218:221], v[28:31]
	v_mfma_f32_16x16x32_bf16 v[24:27], v[178:181], v[218:221], v[24:27]
	v_mfma_f32_16x16x32_bf16 v[12:15], v[170:173], v[228:231], v[12:15]
	v_mfma_f32_16x16x32_bf16 v[8:11], v[178:181], v[228:231], v[8:11]
	s_setprio 0
	s_setprio 1
	v_mfma_f32_16x16x32_bf16 v[52:55], v[182:185], v[198:201], v[52:55]
	v_mfma_f32_16x16x32_bf16 v[48:51], v[190:193], v[198:201], v[48:51]
	v_mfma_f32_16x16x32_bf16 v[36:39], v[182:185], v[206:209], v[36:39]
	v_mfma_f32_16x16x32_bf16 v[32:35], v[190:193], v[206:209], v[32:35]
	v_mfma_f32_16x16x32_bf16 v[20:23], v[182:185], v[214:217], v[20:23]
	v_mfma_f32_16x16x32_bf16 v[16:19], v[190:193], v[214:217], v[16:19]
	v_mfma_f32_16x16x32_bf16 v[4:7], v[182:185], v[222:225], v[4:7]
	v_mfma_f32_16x16x32_bf16 v[0:3], v[190:193], v[222:225], v[0:3]
	v_mfma_f32_16x16x32_bf16 v[52:55], v[186:189], v[202:205], v[52:55]
	v_mfma_f32_16x16x32_bf16 v[48:51], v[194:197], v[202:205], v[48:51]
	v_mfma_f32_16x16x32_bf16 v[36:39], v[186:189], v[210:213], v[36:39]
	v_mfma_f32_16x16x32_bf16 v[32:35], v[194:197], v[210:213], v[32:35]
	v_mfma_f32_16x16x32_bf16 v[20:23], v[186:189], v[218:221], v[20:23]
	v_mfma_f32_16x16x32_bf16 v[16:19], v[194:197], v[218:221], v[16:19]
	v_mfma_f32_16x16x32_bf16 v[4:7], v[186:189], v[228:231], v[4:7]
	v_mfma_f32_16x16x32_bf16 v[0:3], v[194:197], v[228:231], v[0:3]
	s_setprio 0
	s_barrier
	s_add_i32 s70, s70, 2
	s_add_u32 s68, s68, 0x100
	s_addc_u32 s69, s69, 0
	s_cmp_gt_u32 s70, 41
	s_mov_b64 s[16:17], s[18:19]
	s_cbranch_scc0 .LBB0_297
	s_lshl_b32 s16, s66, 8
	v_lshl_or_b32 v166, s65, 8, v148
	v_mov_b32 v136, 0
	v_xor_b32_e32 v169, 32, v165
	v_add3_u32 v167, s16, v146, v136
	v_add_u32_e32 v168, v166, v136
	v_lshl_add_u32 v136, v167, 10, v168
	v_lshl_add_u64 v[178:179], v[136:137], 1, s[40:41]
	v_add_u32_e32 v136, 0x80, v136
	global_load_dwordx4 v[170:173], v[178:179], off
	v_lshl_add_u64 v[180:181], v[136:137], 1, s[40:41]
	global_load_dwordx4 v[174:177], v[180:181], off
	v_add_u32_e32 v136, 16, v167
	v_lshl_add_u32 v136, v136, 10, v168
	v_lshl_add_u64 v[224:225], v[136:137], 1, s[40:41]
	v_add_u32_e32 v136, 0x80, v136
	global_load_dwordx4 v[192:195], v[224:225], off
	v_lshl_add_u64 v[248:249], v[136:137], 1, s[40:41]
	global_load_dwordx4 v[196:199], v[248:249], off
	v_add_u32_e32 v136, 32, v167
	v_lshl_add_u32 v136, v136, 10, v168
	v_lshl_add_u64 v[224:225], v[136:137], 1, s[40:41]
	v_add_u32_e32 v136, 0x80, v136
	global_load_dwordx4 v[200:203], v[224:225], off
	v_lshl_add_u64 v[248:249], v[136:137], 1, s[40:41]
	global_load_dwordx4 v[204:207], v[248:249], off
	v_add_u32_e32 v136, 48, v167
	v_lshl_add_u32 v136, v136, 10, v168
	v_lshl_add_u64 v[224:225], v[136:137], 1, s[40:41]
	v_add_u32_e32 v136, 0x80, v136
	global_load_dwordx4 v[208:211], v[224:225], off
	v_lshl_add_u64 v[248:249], v[136:137], 1, s[40:41]
	global_load_dwordx4 v[212:215], v[248:249], off
	v_add_u32_e32 v136, 0x80, v167
	v_lshl_add_u32 v136, v136, 10, v168
	v_lshl_add_u64 v[224:225], v[136:137], 1, s[40:41]
	v_add_u32_e32 v136, 0x80, v136
	global_load_dwordx4 v[216:219], v[224:225], off
	v_lshl_add_u64 v[248:249], v[136:137], 1, s[40:41]
	global_load_dwordx4 v[220:223], v[248:249], off
	v_add_u32_e32 v136, 0x90, v167
	v_lshl_add_u32 v136, v136, 10, v168
	v_lshl_add_u64 v[224:225], v[136:137], 1, s[40:41]
	v_add_u32_e32 v136, 0x80, v136
	global_load_dwordx4 v[228:231], v[224:225], off
	v_lshl_add_u64 v[248:249], v[136:137], 1, s[40:41]
	global_load_dwordx4 v[244:247], v[248:249], off
	v_and_b32_e32 v166, 64, v165
	v_xor_b32_e32 v136, 16, v165
	v_add_u32_e32 v166, 64, v166
	v_cmp_lt_i32_e32 vcc, v136, v166
	s_lshl_b32 s16, s65, 2
	s_or_b32 s18, s16, s44
	v_cndmask_b32_e32 v136, v165, v136, vcc
	v_cmp_lt_i32_e32 vcc, v169, v166
	v_lshlrev_b32_e32 v166, 2, v136
	s_waitcnt vmcnt(10)
;   __device__ __forceinline__ void operator()(const pg8::f32x4 (&acc)[2][2][4][2], const pg8::Unit& u, int wr, int wc, int fr, int fq) const {
;     ...
;         const int tok = row0 + ai * 128 + m * 16; float ss = 0.f;
; #pragma unroll
;         for (int bj = 0; bj < 2; ++bj) {
;           const unsigned off = (unsigned)tok * DM + colb + 128 * bj;
;           f8_t n = __builtin_convertvector(*(const h8_t*)(x16 + off), f8_t);
; #pragma unroll
;           for (int c = 0; c < 4; ++c) { n[c] += sc * acc[ai][bj][m][0][c]; n[4 + c] += sc * acc[ai][bj][m][1][c]; }
;           if (aux) {
;             *(h8_t*)(x16 + off) = __builtin_convertvector(n, h8_t);
;             ss += ((n[0] * n[0] + n[1] * n[1]) + (n[2] * n[2] + n[3] * n[3])) + ((n[4] * n[4] + n[5] * n[5]) + (n[6] * n[6] + n[7] * n[7]));
;           } else {
;             *(f32x4*)(xout + off) = (f32x4){n[0], n[1], n[2], n[3]}; *(f32x4*)(xout + off + 4) = (f32x4){n[4], n[5], n[6], n[7]};
;           }
;         }
;         if (aux) { ss += __shfl_xor(ss, 16); ss += __shfl_xor(ss, 32); if (fq == 0) ssq[(unsigned)tok * 16 + u.pn * 4 + wc] = ss; }
	v_cvt_f32_f16_e32 v182, v173
	v_cvt_f32_f16_sdwa v183, v173 dst_sel:DWORD dst_unused:UNUSED_PAD src0_sel:WORD_1
	v_cvt_f32_f16_e32 v184, v171
	v_cvt_f32_f16_sdwa v185, v171 dst_sel:DWORD dst_unused:UNUSED_PAD src0_sel:WORD_1
	v_cvt_f32_f16_e32 v186, v172
	v_cvt_f32_f16_sdwa v187, v172 dst_sel:DWORD dst_unused:UNUSED_PAD src0_sel:WORD_1
	v_cvt_f32_f16_e32 v172, v170
	v_cvt_f32_f16_sdwa v173, v170 dst_sel:DWORD dst_unused:UNUSED_PAD src0_sel:WORD_1
	v_cvt_f32_f16_e32 v170, v177
	v_cvt_f32_f16_sdwa v171, v177 dst_sel:DWORD dst_unused:UNUSED_PAD src0_sel:WORD_1
	v_cvt_f32_f16_e32 v188, v175
	v_cvt_f32_f16_sdwa v189, v175 dst_sel:DWORD dst_unused:UNUSED_PAD src0_sel:WORD_1
	v_cvt_f32_f16_e32 v190, v176
	v_cvt_f32_f16_sdwa v191, v176 dst_sel:DWORD dst_unused:UNUSED_PAD src0_sel:WORD_1
	v_cvt_f32_f16_e32 v176, v174
	v_cvt_f32_f16_sdwa v177, v174 dst_sel:DWORD dst_unused:UNUSED_PAD src0_sel:WORD_1
	v_pk_fma_f32 v[124:125], v[124:125], 0.5, v[172:173] op_sel_hi:[1,0,1]
	v_pk_fma_f32 v[172:173], v[120:121], 0.5, v[186:187] op_sel_hi:[1,0,1]
	v_pk_fma_f32 v[126:127], v[126:127], 0.5, v[184:185] op_sel_hi:[1,0,1]
	v_pk_fma_f32 v[122:123], v[122:123], 0.5, v[182:183] op_sel_hi:[1,0,1]
	v_cvt_pk_f16_f32 v120, v172, v173
	v_cvt_pk_f16_f32 v121, v122, v123
	v_pk_mul_f32 v[174:175], v[124:125], v[124:125]
	v_pk_mul_f32 v[182:183], v[126:127], v[126:127]
	v_pk_fma_f32 v[174:175], v[172:173], v[172:173], v[174:175]
	v_pk_fma_f32 v[182:183], v[122:123], v[122:123], v[182:183]
	v_pk_fma_f32 v[176:177], v[116:117], 0.5, v[176:177] op_sel_hi:[1,0,1]
	v_pk_fma_f32 v[116:117], v[112:113], 0.5, v[190:191] op_sel_hi:[1,0,1]
	v_pk_fma_f32 v[184:185], v[118:119], 0.5, v[188:189] op_sel_hi:[1,0,1]
	v_pk_fma_f32 v[112:113], v[114:115], 0.5, v[170:171] op_sel_hi:[1,0,1]
	v_pk_fma_f32 v[174:175], v[176:177], v[176:177], v[174:175]
	v_pk_fma_f32 v[182:183], v[184:185], v[184:185], v[182:183]
	v_pk_fma_f32 v[174:175], v[116:117], v[116:117], v[174:175]
	v_pk_fma_f32 v[182:183], v[112:113], v[112:113], v[182:183]
	v_pk_add_f32 v[174:175], v[174:175], v[182:183]
	v_add_f32_e32 v114, v174, v175
	v_mov_b32_e32 v115, v114
	s_nop 1
	v_permlane16_swap_b32_e32 v114, v115
	v_cndmask_b32_e32 v169, v165, v169, vcc
	v_cvt_pk_f16_f32 v119, v126, v127
	v_cvt_pk_f16_f32 v118, v124, v125
	global_store_dwordx4 v[178:179], v[118:121], off
	s_nop 1
	v_cvt_pk_f16_f32 v119, v112, v113
	s_waitcnt lgkmcnt(0)
	v_add_f32_e32 v113, v114, v115
	v_lshlrev_b32_e32 v112, 2, v169
	v_mov_b32_e32 v114, v113
	s_nop 1
	v_permlane32_swap_b32_e32 v113, v114
	v_cvt_pk_f16_f32 v118, v116, v117
	v_cvt_pk_f16_f32 v117, v184, v185
	v_cvt_pk_f16_f32 v116, v176, v177
	global_store_dwordx4 v[180:181], v[116:119], off
	s_and_saveexec_b64 s[16:17], s[4:5]
	s_cbranch_execz .LBB0_300
	v_lshl_add_u32 v136, v167, 4, s18
	s_waitcnt lgkmcnt(0)
	v_add_f32_e32 v113, v113, v114
	v_lshl_add_u64 v[114:115], v[136:137], 2, s[42:43]
	global_store_dword v[114:115], v113, off
.LBB0_300:
	s_or_b64 exec, exec, s[16:17]
	v_add_u32_e32 v113, 16, v167
	v_lshl_add_u32 v136, v113, 10, v168
	v_lshl_add_u64 v[122:123], v[136:137], 1, s[40:41]
	v_add_u32_e32 v136, 0x80, v136
	v_lshl_add_u64 v[124:125], v[136:137], 1, s[40:41]
	s_waitcnt lgkmcnt(0)
	s_waitcnt vmcnt(10)
	v_cvt_f32_f16_e32 v126, v195
	v_cvt_f32_f16_sdwa v127, v195 dst_sel:DWORD dst_unused:UNUSED_PAD src0_sel:WORD_1
	v_cvt_f32_f16_e32 v170, v193
	v_cvt_f32_f16_sdwa v171, v193 dst_sel:DWORD dst_unused:UNUSED_PAD src0_sel:WORD_1
	v_cvt_f32_f16_e32 v172, v194
	v_cvt_f32_f16_sdwa v173, v194 dst_sel:DWORD dst_unused:UNUSED_PAD src0_sel:WORD_1
	v_cvt_f32_f16_e32 v116, v192
	v_cvt_f32_f16_sdwa v117, v192 dst_sel:DWORD dst_unused:UNUSED_PAD src0_sel:WORD_1
	v_cvt_f32_f16_e32 v114, v199
	v_cvt_f32_f16_sdwa v115, v199 dst_sel:DWORD dst_unused:UNUSED_PAD src0_sel:WORD_1
	v_cvt_f32_f16_e32 v174, v197
	v_cvt_f32_f16_sdwa v175, v197 dst_sel:DWORD dst_unused:UNUSED_PAD src0_sel:WORD_1
	v_cvt_f32_f16_e32 v176, v198
	v_cvt_f32_f16_sdwa v177, v198 dst_sel:DWORD dst_unused:UNUSED_PAD src0_sel:WORD_1
	v_cvt_f32_f16_e32 v120, v196
	v_cvt_f32_f16_sdwa v121, v196 dst_sel:DWORD dst_unused:UNUSED_PAD src0_sel:WORD_1
	v_pk_fma_f32 v[108:109], v[108:109], 0.5, v[116:117] op_sel_hi:[1,0,1]
	v_pk_fma_f32 v[116:117], v[104:105], 0.5, v[172:173] op_sel_hi:[1,0,1]
	v_pk_fma_f32 v[110:111], v[110:111], 0.5, v[170:171] op_sel_hi:[1,0,1]
	v_pk_fma_f32 v[106:107], v[106:107], 0.5, v[126:127] op_sel_hi:[1,0,1]
	v_pk_fma_f32 v[120:121], v[100:101], 0.5, v[120:121] op_sel_hi:[1,0,1]
	v_pk_fma_f32 v[170:171], v[96:97], 0.5, v[176:177] op_sel_hi:[1,0,1]
	v_pk_fma_f32 v[172:173], v[102:103], 0.5, v[174:175] op_sel_hi:[1,0,1]
	v_pk_fma_f32 v[96:97], v[98:99], 0.5, v[114:115] op_sel_hi:[1,0,1]
	v_cvt_pk_f16_f32 v105, v106, v107
	v_cvt_pk_f16_f32 v104, v116, v117
	v_pk_mul_f32 v[118:119], v[108:109], v[108:109]
	v_pk_mul_f32 v[126:127], v[110:111], v[110:111]
	v_pk_fma_f32 v[118:119], v[116:117], v[116:117], v[118:119]
	v_pk_fma_f32 v[126:127], v[106:107], v[106:107], v[126:127]
	v_pk_fma_f32 v[118:119], v[120:121], v[120:121], v[118:119]
	v_pk_fma_f32 v[126:127], v[172:173], v[172:173], v[126:127]
	v_pk_fma_f32 v[118:119], v[170:171], v[170:171], v[118:119]
	v_pk_fma_f32 v[126:127], v[96:97], v[96:97], v[126:127]
	v_pk_add_f32 v[118:119], v[118:119], v[126:127]
	v_add_f32_e32 v98, v118, v119
	v_mov_b32_e32 v99, v98
	s_nop 1
	v_permlane16_swap_b32_e32 v98, v99
	v_cvt_pk_f16_f32 v101, v96, v97
	v_cvt_pk_f16_f32 v103, v110, v111
	v_cvt_pk_f16_f32 v102, v108, v109
	v_cvt_pk_f16_f32 v100, v170, v171
	s_waitcnt lgkmcnt(0)
	v_add_f32_e32 v96, v98, v99
	v_mov_b32_e32 v97, v96
	s_nop 1
	v_permlane32_swap_b32_e32 v96, v97
	v_cvt_pk_f16_f32 v99, v172, v173
	v_cvt_pk_f16_f32 v98, v120, v121
	global_store_dwordx4 v[122:123], v[102:105], off
	global_store_dwordx4 v[124:125], v[98:101], off
	s_and_saveexec_b64 s[16:17], s[4:5]
	s_cbranch_execz .LBB0_302
	v_lshl_add_u32 v136, v113, 4, s18
	s_waitcnt lgkmcnt(0)
	v_add_f32_e32 v98, v96, v97
	v_lshl_add_u64 v[96:97], v[136:137], 2, s[42:43]
	global_store_dword v[96:97], v98, off
;   __device__ __forceinline__ void operator()(const pg8::f32x4 (&acc)[2][2][4][2], const pg8::Unit& u, int wr, int wc, int fr, int fq) const {
;     ...
;         const int tok = row0 + ai * 128 + m * 16; float ss = 0.f;
; #pragma unroll
;         for (int bj = 0; bj < 2; ++bj) {
;           const unsigned off = (unsigned)tok * DM + colb + 128 * bj;
;           f8_t n = __builtin_convertvector(*(const h8_t*)(x16 + off), f8_t);
; #pragma unroll
;           for (int c = 0; c < 4; ++c) { n[c] += sc * acc[ai][bj][m][0][c]; n[4 + c] += sc * acc[ai][bj][m][1][c]; }
;           if (aux) {
;             *(h8_t*)(x16 + off) = __builtin_convertvector(n, h8_t);
;             ss += ((n[0] * n[0] + n[1] * n[1]) + (n[2] * n[2] + n[3] * n[3])) + ((n[4] * n[4] + n[5] * n[5]) + (n[6] * n[6] + n[7] * n[7]));
;           } else {
;             *(f32x4*)(xout + off) = (f32x4){n[0], n[1], n[2], n[3]}; *(f32x4*)(xout + off + 4) = (f32x4){n[4], n[5], n[6], n[7]};
;           }
;         }
;         if (aux) { ss += __shfl_xor(ss, 16); ss += __shfl_xor(ss, 32); if (fq == 0) ssq[(unsigned)tok * 16 + u.pn * 4 + wc] = ss; }
.LBB0_302:
	s_or_b64 exec, exec, s[16:17]
	v_add_u32_e32 v96, 32, v167
	v_lshl_add_u32 v136, v96, 10, v168
	v_lshl_add_u64 v[106:107], v[136:137], 1, s[40:41]
	v_add_u32_e32 v136, 0x80, v136
	v_lshl_add_u64 v[108:109], v[136:137], 1, s[40:41]
	s_waitcnt vmcnt(10)
	v_cvt_f32_f16_e32 v110, v203
	v_cvt_f32_f16_sdwa v111, v203 dst_sel:DWORD dst_unused:UNUSED_PAD src0_sel:WORD_1
	v_cvt_f32_f16_e32 v114, v201
	v_cvt_f32_f16_sdwa v115, v201 dst_sel:DWORD dst_unused:UNUSED_PAD src0_sel:WORD_1
	v_cvt_f32_f16_e32 v116, v202
	v_cvt_f32_f16_sdwa v117, v202 dst_sel:DWORD dst_unused:UNUSED_PAD src0_sel:WORD_1
	v_cvt_f32_f16_e32 v100, v200
	v_cvt_f32_f16_sdwa v101, v200 dst_sel:DWORD dst_unused:UNUSED_PAD src0_sel:WORD_1
	v_cvt_f32_f16_e32 v98, v207
	v_cvt_f32_f16_sdwa v99, v207 dst_sel:DWORD dst_unused:UNUSED_PAD src0_sel:WORD_1
	v_cvt_f32_f16_e32 v118, v205
	v_cvt_f32_f16_sdwa v119, v205 dst_sel:DWORD dst_unused:UNUSED_PAD src0_sel:WORD_1
	v_cvt_f32_f16_e32 v120, v206
	v_cvt_f32_f16_sdwa v121, v206 dst_sel:DWORD dst_unused:UNUSED_PAD src0_sel:WORD_1
	v_cvt_f32_f16_e32 v104, v204
	v_cvt_f32_f16_sdwa v105, v204 dst_sel:DWORD dst_unused:UNUSED_PAD src0_sel:WORD_1
	v_pk_fma_f32 v[92:93], v[92:93], 0.5, v[100:101] op_sel_hi:[1,0,1]
	v_pk_fma_f32 v[100:101], v[88:89], 0.5, v[116:117] op_sel_hi:[1,0,1]
	v_pk_fma_f32 v[94:95], v[94:95], 0.5, v[114:115] op_sel_hi:[1,0,1]
	v_pk_fma_f32 v[90:91], v[90:91], 0.5, v[110:111] op_sel_hi:[1,0,1]
	v_cvt_pk_f16_f32 v88, v100, v101
	v_cvt_pk_f16_f32 v89, v90, v91
	v_pk_mul_f32 v[102:103], v[92:93], v[92:93]
	v_pk_mul_f32 v[110:111], v[94:95], v[94:95]
	v_pk_fma_f32 v[102:103], v[100:101], v[100:101], v[102:103]
	v_pk_fma_f32 v[110:111], v[90:91], v[90:91], v[110:111]
	v_pk_fma_f32 v[104:105], v[84:85], 0.5, v[104:105] op_sel_hi:[1,0,1]
	v_pk_fma_f32 v[114:115], v[80:81], 0.5, v[120:121] op_sel_hi:[1,0,1]
	v_pk_fma_f32 v[116:117], v[86:87], 0.5, v[118:119] op_sel_hi:[1,0,1]
	v_pk_fma_f32 v[80:81], v[82:83], 0.5, v[98:99] op_sel_hi:[1,0,1]
	v_pk_fma_f32 v[102:103], v[104:105], v[104:105], v[102:103]
	v_pk_fma_f32 v[110:111], v[116:117], v[116:117], v[110:111]
	v_pk_fma_f32 v[102:103], v[114:115], v[114:115], v[102:103]
	v_pk_fma_f32 v[110:111], v[80:81], v[80:81], v[110:111]
	s_waitcnt lgkmcnt(0)
	v_pk_add_f32 v[102:103], v[102:103], v[110:111]
	v_add_f32_e32 v82, v102, v103
	v_mov_b32_e32 v83, v82
	s_nop 1
	v_permlane16_swap_b32_e32 v82, v83
	v_cvt_pk_f16_f32 v85, v80, v81
	v_cvt_pk_f16_f32 v87, v94, v95
	v_cvt_pk_f16_f32 v86, v92, v93
	v_cvt_pk_f16_f32 v84, v114, v115
	s_waitcnt lgkmcnt(0)
	v_add_f32_e32 v80, v82, v83
	v_mov_b32_e32 v81, v80
	s_nop 1
	v_permlane32_swap_b32_e32 v80, v81
	v_cvt_pk_f16_f32 v83, v116, v117
	v_cvt_pk_f16_f32 v82, v104, v105
	global_store_dwordx4 v[106:107], v[86:89], off
	global_store_dwordx4 v[108:109], v[82:85], off
	s_and_saveexec_b64 s[16:17], s[4:5]
	s_cbranch_execz .LBB0_304
	v_lshl_add_u32 v136, v96, 4, s18
	s_waitcnt lgkmcnt(0)
	v_add_f32_e32 v82, v80, v81
	v_lshl_add_u64 v[80:81], v[136:137], 2, s[42:43]
	global_store_dword v[80:81], v82, off
.LBB0_304:
	s_or_b64 exec, exec, s[16:17]
	v_add_u32_e32 v80, 48, v167
	v_lshl_add_u32 v136, v80, 10, v168
	v_lshl_add_u64 v[90:91], v[136:137], 1, s[40:41]
	v_add_u32_e32 v136, 0x80, v136
	v_lshl_add_u64 v[92:93], v[136:137], 1, s[40:41]
	s_waitcnt vmcnt(10)
	v_cvt_f32_f16_e32 v94, v211
	v_cvt_f32_f16_sdwa v95, v211 dst_sel:DWORD dst_unused:UNUSED_PAD src0_sel:WORD_1
	v_cvt_f32_f16_e32 v96, v209
	v_cvt_f32_f16_sdwa v97, v209 dst_sel:DWORD dst_unused:UNUSED_PAD src0_sel:WORD_1
	v_cvt_f32_f16_e32 v98, v210
	v_cvt_f32_f16_sdwa v99, v210 dst_sel:DWORD dst_unused:UNUSED_PAD src0_sel:WORD_1
	v_cvt_f32_f16_e32 v84, v208
	v_cvt_f32_f16_sdwa v85, v208 dst_sel:DWORD dst_unused:UNUSED_PAD src0_sel:WORD_1
	v_cvt_f32_f16_e32 v82, v215
	v_cvt_f32_f16_sdwa v83, v215 dst_sel:DWORD dst_unused:UNUSED_PAD src0_sel:WORD_1
	v_cvt_f32_f16_e32 v100, v213
	v_cvt_f32_f16_sdwa v101, v213 dst_sel:DWORD dst_unused:UNUSED_PAD src0_sel:WORD_1
	v_cvt_f32_f16_e32 v102, v214
	v_cvt_f32_f16_sdwa v103, v214 dst_sel:DWORD dst_unused:UNUSED_PAD src0_sel:WORD_1
	v_cvt_f32_f16_e32 v88, v212
	v_cvt_f32_f16_sdwa v89, v212 dst_sel:DWORD dst_unused:UNUSED_PAD src0_sel:WORD_1
	v_pk_fma_f32 v[76:77], v[76:77], 0.5, v[84:85] op_sel_hi:[1,0,1]
	v_pk_fma_f32 v[84:85], v[72:73], 0.5, v[98:99] op_sel_hi:[1,0,1]
	v_pk_fma_f32 v[78:79], v[78:79], 0.5, v[96:97] op_sel_hi:[1,0,1]
	v_pk_fma_f32 v[74:75], v[74:75], 0.5, v[94:95] op_sel_hi:[1,0,1]
	v_cvt_pk_f16_f32 v72, v84, v85
	v_cvt_pk_f16_f32 v73, v74, v75
	v_pk_mul_f32 v[86:87], v[76:77], v[76:77]
	v_pk_mul_f32 v[94:95], v[78:79], v[78:79]
	v_pk_fma_f32 v[86:87], v[84:85], v[84:85], v[86:87]
	v_pk_fma_f32 v[94:95], v[74:75], v[74:75], v[94:95]
	v_pk_fma_f32 v[88:89], v[68:69], 0.5, v[88:89] op_sel_hi:[1,0,1]
	v_pk_fma_f32 v[96:97], v[64:65], 0.5, v[102:103] op_sel_hi:[1,0,1]
	v_pk_fma_f32 v[98:99], v[70:71], 0.5, v[100:101] op_sel_hi:[1,0,1]
	v_pk_fma_f32 v[64:65], v[66:67], 0.5, v[82:83] op_sel_hi:[1,0,1]
	v_pk_fma_f32 v[86:87], v[88:89], v[88:89], v[86:87]
	v_pk_fma_f32 v[94:95], v[98:99], v[98:99], v[94:95]
	v_pk_fma_f32 v[86:87], v[96:97], v[96:97], v[86:87]
	v_pk_fma_f32 v[94:95], v[64:65], v[64:65], v[94:95]
	s_waitcnt lgkmcnt(0)
	v_pk_add_f32 v[86:87], v[86:87], v[94:95]
	v_add_f32_e32 v66, v86, v87
	v_mov_b32_e32 v67, v66
	s_nop 1
	v_permlane16_swap_b32_e32 v66, v67
	v_cvt_pk_f16_f32 v69, v64, v65
	v_cvt_pk_f16_f32 v71, v78, v79
	v_cvt_pk_f16_f32 v70, v76, v77
	v_cvt_pk_f16_f32 v68, v96, v97
	s_waitcnt lgkmcnt(0)
	v_add_f32_e32 v64, v66, v67
	v_mov_b32_e32 v65, v64
	s_nop 1
	v_permlane32_swap_b32_e32 v64, v65
	v_cvt_pk_f16_f32 v67, v98, v99
	v_cvt_pk_f16_f32 v66, v88, v89
	global_store_dwordx4 v[90:91], v[70:73], off
	global_store_dwordx4 v[92:93], v[66:69], off
	s_and_saveexec_b64 s[16:17], s[4:5]
	s_cbranch_execz .LBB0_306
	v_lshl_add_u32 v136, v80, 4, s18
	s_waitcnt lgkmcnt(0)
	v_add_f32_e32 v66, v64, v65
	v_lshl_add_u64 v[64:65], v[136:137], 2, s[42:43]
	global_store_dword v[64:65], v66, off
;   __device__ __forceinline__ void operator()(const pg8::f32x4 (&acc)[2][2][4][2], const pg8::Unit& u, int wr, int wc, int fr, int fq) const {
;     ...
;         const int tok = row0 + ai * 128 + m * 16; float ss = 0.f;
; #pragma unroll
;         for (int bj = 0; bj < 2; ++bj) {
;           const unsigned off = (unsigned)tok * DM + colb + 128 * bj;
;           f8_t n = __builtin_convertvector(*(const h8_t*)(x16 + off), f8_t);
; #pragma unroll
;           for (int c = 0; c < 4; ++c) { n[c] += sc * acc[ai][bj][m][0][c]; n[4 + c] += sc * acc[ai][bj][m][1][c]; }
;           if (aux) {
;             *(h8_t*)(x16 + off) = __builtin_convertvector(n, h8_t);
;             ss += ((n[0] * n[0] + n[1] * n[1]) + (n[2] * n[2] + n[3] * n[3])) + ((n[4] * n[4] + n[5] * n[5]) + (n[6] * n[6] + n[7] * n[7]));
;           } else {
;             *(f32x4*)(xout + off) = (f32x4){n[0], n[1], n[2], n[3]}; *(f32x4*)(xout + off + 4) = (f32x4){n[4], n[5], n[6], n[7]};
;           }
;         }
;         if (aux) { ss += __shfl_xor(ss, 16); ss += __shfl_xor(ss, 32); if (fq == 0) ssq[(unsigned)tok * 16 + u.pn * 4 + wc] = ss; }
.LBB0_306:
	s_or_b64 exec, exec, s[16:17]
	v_add_u32_e32 v64, 0x80, v167
	v_lshl_add_u32 v136, v64, 10, v168
	v_lshl_add_u64 v[74:75], v[136:137], 1, s[40:41]
	v_add_u32_e32 v136, 0x80, v136
	v_lshl_add_u64 v[76:77], v[136:137], 1, s[40:41]
	s_waitcnt vmcnt(10)
	v_cvt_f32_f16_e32 v78, v219
	v_cvt_f32_f16_sdwa v79, v219 dst_sel:DWORD dst_unused:UNUSED_PAD src0_sel:WORD_1
	v_cvt_f32_f16_e32 v80, v217
	v_cvt_f32_f16_sdwa v81, v217 dst_sel:DWORD dst_unused:UNUSED_PAD src0_sel:WORD_1
	v_cvt_f32_f16_e32 v82, v218
	v_cvt_f32_f16_sdwa v83, v218 dst_sel:DWORD dst_unused:UNUSED_PAD src0_sel:WORD_1
	v_cvt_f32_f16_e32 v68, v216
	v_cvt_f32_f16_sdwa v69, v216 dst_sel:DWORD dst_unused:UNUSED_PAD src0_sel:WORD_1
	v_cvt_f32_f16_e32 v66, v223
	v_cvt_f32_f16_sdwa v67, v223 dst_sel:DWORD dst_unused:UNUSED_PAD src0_sel:WORD_1
	v_cvt_f32_f16_e32 v84, v221
	v_cvt_f32_f16_sdwa v85, v221 dst_sel:DWORD dst_unused:UNUSED_PAD src0_sel:WORD_1
	v_cvt_f32_f16_e32 v86, v222
	v_cvt_f32_f16_sdwa v87, v222 dst_sel:DWORD dst_unused:UNUSED_PAD src0_sel:WORD_1
	v_cvt_f32_f16_e32 v72, v220
	v_cvt_f32_f16_sdwa v73, v220 dst_sel:DWORD dst_unused:UNUSED_PAD src0_sel:WORD_1
	v_pk_fma_f32 v[60:61], v[60:61], 0.5, v[68:69] op_sel_hi:[1,0,1]
	v_pk_fma_f32 v[68:69], v[56:57], 0.5, v[82:83] op_sel_hi:[1,0,1]
	v_pk_fma_f32 v[62:63], v[62:63], 0.5, v[80:81] op_sel_hi:[1,0,1]
	v_pk_fma_f32 v[58:59], v[58:59], 0.5, v[78:79] op_sel_hi:[1,0,1]
	v_cvt_pk_f16_f32 v56, v68, v69
	v_cvt_pk_f16_f32 v57, v58, v59
	v_pk_mul_f32 v[70:71], v[60:61], v[60:61]
	v_pk_mul_f32 v[78:79], v[62:63], v[62:63]
	v_pk_fma_f32 v[70:71], v[68:69], v[68:69], v[70:71]
	v_pk_fma_f32 v[78:79], v[58:59], v[58:59], v[78:79]
	v_pk_fma_f32 v[72:73], v[52:53], 0.5, v[72:73] op_sel_hi:[1,0,1]
	v_pk_fma_f32 v[80:81], v[48:49], 0.5, v[86:87] op_sel_hi:[1,0,1]
	v_pk_fma_f32 v[82:83], v[54:55], 0.5, v[84:85] op_sel_hi:[1,0,1]
	v_pk_fma_f32 v[48:49], v[50:51], 0.5, v[66:67] op_sel_hi:[1,0,1]
	v_pk_fma_f32 v[70:71], v[72:73], v[72:73], v[70:71]
	v_pk_fma_f32 v[78:79], v[82:83], v[82:83], v[78:79]
	v_pk_fma_f32 v[70:71], v[80:81], v[80:81], v[70:71]
	v_pk_fma_f32 v[78:79], v[48:49], v[48:49], v[78:79]
	s_waitcnt lgkmcnt(0)
	v_pk_add_f32 v[70:71], v[70:71], v[78:79]
	v_add_f32_e32 v50, v70, v71
	v_mov_b32_e32 v51, v50
	s_nop 1
	v_permlane16_swap_b32_e32 v50, v51
	v_cvt_pk_f16_f32 v53, v48, v49
	v_cvt_pk_f16_f32 v55, v62, v63
	v_cvt_pk_f16_f32 v54, v60, v61
	v_cvt_pk_f16_f32 v52, v80, v81
	s_waitcnt lgkmcnt(0)
	v_add_f32_e32 v48, v50, v51
	v_mov_b32_e32 v49, v48
	s_nop 1
	v_permlane32_swap_b32_e32 v48, v49
	v_cvt_pk_f16_f32 v51, v82, v83
	v_cvt_pk_f16_f32 v50, v72, v73
	global_store_dwordx4 v[74:75], v[54:57], off
	global_store_dwordx4 v[76:77], v[50:53], off
	s_and_saveexec_b64 s[16:17], s[4:5]
	s_cbranch_execz .LBB0_308
	v_lshl_add_u32 v136, v64, 4, s18
	s_waitcnt lgkmcnt(0)
	v_add_f32_e32 v50, v48, v49
	v_lshl_add_u64 v[48:49], v[136:137], 2, s[42:43]
	global_store_dword v[48:49], v50, off
.LBB0_308:
	s_or_b64 exec, exec, s[16:17]
	v_add_u32_e32 v48, 0x90, v167
	v_lshl_add_u32 v136, v48, 10, v168
	v_lshl_add_u64 v[58:59], v[136:137], 1, s[40:41]
	v_add_u32_e32 v136, 0x80, v136
	v_lshl_add_u64 v[60:61], v[136:137], 1, s[40:41]
	s_waitcnt vmcnt(10)
	v_cvt_f32_f16_e32 v62, v231
	v_cvt_f32_f16_sdwa v63, v231 dst_sel:DWORD dst_unused:UNUSED_PAD src0_sel:WORD_1
	v_cvt_f32_f16_e32 v64, v229
	v_cvt_f32_f16_sdwa v65, v229 dst_sel:DWORD dst_unused:UNUSED_PAD src0_sel:WORD_1
	v_cvt_f32_f16_e32 v66, v230
	v_cvt_f32_f16_sdwa v67, v230 dst_sel:DWORD dst_unused:UNUSED_PAD src0_sel:WORD_1
	v_cvt_f32_f16_e32 v52, v228
	v_cvt_f32_f16_sdwa v53, v228 dst_sel:DWORD dst_unused:UNUSED_PAD src0_sel:WORD_1
	v_cvt_f32_f16_e32 v50, v247
	v_cvt_f32_f16_sdwa v51, v247 dst_sel:DWORD dst_unused:UNUSED_PAD src0_sel:WORD_1
	v_cvt_f32_f16_e32 v68, v245
	v_cvt_f32_f16_sdwa v69, v245 dst_sel:DWORD dst_unused:UNUSED_PAD src0_sel:WORD_1
	v_cvt_f32_f16_e32 v70, v246
	v_cvt_f32_f16_sdwa v71, v246 dst_sel:DWORD dst_unused:UNUSED_PAD src0_sel:WORD_1
	v_cvt_f32_f16_e32 v56, v244
	v_cvt_f32_f16_sdwa v57, v244 dst_sel:DWORD dst_unused:UNUSED_PAD src0_sel:WORD_1
	v_pk_fma_f32 v[44:45], v[44:45], 0.5, v[52:53] op_sel_hi:[1,0,1]
	v_pk_fma_f32 v[52:53], v[40:41], 0.5, v[66:67] op_sel_hi:[1,0,1]
	v_pk_fma_f32 v[46:47], v[46:47], 0.5, v[64:65] op_sel_hi:[1,0,1]
	v_pk_fma_f32 v[42:43], v[42:43], 0.5, v[62:63] op_sel_hi:[1,0,1]
	v_cvt_pk_f16_f32 v40, v52, v53
	v_cvt_pk_f16_f32 v41, v42, v43
	v_pk_mul_f32 v[54:55], v[44:45], v[44:45]
	v_pk_mul_f32 v[62:63], v[46:47], v[46:47]
	v_pk_fma_f32 v[54:55], v[52:53], v[52:53], v[54:55]
	v_pk_fma_f32 v[62:63], v[42:43], v[42:43], v[62:63]
	v_pk_fma_f32 v[56:57], v[36:37], 0.5, v[56:57] op_sel_hi:[1,0,1]
	v_pk_fma_f32 v[64:65], v[32:33], 0.5, v[70:71] op_sel_hi:[1,0,1]
	v_pk_fma_f32 v[66:67], v[38:39], 0.5, v[68:69] op_sel_hi:[1,0,1]
	v_pk_fma_f32 v[32:33], v[34:35], 0.5, v[50:51] op_sel_hi:[1,0,1]
	v_pk_fma_f32 v[54:55], v[56:57], v[56:57], v[54:55]
	v_pk_fma_f32 v[62:63], v[66:67], v[66:67], v[62:63]
	v_pk_fma_f32 v[54:55], v[64:65], v[64:65], v[54:55]
	v_pk_fma_f32 v[62:63], v[32:33], v[32:33], v[62:63]
	s_waitcnt lgkmcnt(0)
	v_pk_add_f32 v[54:55], v[54:55], v[62:63]
	v_add_f32_e32 v34, v54, v55
	v_mov_b32_e32 v35, v34
	s_nop 1
	v_permlane16_swap_b32_e32 v34, v35
	v_cvt_pk_f16_f32 v37, v32, v33
	v_cvt_pk_f16_f32 v39, v46, v47
	v_cvt_pk_f16_f32 v38, v44, v45
	v_cvt_pk_f16_f32 v36, v64, v65
	s_waitcnt lgkmcnt(0)
	v_add_f32_e32 v32, v34, v35
	v_mov_b32_e32 v33, v32
	s_nop 1
	v_permlane32_swap_b32_e32 v32, v33
	v_cvt_pk_f16_f32 v35, v66, v67
	v_cvt_pk_f16_f32 v34, v56, v57
	global_store_dwordx4 v[58:59], v[38:41], off
	global_store_dwordx4 v[60:61], v[34:37], off
	s_and_saveexec_b64 s[16:17], s[4:5]
	s_cbranch_execz .LBB0_310
	v_lshl_add_u32 v136, v48, 4, s18
	s_waitcnt lgkmcnt(0)
	v_add_f32_e32 v34, v32, v33
	v_lshl_add_u64 v[32:33], v[136:137], 2, s[42:43]
	global_store_dword v[32:33], v34, off
;   __device__ __forceinline__ void operator()(const pg8::f32x4 (&acc)[2][2][4][2], const pg8::Unit& u, int wr, int wc, int fr, int fq) const {
;     ...
;         const int tok = row0 + ai * 128 + m * 16; float ss = 0.f;
; #pragma unroll
;         for (int bj = 0; bj < 2; ++bj) {
;           const unsigned off = (unsigned)tok * DM + colb + 128 * bj;
;           f8_t n = __builtin_convertvector(*(const h8_t*)(x16 + off), f8_t);
; #pragma unroll
;           for (int c = 0; c < 4; ++c) { n[c] += sc * acc[ai][bj][m][0][c]; n[4 + c] += sc * acc[ai][bj][m][1][c]; }
;           if (aux) {
;             *(h8_t*)(x16 + off) = __builtin_convertvector(n, h8_t);
;             ss += ((n[0] * n[0] + n[1] * n[1]) + (n[2] * n[2] + n[3] * n[3])) + ((n[4] * n[4] + n[5] * n[5]) + (n[6] * n[6] + n[7] * n[7]));
;           } else {
;             *(f32x4*)(xout + off) = (f32x4){n[0], n[1], n[2], n[3]}; *(f32x4*)(xout + off + 4) = (f32x4){n[4], n[5], n[6], n[7]};
;           }
;         }
;         if (aux) { ss += __shfl_xor(ss, 16); ss += __shfl_xor(ss, 32); if (fq == 0) ssq[(unsigned)tok * 16 + u.pn * 4 + wc] = ss; }
.LBB0_310:
	s_or_b64 exec, exec, s[16:17]
	v_add_u32_e32 v32, 0xa0, v167
	v_lshl_add_u32 v136, v32, 10, v168
	v_lshl_add_u64 v[42:43], v[136:137], 1, s[40:41]
	v_add_u32_e32 v136, 0x80, v136
	global_load_dwordx4 v[34:37], v[42:43], off
	v_lshl_add_u64 v[44:45], v[136:137], 1, s[40:41]
	global_load_dwordx4 v[38:41], v[44:45], off
	s_waitcnt vmcnt(1)
	v_cvt_f32_f16_e32 v46, v37
	v_cvt_f32_f16_sdwa v47, v37 dst_sel:DWORD dst_unused:UNUSED_PAD src0_sel:WORD_1
	v_cvt_f32_f16_e32 v48, v35
	v_cvt_f32_f16_sdwa v49, v35 dst_sel:DWORD dst_unused:UNUSED_PAD src0_sel:WORD_1
	v_cvt_f32_f16_e32 v50, v36
	v_cvt_f32_f16_sdwa v51, v36 dst_sel:DWORD dst_unused:UNUSED_PAD src0_sel:WORD_1
	v_cvt_f32_f16_e32 v36, v34
	v_cvt_f32_f16_sdwa v37, v34 dst_sel:DWORD dst_unused:UNUSED_PAD src0_sel:WORD_1
	s_waitcnt vmcnt(0)
	v_cvt_f32_f16_e32 v34, v41
	v_cvt_f32_f16_sdwa v35, v41 dst_sel:DWORD dst_unused:UNUSED_PAD src0_sel:WORD_1
	v_cvt_f32_f16_e32 v52, v39
	v_cvt_f32_f16_sdwa v53, v39 dst_sel:DWORD dst_unused:UNUSED_PAD src0_sel:WORD_1
	v_cvt_f32_f16_e32 v54, v40
	v_cvt_f32_f16_sdwa v55, v40 dst_sel:DWORD dst_unused:UNUSED_PAD src0_sel:WORD_1
	v_cvt_f32_f16_e32 v40, v38
	v_cvt_f32_f16_sdwa v41, v38 dst_sel:DWORD dst_unused:UNUSED_PAD src0_sel:WORD_1
	v_pk_fma_f32 v[28:29], v[28:29], 0.5, v[36:37] op_sel_hi:[1,0,1]
	v_pk_fma_f32 v[36:37], v[24:25], 0.5, v[50:51] op_sel_hi:[1,0,1]
	v_pk_fma_f32 v[30:31], v[30:31], 0.5, v[48:49] op_sel_hi:[1,0,1]
	v_pk_fma_f32 v[26:27], v[26:27], 0.5, v[46:47] op_sel_hi:[1,0,1]
	v_cvt_pk_f16_f32 v24, v36, v37
	v_cvt_pk_f16_f32 v25, v26, v27
	v_pk_mul_f32 v[38:39], v[28:29], v[28:29]
	v_pk_mul_f32 v[46:47], v[30:31], v[30:31]
	v_pk_fma_f32 v[38:39], v[36:37], v[36:37], v[38:39]
	v_pk_fma_f32 v[46:47], v[26:27], v[26:27], v[46:47]
	v_pk_fma_f32 v[40:41], v[20:21], 0.5, v[40:41] op_sel_hi:[1,0,1]
	v_pk_fma_f32 v[48:49], v[16:17], 0.5, v[54:55] op_sel_hi:[1,0,1]
	v_pk_fma_f32 v[50:51], v[22:23], 0.5, v[52:53] op_sel_hi:[1,0,1]
	v_pk_fma_f32 v[16:17], v[18:19], 0.5, v[34:35] op_sel_hi:[1,0,1]
	v_pk_fma_f32 v[38:39], v[40:41], v[40:41], v[38:39]
	v_pk_fma_f32 v[46:47], v[50:51], v[50:51], v[46:47]
	v_pk_fma_f32 v[38:39], v[48:49], v[48:49], v[38:39]
	v_pk_fma_f32 v[46:47], v[16:17], v[16:17], v[46:47]
	s_waitcnt lgkmcnt(0)
	v_pk_add_f32 v[38:39], v[38:39], v[46:47]
	v_add_f32_e32 v18, v38, v39
	v_mov_b32_e32 v19, v18
	s_nop 1
	v_permlane16_swap_b32_e32 v18, v19
	v_cvt_pk_f16_f32 v21, v16, v17
	v_cvt_pk_f16_f32 v23, v30, v31
	v_cvt_pk_f16_f32 v22, v28, v29
	v_cvt_pk_f16_f32 v20, v48, v49
	s_waitcnt lgkmcnt(0)
	v_add_f32_e32 v16, v18, v19
	v_mov_b32_e32 v17, v16
	s_nop 1
	v_permlane32_swap_b32_e32 v16, v17
	v_cvt_pk_f16_f32 v19, v50, v51
	v_cvt_pk_f16_f32 v18, v40, v41
	global_store_dwordx4 v[42:43], v[22:25], off
	global_store_dwordx4 v[44:45], v[18:21], off
	s_and_saveexec_b64 s[16:17], s[4:5]
	s_cbranch_execz .LBB0_312
	v_lshl_add_u32 v136, v32, 4, s18
	s_waitcnt lgkmcnt(0)
	v_add_f32_e32 v18, v16, v17
	v_lshl_add_u64 v[16:17], v[136:137], 2, s[42:43]
	global_store_dword v[16:17], v18, off
.LBB0_312:
	s_or_b64 exec, exec, s[16:17]
	v_add_u32_e32 v16, 0xb0, v167
	v_lshl_add_u32 v136, v16, 10, v168
	v_lshl_add_u64 v[26:27], v[136:137], 1, s[40:41]
	v_add_u32_e32 v136, 0x80, v136
	global_load_dwordx4 v[18:21], v[26:27], off
	v_lshl_add_u64 v[28:29], v[136:137], 1, s[40:41]
	global_load_dwordx4 v[22:25], v[28:29], off
	s_waitcnt vmcnt(1)
	v_cvt_f32_f16_e32 v30, v21
	v_cvt_f32_f16_sdwa v31, v21 dst_sel:DWORD dst_unused:UNUSED_PAD src0_sel:WORD_1
	v_cvt_f32_f16_e32 v32, v19
	v_cvt_f32_f16_sdwa v33, v19 dst_sel:DWORD dst_unused:UNUSED_PAD src0_sel:WORD_1
	v_cvt_f32_f16_e32 v34, v20
	v_cvt_f32_f16_sdwa v35, v20 dst_sel:DWORD dst_unused:UNUSED_PAD src0_sel:WORD_1
	v_cvt_f32_f16_e32 v20, v18
	v_cvt_f32_f16_sdwa v21, v18 dst_sel:DWORD dst_unused:UNUSED_PAD src0_sel:WORD_1
	s_waitcnt vmcnt(0)
	v_cvt_f32_f16_e32 v18, v25
	v_cvt_f32_f16_sdwa v19, v25 dst_sel:DWORD dst_unused:UNUSED_PAD src0_sel:WORD_1
	v_cvt_f32_f16_e32 v36, v23
	v_cvt_f32_f16_sdwa v37, v23 dst_sel:DWORD dst_unused:UNUSED_PAD src0_sel:WORD_1
	v_cvt_f32_f16_e32 v38, v24
	v_cvt_f32_f16_sdwa v39, v24 dst_sel:DWORD dst_unused:UNUSED_PAD src0_sel:WORD_1
	v_cvt_f32_f16_e32 v24, v22
	v_cvt_f32_f16_sdwa v25, v22 dst_sel:DWORD dst_unused:UNUSED_PAD src0_sel:WORD_1
	v_pk_fma_f32 v[12:13], v[12:13], 0.5, v[20:21] op_sel_hi:[1,0,1]
	v_pk_fma_f32 v[20:21], v[8:9], 0.5, v[34:35] op_sel_hi:[1,0,1]
	v_pk_fma_f32 v[14:15], v[14:15], 0.5, v[32:33] op_sel_hi:[1,0,1]
	v_pk_fma_f32 v[10:11], v[10:11], 0.5, v[30:31] op_sel_hi:[1,0,1]
	v_cvt_pk_f16_f32 v8, v20, v21
	v_cvt_pk_f16_f32 v9, v10, v11
	v_pk_mul_f32 v[22:23], v[12:13], v[12:13]
	v_pk_mul_f32 v[30:31], v[14:15], v[14:15]
	v_pk_fma_f32 v[22:23], v[20:21], v[20:21], v[22:23]
	v_pk_fma_f32 v[30:31], v[10:11], v[10:11], v[30:31]
	v_pk_fma_f32 v[24:25], v[4:5], 0.5, v[24:25] op_sel_hi:[1,0,1]
	v_pk_fma_f32 v[32:33], v[0:1], 0.5, v[38:39] op_sel_hi:[1,0,1]
	v_pk_fma_f32 v[34:35], v[6:7], 0.5, v[36:37] op_sel_hi:[1,0,1]
	v_pk_fma_f32 v[0:1], v[2:3], 0.5, v[18:19] op_sel_hi:[1,0,1]
	v_pk_fma_f32 v[22:23], v[24:25], v[24:25], v[22:23]
	v_pk_fma_f32 v[30:31], v[34:35], v[34:35], v[30:31]
	v_pk_fma_f32 v[22:23], v[32:33], v[32:33], v[22:23]
	v_pk_fma_f32 v[30:31], v[0:1], v[0:1], v[30:31]
	s_waitcnt lgkmcnt(0)
	v_pk_add_f32 v[22:23], v[22:23], v[30:31]
	v_add_f32_e32 v2, v22, v23
	v_mov_b32_e32 v3, v2
	s_nop 1
	v_permlane16_swap_b32_e32 v2, v3
	v_cvt_pk_f16_f32 v5, v0, v1
	v_cvt_pk_f16_f32 v7, v14, v15
	v_cvt_pk_f16_f32 v6, v12, v13
	v_cvt_pk_f16_f32 v4, v32, v33
	s_waitcnt lgkmcnt(0)
	v_add_f32_e32 v0, v2, v3
	v_mov_b32_e32 v1, v0
	s_nop 1
	v_permlane32_swap_b32_e32 v0, v1
	v_cvt_pk_f16_f32 v3, v34, v35
	v_cvt_pk_f16_f32 v2, v24, v25
	global_store_dwordx4 v[26:27], v[6:9], off
	global_store_dwordx4 v[28:29], v[2:5], off
	s_and_saveexec_b64 s[16:17], s[4:5]
	s_cbranch_execz .LBB0_285
	v_lshl_add_u32 v136, v16, 4, s18
	s_waitcnt lgkmcnt(0)
	v_add_f32_e32 v2, v0, v1
	v_lshl_add_u64 v[0:1], v[136:137], 2, s[42:43]
	global_store_dword v[0:1], v2, off
	s_branch .LBB0_285

; #define PG8_STAGE(bufoff, gbase, voff) do { _Pragma("unroll") for (int _i = 0; _i < 2; ++_i) \
;         __builtin_amdgcn_global_load_lds((const unsigned*)((const char*)(gbase) + (voff)[_i]), (PG8_LAS unsigned*)(lds + (bufoff) + ldsw + _i * 8192), 16, 0, 0); } while (0)
; #define PG8_LDA(dst, b, h) do { _Pragma("unroll") for (int m = 0; m < 4; ++m) _Pragma("unroll") for (int k = 0; k < 2; ++k) dst[m][k] = *(const PG8_LAS bf16x8*)(lds + PG8_SA(b, h) + aoff + m * 2048 + k * 1024); } while (0)
; #define PG8_LDB(dst, b, h) do { _Pragma("unroll") for (int n = 0; n < 2; ++n) _Pragma("unroll") for (int k = 0; k < 2; ++k) dst[n][k] = *(const PG8_LAS bf16x8*)(lds + PG8_SB(b, h) + boff + n * 2048 + k * 1024); } while (0)
; #define PG8_WAIT_V(n) asm volatile("s_waitcnt vmcnt(" #n ")" ::: "memory")
; #define PG8_WAIT_L(n) asm volatile("s_waitcnt lgkmcnt(" #n ")" ::: "memory")
; #define PG8_BAR __builtin_amdgcn_s_barrier()
; #define PG8_SCHED __builtin_amdgcn_sched_barrier(0)
; template <class Epi, class Sched, bool ALIGN_EPI = false, bool SP2 = false, bool F16 = false, bool TOKPERM = false>
; __device__ __forceinline__ void gemm_phase(PG8_LAS unsigned char* lds, const Gemm g, const Sched& S, const Epi& E, int wv) {
;     ...
;         const bool has_next = S.next(ui + 1, nxt);
;         const char* nA = has_next ? (const char*)g.A + (size_t)nxt.pm * tstep : cA; const char* nB = has_next ? (const char*)g.Bt + (size_t)nxt.pn * tstep : cB;
;         for (int t = 0; t < nt; t += 2) {
;             const bool last = (t == nt - 2);
;             const char* a1 = cA + (size_t)(t + 1) * kstep;
;             const char* a2 = last ? nA : cA + (size_t)(t + 2) * kstep; const char* b2 = last ? nB : cB + (size_t)(t + 2) * kstep;
;             const char* a3 = a2 + kstep; const char* b3 = b2 + kstep;
;             if (last && has_next) S.a_ready(nxt);
;             if constexpr (SP2) {
;             PG8_LDB(B0, 0, 0); PG8_LDB(B1, 0, 1); PG8_SCHED; PG8_LDA(At, 0, 0); PG8_STAGE(PG8_SA(1, 1), a1 + hstep, voffA);
;             PG8_WAIT_V(8); PG8_WAIT_L(0); PG8_BAR; PG8_MMA(0, 0, At, B0); PG8_MMA(0, 1, At, B1); PG8_BAR; PG8_SCHED;
;             PG8_LDA(At, 0, 1); PG8_STAGE(PG8_SB(0, 0), b2, voffB); PG8_STAGE(PG8_SB(0, 1), b2 + hstep, voffB); PG8_STAGE(PG8_SA(0, 0), a2, voffA);
;             PG8_WAIT_V(8); PG8_WAIT_L(0); PG8_BAR; PG8_MMA(1, 0, At, B0); PG8_MMA(1, 1, At, B1); PG8_BAR; PG8_SCHED;
.LBB0_685:
	ds_read_b128 v[166:169], v149
	ds_read_b128 v[170:173], v150
	ds_read_b128 v[174:177], v151
	ds_read_b128 v[178:181], v152
	ds_read_b128 v[182:185], v153
	ds_read_b128 v[186:189], v154
	ds_read_b128 v[190:193], v155
	ds_read_b128 v[194:197], v156
	s_add_u32 s54, s52, 0xfffc0080
	s_addc_u32 s55, s53, -1
	s_cmp_eq_u32 s69, 12
	s_cselect_b32 s57, s13, s55
	s_cselect_b32 s56, s49, s54
	s_cselect_b32 s55, s11, s68
	s_cselect_b32 s54, s66, s67
	s_mov_b32 m0, s64
	v_lshl_add_u64 v[232:233], s[52:53], 0, v[138:139]
	ds_read_b128 v[198:201], v147
	ds_read_b128 v[202:205], v147 offset:1024
	ds_read_b128 v[206:209], v147 offset:2048
	ds_read_b128 v[210:213], v147 offset:3072
	ds_read_b128 v[214:217], v147 offset:4096
	ds_read_b128 v[218:221], v147 offset:5120
	ds_read_b128 v[222:225], v147 offset:6144
	ds_read_b128 v[228:231], v147 offset:7168
	global_load_lds_dwordx4 v[232:233], off
	v_lshl_add_u64 v[232:233], s[52:53], 0, v[140:141]
	s_mov_b32 m0, s65
	s_nop 0
	global_load_lds_dwordx4 v[232:233], off
	s_waitcnt vmcnt(8)
	s_waitcnt lgkmcnt(0)
	s_barrier
	s_setprio 1
	s_waitcnt lgkmcnt(0)
	v_mfma_f32_16x16x32_bf16 v[124:127], v[166:169], v[198:201], v[124:127]
	v_mfma_f32_16x16x32_bf16 v[120:123], v[174:177], v[198:201], v[120:123]
	v_mfma_f32_16x16x32_bf16 v[108:111], v[166:169], v[206:209], v[108:111]
	v_mfma_f32_16x16x32_bf16 v[104:107], v[174:177], v[206:209], v[104:107]
	v_mfma_f32_16x16x32_bf16 v[92:95], v[166:169], v[214:217], v[92:95]
	v_mfma_f32_16x16x32_bf16 v[88:91], v[174:177], v[214:217], v[88:91]
	v_mfma_f32_16x16x32_bf16 v[76:79], v[166:169], v[222:225], v[76:79]
	v_mfma_f32_16x16x32_bf16 v[72:75], v[174:177], v[222:225], v[72:75]
	v_mfma_f32_16x16x32_bf16 v[124:127], v[170:173], v[202:205], v[124:127]
	v_mfma_f32_16x16x32_bf16 v[120:123], v[178:181], v[202:205], v[120:123]
	v_mfma_f32_16x16x32_bf16 v[108:111], v[170:173], v[210:213], v[108:111]
	v_mfma_f32_16x16x32_bf16 v[104:107], v[178:181], v[210:213], v[104:107]
	v_mfma_f32_16x16x32_bf16 v[92:95], v[170:173], v[218:221], v[92:95]
	v_mfma_f32_16x16x32_bf16 v[88:91], v[178:181], v[218:221], v[88:91]
	v_mfma_f32_16x16x32_bf16 v[76:79], v[170:173], v[228:231], v[76:79]
	v_mfma_f32_16x16x32_bf16 v[72:75], v[178:181], v[228:231], v[72:75]
	s_setprio 0
	s_setprio 1
	v_mfma_f32_16x16x32_bf16 v[116:119], v[182:185], v[198:201], v[116:119]
	v_mfma_f32_16x16x32_bf16 v[112:115], v[190:193], v[198:201], v[112:115]
	v_mfma_f32_16x16x32_bf16 v[100:103], v[182:185], v[206:209], v[100:103]
	v_mfma_f32_16x16x32_bf16 v[96:99], v[190:193], v[206:209], v[96:99]
	v_mfma_f32_16x16x32_bf16 v[84:87], v[182:185], v[214:217], v[84:87]
	v_mfma_f32_16x16x32_bf16 v[80:83], v[190:193], v[214:217], v[80:83]
	v_mfma_f32_16x16x32_bf16 v[68:71], v[182:185], v[222:225], v[68:71]
	v_mfma_f32_16x16x32_bf16 v[64:67], v[190:193], v[222:225], v[64:67]
	v_mfma_f32_16x16x32_bf16 v[116:119], v[186:189], v[202:205], v[116:119]
	v_mfma_f32_16x16x32_bf16 v[112:115], v[194:197], v[202:205], v[112:115]
	v_mfma_f32_16x16x32_bf16 v[100:103], v[186:189], v[210:213], v[100:103]
	v_mfma_f32_16x16x32_bf16 v[96:99], v[194:197], v[210:213], v[96:99]
	v_mfma_f32_16x16x32_bf16 v[84:87], v[186:189], v[218:221], v[84:87]
	v_mfma_f32_16x16x32_bf16 v[80:83], v[194:197], v[218:221], v[80:83]
	v_mfma_f32_16x16x32_bf16 v[68:71], v[186:189], v[228:231], v[68:71]
	v_mfma_f32_16x16x32_bf16 v[64:67], v[194:197], v[228:231], v[64:67]
	s_setprio 0
	s_barrier
	s_mov_b32 m0, s2
	v_lshl_add_u64 v[232:233], s[54:55], 0, v[130:131]
	s_add_u32 s70, s54, 0x40000
	ds_read_b128 v[198:201], v147 offset:16384
	ds_read_b128 v[202:205], v147 offset:17408
	ds_read_b128 v[206:209], v147 offset:18432
	ds_read_b128 v[210:213], v147 offset:19456
	ds_read_b128 v[214:217], v147 offset:20480
	ds_read_b128 v[218:221], v147 offset:21504
	ds_read_b128 v[222:225], v147 offset:22528
	ds_read_b128 v[228:231], v147 offset:23552
	global_load_lds_dwordx4 v[232:233], off
	v_lshl_add_u64 v[234:235], s[54:55], 0, v[134:135]
	s_mov_b32 m0, s3
	s_addc_u32 s71, s55, 0
	global_load_lds_dwordx4 v[234:235], off
	v_lshl_add_u64 v[236:237], s[70:71], 0, v[130:131]
	s_mov_b32 m0, s20
	v_lshl_add_u64 v[238:239], s[56:57], 0, v[132:133]
	global_load_lds_dwordx4 v[236:237], off
	v_lshl_add_u64 v[236:237], s[70:71], 0, v[134:135]
	s_mov_b32 m0, s21
	s_nop 0
	global_load_lds_dwordx4 v[236:237], off
	v_lshl_add_u64 v[236:237], s[56:57], 0, v[128:129]
	s_mov_b32 m0, s1
	s_nop 0
	global_load_lds_dwordx4 v[236:237], off
	s_mov_b32 m0, s22
	s_nop 0
	global_load_lds_dwordx4 v[238:239], off
	s_waitcnt vmcnt(8)
	s_waitcnt lgkmcnt(0)
	s_barrier
; #define PG8_STAGE(bufoff, gbase, voff) do { _Pragma("unroll") for (int _i = 0; _i < 2; ++_i) \
;         __builtin_amdgcn_global_load_lds((const unsigned*)((const char*)(gbase) + (voff)[_i]), (PG8_LAS unsigned*)(lds + (bufoff) + ldsw + _i * 8192), 16, 0, 0); } while (0)
; #define PG8_LDA(dst, b, h) do { _Pragma("unroll") for (int m = 0; m < 4; ++m) _Pragma("unroll") for (int k = 0; k < 2; ++k) dst[m][k] = *(const PG8_LAS bf16x8*)(lds + PG8_SA(b, h) + aoff + m * 2048 + k * 1024); } while (0)
; #define PG8_LDB(dst, b, h) do { _Pragma("unroll") for (int n = 0; n < 2; ++n) _Pragma("unroll") for (int k = 0; k < 2; ++k) dst[n][k] = *(const PG8_LAS bf16x8*)(lds + PG8_SB(b, h) + boff + n * 2048 + k * 1024); } while (0)
; #define PG8_MMA(ai, bj, At, Bt) do { __builtin_amdgcn_s_setprio(1); _Pragma("unroll") for (int m = 0; m < 4; ++m) _Pragma("unroll") for (int n = 0; n < 2; ++n) _Pragma("unroll") for (int k = 0; k < 2; ++k) \
;         acc[ai][bj][m][n] = mma16<F16>(Bt[n][k], At[m][k], acc[ai][bj][m][n]); __builtin_amdgcn_s_setprio(0); } while (0)
; #define PG8_WAIT_V(n) asm volatile("s_waitcnt vmcnt(" #n ")" ::: "memory")
; #define PG8_WAIT_L(n) asm volatile("s_waitcnt lgkmcnt(" #n ")" ::: "memory")
; #define PG8_BAR __builtin_amdgcn_s_barrier()
; #define PG8_SCHED __builtin_amdgcn_sched_barrier(0)
; template <class Epi, class Sched, bool ALIGN_EPI = false, bool SP2 = false, bool F16 = false, bool TOKPERM = false>
; __device__ __forceinline__ void gemm_phase(PG8_LAS unsigned char* lds, const Gemm g, const Sched& S, const Epi& E, int wv) {
;     ...
;             PG8_WAIT_V(8); PG8_WAIT_L(0); PG8_BAR; PG8_MMA(1, 0, At, B0); PG8_MMA(1, 1, At, B1); PG8_BAR; PG8_SCHED;
;             PG8_LDB(B0, 1, 0); PG8_LDB(B1, 1, 1); PG8_SCHED; PG8_LDA(At, 1, 0); PG8_STAGE(PG8_SA(0, 1), a2 + hstep, voffA);
;             PG8_WAIT_V(8); PG8_WAIT_L(0); PG8_BAR; PG8_MMA(0, 0, At, B0); PG8_MMA(0, 1, At, B1); PG8_BAR; PG8_SCHED;
	s_setprio 1
	s_waitcnt lgkmcnt(0)
	v_mfma_f32_16x16x32_bf16 v[60:63], v[166:169], v[198:201], v[60:63]
	v_mfma_f32_16x16x32_bf16 v[56:59], v[174:177], v[198:201], v[56:59]
	v_mfma_f32_16x16x32_bf16 v[44:47], v[166:169], v[206:209], v[44:47]
	v_mfma_f32_16x16x32_bf16 v[40:43], v[174:177], v[206:209], v[40:43]
	v_mfma_f32_16x16x32_bf16 v[28:31], v[166:169], v[214:217], v[28:31]
	v_mfma_f32_16x16x32_bf16 v[24:27], v[174:177], v[214:217], v[24:27]
	v_mfma_f32_16x16x32_bf16 v[12:15], v[166:169], v[222:225], v[12:15]
	v_mfma_f32_16x16x32_bf16 v[8:11], v[174:177], v[222:225], v[8:11]
	v_mfma_f32_16x16x32_bf16 v[60:63], v[170:173], v[202:205], v[60:63]
	v_mfma_f32_16x16x32_bf16 v[56:59], v[178:181], v[202:205], v[56:59]
	v_mfma_f32_16x16x32_bf16 v[44:47], v[170:173], v[210:213], v[44:47]
	v_mfma_f32_16x16x32_bf16 v[40:43], v[178:181], v[210:213], v[40:43]
	v_mfma_f32_16x16x32_bf16 v[28:31], v[170:173], v[218:221], v[28:31]
	v_mfma_f32_16x16x32_bf16 v[24:27], v[178:181], v[218:221], v[24:27]
	v_mfma_f32_16x16x32_bf16 v[12:15], v[170:173], v[228:231], v[12:15]
	v_mfma_f32_16x16x32_bf16 v[8:11], v[178:181], v[228:231], v[8:11]
	s_setprio 0
	s_setprio 1
	v_mfma_f32_16x16x32_bf16 v[52:55], v[182:185], v[198:201], v[52:55]
	v_mfma_f32_16x16x32_bf16 v[48:51], v[190:193], v[198:201], v[48:51]
	v_mfma_f32_16x16x32_bf16 v[36:39], v[182:185], v[206:209], v[36:39]
	v_mfma_f32_16x16x32_bf16 v[32:35], v[190:193], v[206:209], v[32:35]
	v_mfma_f32_16x16x32_bf16 v[20:23], v[182:185], v[214:217], v[20:23]
	v_mfma_f32_16x16x32_bf16 v[16:19], v[190:193], v[214:217], v[16:19]
	v_mfma_f32_16x16x32_bf16 v[4:7], v[182:185], v[222:225], v[4:7]
	v_mfma_f32_16x16x32_bf16 v[0:3], v[190:193], v[222:225], v[0:3]
	v_mfma_f32_16x16x32_bf16 v[52:55], v[186:189], v[202:205], v[52:55]
	v_mfma_f32_16x16x32_bf16 v[48:51], v[194:197], v[202:205], v[48:51]
	v_mfma_f32_16x16x32_bf16 v[36:39], v[186:189], v[210:213], v[36:39]
	v_mfma_f32_16x16x32_bf16 v[32:35], v[194:197], v[210:213], v[32:35]
	v_mfma_f32_16x16x32_bf16 v[20:23], v[186:189], v[218:221], v[20:23]
	v_mfma_f32_16x16x32_bf16 v[16:19], v[194:197], v[218:221], v[16:19]
	v_mfma_f32_16x16x32_bf16 v[4:7], v[186:189], v[228:231], v[4:7]
	v_mfma_f32_16x16x32_bf16 v[0:3], v[194:197], v[228:231], v[0:3]
	s_setprio 0
	s_barrier
	ds_read_b128 v[166:169], v157
	ds_read_b128 v[170:173], v158
	ds_read_b128 v[174:177], v159
	ds_read_b128 v[178:181], v160
	ds_read_b128 v[182:185], v161
	ds_read_b128 v[186:189], v162
	ds_read_b128 v[190:193], v163
	ds_read_b128 v[194:197], v164
	s_add_u32 s56, s56, 0x40000
	s_addc_u32 s57, s57, 0
	s_mov_b32 m0, s23
	v_lshl_add_u64 v[240:241], s[56:57], 0, v[128:129]
	ds_read_b128 v[198:201], v147 offset:32768
	ds_read_b128 v[202:205], v147 offset:33792
	ds_read_b128 v[206:209], v147 offset:34816
	ds_read_b128 v[210:213], v147 offset:35840
	ds_read_b128 v[214:217], v147 offset:36864
	ds_read_b128 v[218:221], v147 offset:37888
	ds_read_b128 v[222:225], v147 offset:38912
	ds_read_b128 v[228:231], v147 offset:39936
	global_load_lds_dwordx4 v[240:241], off
	v_lshl_add_u64 v[240:241], s[56:57], 0, v[132:133]
	s_mov_b32 m0, s33
	s_nop 0
	global_load_lds_dwordx4 v[240:241], off
	s_waitcnt vmcnt(8)
	s_waitcnt lgkmcnt(0)
	s_barrier
	s_setprio 1
	s_waitcnt lgkmcnt(0)
	v_mfma_f32_16x16x32_bf16 v[124:127], v[166:169], v[198:201], v[124:127]
	v_mfma_f32_16x16x32_bf16 v[120:123], v[174:177], v[198:201], v[120:123]
	v_mfma_f32_16x16x32_bf16 v[108:111], v[166:169], v[206:209], v[108:111]
	v_mfma_f32_16x16x32_bf16 v[104:107], v[174:177], v[206:209], v[104:107]
	v_mfma_f32_16x16x32_bf16 v[92:95], v[166:169], v[214:217], v[92:95]
	v_mfma_f32_16x16x32_bf16 v[88:91], v[174:177], v[214:217], v[88:91]
	v_mfma_f32_16x16x32_bf16 v[76:79], v[166:169], v[222:225], v[76:79]
	v_mfma_f32_16x16x32_bf16 v[72:75], v[174:177], v[222:225], v[72:75]
	v_mfma_f32_16x16x32_bf16 v[124:127], v[170:173], v[202:205], v[124:127]
	v_mfma_f32_16x16x32_bf16 v[120:123], v[178:181], v[202:205], v[120:123]
	v_mfma_f32_16x16x32_bf16 v[108:111], v[170:173], v[210:213], v[108:111]
	v_mfma_f32_16x16x32_bf16 v[104:107], v[178:181], v[210:213], v[104:107]
	v_mfma_f32_16x16x32_bf16 v[92:95], v[170:173], v[218:221], v[92:95]
	v_mfma_f32_16x16x32_bf16 v[88:91], v[178:181], v[218:221], v[88:91]
	v_mfma_f32_16x16x32_bf16 v[76:79], v[170:173], v[228:231], v[76:79]
	v_mfma_f32_16x16x32_bf16 v[72:75], v[178:181], v[228:231], v[72:75]
	s_setprio 0
	s_setprio 1
	v_mfma_f32_16x16x32_bf16 v[116:119], v[182:185], v[198:201], v[116:119]
	v_mfma_f32_16x16x32_bf16 v[112:115], v[190:193], v[198:201], v[112:115]
	v_mfma_f32_16x16x32_bf16 v[100:103], v[182:185], v[206:209], v[100:103]
	v_mfma_f32_16x16x32_bf16 v[96:99], v[190:193], v[206:209], v[96:99]
	v_mfma_f32_16x16x32_bf16 v[84:87], v[182:185], v[214:217], v[84:87]
	v_mfma_f32_16x16x32_bf16 v[80:83], v[190:193], v[214:217], v[80:83]
	v_mfma_f32_16x16x32_bf16 v[68:71], v[182:185], v[222:225], v[68:71]
	v_mfma_f32_16x16x32_bf16 v[64:67], v[190:193], v[222:225], v[64:67]
	v_mfma_f32_16x16x32_bf16 v[116:119], v[186:189], v[202:205], v[116:119]
	v_mfma_f32_16x16x32_bf16 v[112:115], v[194:197], v[202:205], v[112:115]
	v_mfma_f32_16x16x32_bf16 v[100:103], v[186:189], v[210:213], v[100:103]
	v_mfma_f32_16x16x32_bf16 v[96:99], v[194:197], v[210:213], v[96:99]
	v_mfma_f32_16x16x32_bf16 v[84:87], v[186:189], v[218:221], v[84:87]
	v_mfma_f32_16x16x32_bf16 v[80:83], v[194:197], v[218:221], v[80:83]
	v_mfma_f32_16x16x32_bf16 v[68:71], v[186:189], v[228:231], v[68:71]
	v_mfma_f32_16x16x32_bf16 v[64:67], v[194:197], v[228:231], v[64:67]
	s_setprio 0
	s_barrier
; #define PG8_STAGE(bufoff, gbase, voff) do { _Pragma("unroll") for (int _i = 0; _i < 2; ++_i) \
;         __builtin_amdgcn_global_load_lds((const unsigned*)((const char*)(gbase) + (voff)[_i]), (PG8_LAS unsigned*)(lds + (bufoff) + ldsw + _i * 8192), 16, 0, 0); } while (0)
; #define PG8_LDA(dst, b, h) do { _Pragma("unroll") for (int m = 0; m < 4; ++m) _Pragma("unroll") for (int k = 0; k < 2; ++k) dst[m][k] = *(const PG8_LAS bf16x8*)(lds + PG8_SA(b, h) + aoff + m * 2048 + k * 1024); } while (0)
; #define PG8_MMA(ai, bj, At, Bt) do { __builtin_amdgcn_s_setprio(1); _Pragma("unroll") for (int m = 0; m < 4; ++m) _Pragma("unroll") for (int n = 0; n < 2; ++n) _Pragma("unroll") for (int k = 0; k < 2; ++k) \
;         acc[ai][bj][m][n] = mma16<F16>(Bt[n][k], At[m][k], acc[ai][bj][m][n]); __builtin_amdgcn_s_setprio(0); } while (0)
; #define PG8_WAIT_V(n) asm volatile("s_waitcnt vmcnt(" #n ")" ::: "memory")
; #define PG8_WAIT_L(n) asm volatile("s_waitcnt lgkmcnt(" #n ")" ::: "memory")
; #define PG8_BAR __builtin_amdgcn_s_barrier()
; #define PG8_SCHED __builtin_amdgcn_sched_barrier(0)
; template <class Epi, class Sched, bool ALIGN_EPI = false, bool SP2 = false, bool F16 = false, bool TOKPERM = false>
; __device__ __forceinline__ void gemm_phase(PG8_LAS unsigned char* lds, const Gemm g, const Sched& S, const Epi& E, int wv) {
;     ...
;             PG8_LDA(At, 1, 1); PG8_STAGE(PG8_SB(1, 0), b3, voffB); PG8_STAGE(PG8_SB(1, 1), b3 + hstep, voffB); PG8_STAGE(PG8_SA(1, 0), a3, voffA);
;             PG8_WAIT_V(8); PG8_WAIT_L(0); PG8_BAR; PG8_MMA(1, 0, At, B0); PG8_MMA(1, 1, At, B1); PG8_BAR; PG8_SCHED;
;   __device__ __forceinline__ void operator()(const pg8::f32x4 (&acc)[2][2][4][2], const pg8::Unit& u, int wr, int wc, int fr, int fq) const {
;     ...
;     const int row0 = u.pm * 256 + wr * 64 + fr + z, colb = u.pn * 256 + wc * 32 + 8 * fq + z;
; #pragma unroll
;     for (int ai = 0; ai < 2; ++ai)
; #pragma unroll
;       for (int m = 0; m < 4; ++m) {
;         const int tok = row0 + ai * 128 + m * 16; float ss = 0.f;
; #pragma unroll
;         for (int bj = 0; bj < 2; ++bj) {
;           const unsigned off = (unsigned)tok * DM + colb + 128 * bj;
;           f8_t n = __builtin_convertvector(*(const h8_t*)(x16 + off), f8_t);
	s_mov_b32 m0, s37
	v_lshl_add_u64 v[232:233], v[232:233], 0, s[8:9]
	s_add_u32 s54, s54, 0x40080
	ds_read_b128 v[198:201], v147 offset:49152
	ds_read_b128 v[202:205], v147 offset:50176
	ds_read_b128 v[206:209], v147 offset:51200
	ds_read_b128 v[210:213], v147 offset:52224
	ds_read_b128 v[214:217], v147 offset:53248
	ds_read_b128 v[218:221], v147 offset:54272
	ds_read_b128 v[222:225], v147 offset:55296
	ds_read_b128 v[228:231], v147 offset:56320
	global_load_lds_dwordx4 v[232:233], off
	v_lshl_add_u64 v[232:233], v[234:235], 0, s[8:9]
	s_mov_b32 m0, s44
	s_addc_u32 s55, s55, 0
	global_load_lds_dwordx4 v[232:233], off
	v_lshl_add_u64 v[232:233], s[54:55], 0, v[130:131]
	s_mov_b32 m0, s58
	s_nop 0
	global_load_lds_dwordx4 v[232:233], off
	v_lshl_add_u64 v[232:233], s[54:55], 0, v[134:135]
	s_mov_b32 m0, s59
	s_nop 0
	global_load_lds_dwordx4 v[232:233], off
	v_lshl_add_u64 v[232:233], v[236:237], 0, s[8:9]
	s_mov_b32 m0, s45
	s_nop 0
	global_load_lds_dwordx4 v[232:233], off
	v_lshl_add_u64 v[232:233], v[238:239], 0, s[8:9]
	s_mov_b32 m0, s51
	s_nop 0
	global_load_lds_dwordx4 v[232:233], off
	s_waitcnt vmcnt(8)
	s_waitcnt lgkmcnt(0)
	s_barrier
	s_setprio 1
	s_waitcnt lgkmcnt(0)
	v_mfma_f32_16x16x32_bf16 v[60:63], v[166:169], v[198:201], v[60:63]
	v_mfma_f32_16x16x32_bf16 v[56:59], v[174:177], v[198:201], v[56:59]
	v_mfma_f32_16x16x32_bf16 v[44:47], v[166:169], v[206:209], v[44:47]
	v_mfma_f32_16x16x32_bf16 v[40:43], v[174:177], v[206:209], v[40:43]
	v_mfma_f32_16x16x32_bf16 v[28:31], v[166:169], v[214:217], v[28:31]
	v_mfma_f32_16x16x32_bf16 v[24:27], v[174:177], v[214:217], v[24:27]
	v_mfma_f32_16x16x32_bf16 v[12:15], v[166:169], v[222:225], v[12:15]
	v_mfma_f32_16x16x32_bf16 v[8:11], v[174:177], v[222:225], v[8:11]
	v_mfma_f32_16x16x32_bf16 v[60:63], v[170:173], v[202:205], v[60:63]
	v_mfma_f32_16x16x32_bf16 v[56:59], v[178:181], v[202:205], v[56:59]
	v_mfma_f32_16x16x32_bf16 v[44:47], v[170:173], v[210:213], v[44:47]
	v_mfma_f32_16x16x32_bf16 v[40:43], v[178:181], v[210:213], v[40:43]
	v_mfma_f32_16x16x32_bf16 v[28:31], v[170:173], v[218:221], v[28:31]
	v_mfma_f32_16x16x32_bf16 v[24:27], v[178:181], v[218:221], v[24:27]
	v_mfma_f32_16x16x32_bf16 v[12:15], v[170:173], v[228:231], v[12:15]
	v_mfma_f32_16x16x32_bf16 v[8:11], v[178:181], v[228:231], v[8:11]
	s_setprio 0
	s_setprio 1
	v_mfma_f32_16x16x32_bf16 v[52:55], v[182:185], v[198:201], v[52:55]
	v_mfma_f32_16x16x32_bf16 v[48:51], v[190:193], v[198:201], v[48:51]
	v_mfma_f32_16x16x32_bf16 v[36:39], v[182:185], v[206:209], v[36:39]
	v_mfma_f32_16x16x32_bf16 v[32:35], v[190:193], v[206:209], v[32:35]
	v_mfma_f32_16x16x32_bf16 v[20:23], v[182:185], v[214:217], v[20:23]
	v_mfma_f32_16x16x32_bf16 v[16:19], v[190:193], v[214:217], v[16:19]
	v_mfma_f32_16x16x32_bf16 v[4:7], v[182:185], v[222:225], v[4:7]
	v_mfma_f32_16x16x32_bf16 v[0:3], v[190:193], v[222:225], v[0:3]
	v_mfma_f32_16x16x32_bf16 v[52:55], v[186:189], v[202:205], v[52:55]
	v_mfma_f32_16x16x32_bf16 v[48:51], v[194:197], v[202:205], v[48:51]
	v_mfma_f32_16x16x32_bf16 v[36:39], v[186:189], v[210:213], v[36:39]
	v_mfma_f32_16x16x32_bf16 v[32:35], v[194:197], v[210:213], v[32:35]
	v_mfma_f32_16x16x32_bf16 v[20:23], v[186:189], v[218:221], v[20:23]
	v_mfma_f32_16x16x32_bf16 v[16:19], v[194:197], v[218:221], v[16:19]
	v_mfma_f32_16x16x32_bf16 v[4:7], v[186:189], v[228:231], v[4:7]
	v_mfma_f32_16x16x32_bf16 v[0:3], v[194:197], v[228:231], v[0:3]
	s_setprio 0
	s_barrier
	s_add_i32 s69, s69, 2
	s_add_u32 s52, s52, 0x100
	s_addc_u32 s53, s53, 0
	s_add_u32 s67, s67, 0x100
	s_addc_u32 s68, s68, 0
	s_cmp_gt_u32 s69, 13
	s_cbranch_scc0 .LBB0_685
	s_lshl_b32 s11, s50, 8
	v_lshl_or_b32 v166, s48, 8, v148
	v_mov_b32 v136, 0
	v_xor_b32_e32 v169, 32, v165
	v_add3_u32 v167, s11, v146, v136
	v_add_u32_e32 v168, v166, v136
	v_lshl_add_u32 v136, v167, 10, v168
	v_lshl_add_u64 v[178:179], v[136:137], 1, s[40:41]
	v_add_u32_e32 v136, 0x80, v136
	global_load_dwordx4 v[170:173], v[178:179], off
	v_lshl_add_u64 v[180:181], v[136:137], 1, s[40:41]
	global_load_dwordx4 v[174:177], v[180:181], off
	v_add_u32_e32 v136, 16, v167
	v_lshl_add_u32 v136, v136, 10, v168
	v_lshl_add_u64 v[224:225], v[136:137], 1, s[40:41]
	v_add_u32_e32 v136, 0x80, v136
	global_load_dwordx4 v[192:195], v[224:225], off
	v_lshl_add_u64 v[248:249], v[136:137], 1, s[40:41]
	global_load_dwordx4 v[196:199], v[248:249], off
	v_add_u32_e32 v136, 32, v167
	v_lshl_add_u32 v136, v136, 10, v168
	v_lshl_add_u64 v[224:225], v[136:137], 1, s[40:41]
	v_add_u32_e32 v136, 0x80, v136
	global_load_dwordx4 v[200:203], v[224:225], off
	v_lshl_add_u64 v[248:249], v[136:137], 1, s[40:41]
	global_load_dwordx4 v[204:207], v[248:249], off
	v_add_u32_e32 v136, 48, v167
	v_lshl_add_u32 v136, v136, 10, v168
	v_lshl_add_u64 v[224:225], v[136:137], 1, s[40:41]
	v_add_u32_e32 v136, 0x80, v136
	global_load_dwordx4 v[208:211], v[224:225], off
	v_lshl_add_u64 v[248:249], v[136:137], 1, s[40:41]
	global_load_dwordx4 v[212:215], v[248:249], off
	v_add_u32_e32 v136, 0x80, v167
	v_lshl_add_u32 v136, v136, 10, v168
	v_lshl_add_u64 v[224:225], v[136:137], 1, s[40:41]
	v_add_u32_e32 v136, 0x80, v136
	global_load_dwordx4 v[216:219], v[224:225], off
	v_lshl_add_u64 v[248:249], v[136:137], 1, s[40:41]
	global_load_dwordx4 v[220:223], v[248:249], off
	v_add_u32_e32 v136, 0x90, v167
	v_lshl_add_u32 v136, v136, 10, v168
	v_lshl_add_u64 v[224:225], v[136:137], 1, s[40:41]
	v_add_u32_e32 v136, 0x80, v136
	global_load_dwordx4 v[228:231], v[224:225], off
	v_lshl_add_u64 v[248:249], v[136:137], 1, s[40:41]
	global_load_dwordx4 v[244:247], v[248:249], off
	v_and_b32_e32 v166, 64, v165
	v_xor_b32_e32 v136, 16, v165
	v_add_u32_e32 v166, 64, v166
	v_cmp_lt_i32_e32 vcc, v136, v166
	s_lshl_b32 s11, s48, 2
	s_or_b32 s11, s11, s36
	v_cndmask_b32_e32 v136, v165, v136, vcc
	v_cmp_lt_i32_e32 vcc, v169, v166
	v_lshlrev_b32_e32 v166, 2, v136
	s_waitcnt vmcnt(10)
;   __device__ __forceinline__ void operator()(const pg8::f32x4 (&acc)[2][2][4][2], const pg8::Unit& u, int wr, int wc, int fr, int fq) const {
;     ...
;         const int tok = row0 + ai * 128 + m * 16; float ss = 0.f;
; #pragma unroll
;         for (int bj = 0; bj < 2; ++bj) {
;           const unsigned off = (unsigned)tok * DM + colb + 128 * bj;
;           f8_t n = __builtin_convertvector(*(const h8_t*)(x16 + off), f8_t);
; #pragma unroll
;           for (int c = 0; c < 4; ++c) { n[c] += sc * acc[ai][bj][m][0][c]; n[4 + c] += sc * acc[ai][bj][m][1][c]; }
;           if (aux) {
;             *(h8_t*)(x16 + off) = __builtin_convertvector(n, h8_t);
;             ss += ((n[0] * n[0] + n[1] * n[1]) + (n[2] * n[2] + n[3] * n[3])) + ((n[4] * n[4] + n[5] * n[5]) + (n[6] * n[6] + n[7] * n[7]));
;           } else {
;             *(f32x4*)(xout + off) = (f32x4){n[0], n[1], n[2], n[3]}; *(f32x4*)(xout + off + 4) = (f32x4){n[4], n[5], n[6], n[7]};
;           }
;         }
;         if (aux) { ss += __shfl_xor(ss, 16); ss += __shfl_xor(ss, 32); if (fq == 0) ssq[(unsigned)tok * 16 + u.pn * 4 + wc] = ss; }
	v_cvt_f32_f16_e32 v182, v173
	v_cvt_f32_f16_sdwa v183, v173 dst_sel:DWORD dst_unused:UNUSED_PAD src0_sel:WORD_1
	v_cvt_f32_f16_e32 v184, v171
	v_cvt_f32_f16_sdwa v185, v171 dst_sel:DWORD dst_unused:UNUSED_PAD src0_sel:WORD_1
	v_cvt_f32_f16_e32 v186, v172
	v_cvt_f32_f16_sdwa v187, v172 dst_sel:DWORD dst_unused:UNUSED_PAD src0_sel:WORD_1
	v_cvt_f32_f16_e32 v172, v170
	v_cvt_f32_f16_sdwa v173, v170 dst_sel:DWORD dst_unused:UNUSED_PAD src0_sel:WORD_1
	v_cvt_f32_f16_e32 v170, v177
	v_cvt_f32_f16_sdwa v171, v177 dst_sel:DWORD dst_unused:UNUSED_PAD src0_sel:WORD_1
	v_cvt_f32_f16_e32 v188, v175
	v_cvt_f32_f16_sdwa v189, v175 dst_sel:DWORD dst_unused:UNUSED_PAD src0_sel:WORD_1
	v_cvt_f32_f16_e32 v190, v176
	v_cvt_f32_f16_sdwa v191, v176 dst_sel:DWORD dst_unused:UNUSED_PAD src0_sel:WORD_1
	v_cvt_f32_f16_e32 v176, v174
	v_cvt_f32_f16_sdwa v177, v174 dst_sel:DWORD dst_unused:UNUSED_PAD src0_sel:WORD_1
	v_pk_add_f32 v[124:125], v[124:125], v[172:173]
	v_pk_add_f32 v[172:173], v[120:121], v[186:187]
	v_pk_add_f32 v[126:127], v[126:127], v[184:185]
	v_pk_add_f32 v[122:123], v[122:123], v[182:183]
	v_cvt_pk_f16_f32 v120, v172, v173
	v_cvt_pk_f16_f32 v121, v122, v123
	v_pk_mul_f32 v[174:175], v[124:125], v[124:125]
	v_pk_mul_f32 v[182:183], v[126:127], v[126:127]
	v_pk_fma_f32 v[174:175], v[172:173], v[172:173], v[174:175]
	v_pk_fma_f32 v[182:183], v[122:123], v[122:123], v[182:183]
	v_pk_add_f32 v[176:177], v[116:117], v[176:177]
	v_pk_add_f32 v[116:117], v[112:113], v[190:191]
	v_pk_add_f32 v[184:185], v[118:119], v[188:189]
	v_pk_add_f32 v[112:113], v[114:115], v[170:171]
	v_pk_fma_f32 v[174:175], v[176:177], v[176:177], v[174:175]
	v_pk_fma_f32 v[182:183], v[184:185], v[184:185], v[182:183]
	v_pk_fma_f32 v[174:175], v[116:117], v[116:117], v[174:175]
	v_pk_fma_f32 v[182:183], v[112:113], v[112:113], v[182:183]
	v_pk_add_f32 v[174:175], v[174:175], v[182:183]
	v_add_f32_e32 v114, v174, v175
	v_mov_b32_e32 v115, v114
	s_nop 1
	v_permlane16_swap_b32_e32 v114, v115
	v_cndmask_b32_e32 v169, v165, v169, vcc
	v_cvt_pk_f16_f32 v119, v126, v127
	v_cvt_pk_f16_f32 v118, v124, v125
	global_store_dwordx4 v[178:179], v[118:121], off
	s_nop 1
	v_cvt_pk_f16_f32 v119, v112, v113
	s_waitcnt lgkmcnt(0)
	v_add_f32_e32 v113, v114, v115
	v_lshlrev_b32_e32 v112, 2, v169
	v_mov_b32_e32 v114, v113
	s_nop 1
	v_permlane32_swap_b32_e32 v113, v114
	v_cvt_pk_f16_f32 v118, v116, v117
	v_cvt_pk_f16_f32 v117, v184, v185
	v_cvt_pk_f16_f32 v116, v176, v177
	global_store_dwordx4 v[180:181], v[116:119], off
	s_and_saveexec_b64 s[48:49], s[4:5]
	s_cbranch_execz .LBB0_688
	v_lshl_add_u32 v136, v167, 4, s11
	s_waitcnt lgkmcnt(0)
	v_add_f32_e32 v113, v113, v114
	v_lshl_add_u64 v[114:115], v[136:137], 2, s[42:43]
	global_store_dword v[114:115], v113, off
.LBB0_688:
	s_or_b64 exec, exec, s[48:49]
	v_add_u32_e32 v113, 16, v167
	v_lshl_add_u32 v136, v113, 10, v168
	v_lshl_add_u64 v[122:123], v[136:137], 1, s[40:41]
	v_add_u32_e32 v136, 0x80, v136
	v_lshl_add_u64 v[124:125], v[136:137], 1, s[40:41]
	s_waitcnt lgkmcnt(0)
	s_waitcnt vmcnt(10)
	v_cvt_f32_f16_e32 v126, v195
	v_cvt_f32_f16_sdwa v127, v195 dst_sel:DWORD dst_unused:UNUSED_PAD src0_sel:WORD_1
	v_cvt_f32_f16_e32 v170, v193
	v_cvt_f32_f16_sdwa v171, v193 dst_sel:DWORD dst_unused:UNUSED_PAD src0_sel:WORD_1
	v_cvt_f32_f16_e32 v172, v194
	v_cvt_f32_f16_sdwa v173, v194 dst_sel:DWORD dst_unused:UNUSED_PAD src0_sel:WORD_1
	v_cvt_f32_f16_e32 v116, v192
	v_cvt_f32_f16_sdwa v117, v192 dst_sel:DWORD dst_unused:UNUSED_PAD src0_sel:WORD_1
	v_cvt_f32_f16_e32 v114, v199
	v_cvt_f32_f16_sdwa v115, v199 dst_sel:DWORD dst_unused:UNUSED_PAD src0_sel:WORD_1
	v_cvt_f32_f16_e32 v174, v197
	v_cvt_f32_f16_sdwa v175, v197 dst_sel:DWORD dst_unused:UNUSED_PAD src0_sel:WORD_1
	v_cvt_f32_f16_e32 v176, v198
	v_cvt_f32_f16_sdwa v177, v198 dst_sel:DWORD dst_unused:UNUSED_PAD src0_sel:WORD_1
	v_cvt_f32_f16_e32 v120, v196
	v_cvt_f32_f16_sdwa v121, v196 dst_sel:DWORD dst_unused:UNUSED_PAD src0_sel:WORD_1
	v_pk_add_f32 v[108:109], v[108:109], v[116:117]
	v_pk_add_f32 v[116:117], v[104:105], v[172:173]
	v_pk_add_f32 v[110:111], v[110:111], v[170:171]
	v_pk_add_f32 v[106:107], v[106:107], v[126:127]
	v_pk_add_f32 v[120:121], v[100:101], v[120:121]
	v_pk_add_f32 v[170:171], v[96:97], v[176:177]
	v_pk_add_f32 v[172:173], v[102:103], v[174:175]
	v_pk_add_f32 v[96:97], v[98:99], v[114:115]
	v_cvt_pk_f16_f32 v105, v106, v107
	v_cvt_pk_f16_f32 v104, v116, v117
	v_pk_mul_f32 v[118:119], v[108:109], v[108:109]
	v_pk_mul_f32 v[126:127], v[110:111], v[110:111]
	v_pk_fma_f32 v[118:119], v[116:117], v[116:117], v[118:119]
	v_pk_fma_f32 v[126:127], v[106:107], v[106:107], v[126:127]
	v_pk_fma_f32 v[118:119], v[120:121], v[120:121], v[118:119]
	v_pk_fma_f32 v[126:127], v[172:173], v[172:173], v[126:127]
	v_pk_fma_f32 v[118:119], v[170:171], v[170:171], v[118:119]
	v_pk_fma_f32 v[126:127], v[96:97], v[96:97], v[126:127]
	v_pk_add_f32 v[118:119], v[118:119], v[126:127]
	v_add_f32_e32 v98, v118, v119
	v_mov_b32_e32 v99, v98
	s_nop 1
	v_permlane16_swap_b32_e32 v98, v99
	v_cvt_pk_f16_f32 v101, v96, v97
	v_cvt_pk_f16_f32 v103, v110, v111
	v_cvt_pk_f16_f32 v102, v108, v109
	v_cvt_pk_f16_f32 v100, v170, v171
	s_waitcnt lgkmcnt(0)
	v_add_f32_e32 v96, v98, v99
	v_mov_b32_e32 v97, v96
	s_nop 1
	v_permlane32_swap_b32_e32 v96, v97
	v_cvt_pk_f16_f32 v99, v172, v173
	v_cvt_pk_f16_f32 v98, v120, v121
	global_store_dwordx4 v[122:123], v[102:105], off
	global_store_dwordx4 v[124:125], v[98:101], off
	s_and_saveexec_b64 s[48:49], s[4:5]
	s_cbranch_execz .LBB0_690
	v_lshl_add_u32 v136, v113, 4, s11
	s_waitcnt lgkmcnt(0)
	v_add_f32_e32 v98, v96, v97
	v_lshl_add_u64 v[96:97], v[136:137], 2, s[42:43]
	global_store_dword v[96:97], v98, off
;   __device__ __forceinline__ void operator()(const pg8::f32x4 (&acc)[2][2][4][2], const pg8::Unit& u, int wr, int wc, int fr, int fq) const {
;     ...
;         const int tok = row0 + ai * 128 + m * 16; float ss = 0.f;
; #pragma unroll
;         for (int bj = 0; bj < 2; ++bj) {
;           const unsigned off = (unsigned)tok * DM + colb + 128 * bj;
;           f8_t n = __builtin_convertvector(*(const h8_t*)(x16 + off), f8_t);
; #pragma unroll
;           for (int c = 0; c < 4; ++c) { n[c] += sc * acc[ai][bj][m][0][c]; n[4 + c] += sc * acc[ai][bj][m][1][c]; }
;           if (aux) {
;             *(h8_t*)(x16 + off) = __builtin_convertvector(n, h8_t);
;             ss += ((n[0] * n[0] + n[1] * n[1]) + (n[2] * n[2] + n[3] * n[3])) + ((n[4] * n[4] + n[5] * n[5]) + (n[6] * n[6] + n[7] * n[7]));
;           } else {
;             *(f32x4*)(xout + off) = (f32x4){n[0], n[1], n[2], n[3]}; *(f32x4*)(xout + off + 4) = (f32x4){n[4], n[5], n[6], n[7]};
;           }
;         }
;         if (aux) { ss += __shfl_xor(ss, 16); ss += __shfl_xor(ss, 32); if (fq == 0) ssq[(unsigned)tok * 16 + u.pn * 4 + wc] = ss; }
.LBB0_690:
	s_or_b64 exec, exec, s[48:49]
	v_add_u32_e32 v96, 32, v167
	v_lshl_add_u32 v136, v96, 10, v168
	v_lshl_add_u64 v[106:107], v[136:137], 1, s[40:41]
	v_add_u32_e32 v136, 0x80, v136
	v_lshl_add_u64 v[108:109], v[136:137], 1, s[40:41]
	s_waitcnt vmcnt(10)
	v_cvt_f32_f16_e32 v110, v203
	v_cvt_f32_f16_sdwa v111, v203 dst_sel:DWORD dst_unused:UNUSED_PAD src0_sel:WORD_1
	v_cvt_f32_f16_e32 v114, v201
	v_cvt_f32_f16_sdwa v115, v201 dst_sel:DWORD dst_unused:UNUSED_PAD src0_sel:WORD_1
	v_cvt_f32_f16_e32 v116, v202
	v_cvt_f32_f16_sdwa v117, v202 dst_sel:DWORD dst_unused:UNUSED_PAD src0_sel:WORD_1
	v_cvt_f32_f16_e32 v100, v200
	v_cvt_f32_f16_sdwa v101, v200 dst_sel:DWORD dst_unused:UNUSED_PAD src0_sel:WORD_1
	v_cvt_f32_f16_e32 v98, v207
	v_cvt_f32_f16_sdwa v99, v207 dst_sel:DWORD dst_unused:UNUSED_PAD src0_sel:WORD_1
	v_cvt_f32_f16_e32 v118, v205
	v_cvt_f32_f16_sdwa v119, v205 dst_sel:DWORD dst_unused:UNUSED_PAD src0_sel:WORD_1
	v_cvt_f32_f16_e32 v120, v206
	v_cvt_f32_f16_sdwa v121, v206 dst_sel:DWORD dst_unused:UNUSED_PAD src0_sel:WORD_1
	v_cvt_f32_f16_e32 v104, v204
	v_cvt_f32_f16_sdwa v105, v204 dst_sel:DWORD dst_unused:UNUSED_PAD src0_sel:WORD_1
	v_pk_add_f32 v[92:93], v[92:93], v[100:101]
	v_pk_add_f32 v[100:101], v[88:89], v[116:117]
	v_pk_add_f32 v[94:95], v[94:95], v[114:115]
	v_pk_add_f32 v[90:91], v[90:91], v[110:111]
	v_cvt_pk_f16_f32 v88, v100, v101
	v_cvt_pk_f16_f32 v89, v90, v91
	v_pk_mul_f32 v[102:103], v[92:93], v[92:93]
	v_pk_mul_f32 v[110:111], v[94:95], v[94:95]
	v_pk_fma_f32 v[102:103], v[100:101], v[100:101], v[102:103]
	v_pk_fma_f32 v[110:111], v[90:91], v[90:91], v[110:111]
	v_pk_add_f32 v[104:105], v[84:85], v[104:105]
	v_pk_add_f32 v[114:115], v[80:81], v[120:121]
	v_pk_add_f32 v[116:117], v[86:87], v[118:119]
	v_pk_add_f32 v[80:81], v[82:83], v[98:99]
	v_pk_fma_f32 v[102:103], v[104:105], v[104:105], v[102:103]
	v_pk_fma_f32 v[110:111], v[116:117], v[116:117], v[110:111]
	v_pk_fma_f32 v[102:103], v[114:115], v[114:115], v[102:103]
	v_pk_fma_f32 v[110:111], v[80:81], v[80:81], v[110:111]
	s_waitcnt lgkmcnt(0)
	v_pk_add_f32 v[102:103], v[102:103], v[110:111]
	v_add_f32_e32 v82, v102, v103
	v_mov_b32_e32 v83, v82
	s_nop 1
	v_permlane16_swap_b32_e32 v82, v83
	v_cvt_pk_f16_f32 v85, v80, v81
	v_cvt_pk_f16_f32 v87, v94, v95
	v_cvt_pk_f16_f32 v86, v92, v93
	v_cvt_pk_f16_f32 v84, v114, v115
	s_waitcnt lgkmcnt(0)
	v_add_f32_e32 v80, v82, v83
	v_mov_b32_e32 v81, v80
	s_nop 1
	v_permlane32_swap_b32_e32 v80, v81
	v_cvt_pk_f16_f32 v83, v116, v117
	v_cvt_pk_f16_f32 v82, v104, v105
	global_store_dwordx4 v[106:107], v[86:89], off
	global_store_dwordx4 v[108:109], v[82:85], off
	s_and_saveexec_b64 s[48:49], s[4:5]
	s_cbranch_execz .LBB0_692
	v_lshl_add_u32 v136, v96, 4, s11
	s_waitcnt lgkmcnt(0)
	v_add_f32_e32 v82, v80, v81
	v_lshl_add_u64 v[80:81], v[136:137], 2, s[42:43]
	global_store_dword v[80:81], v82, off
.LBB0_692:
	s_or_b64 exec, exec, s[48:49]
	v_add_u32_e32 v80, 48, v167
	v_lshl_add_u32 v136, v80, 10, v168
	v_lshl_add_u64 v[90:91], v[136:137], 1, s[40:41]
	v_add_u32_e32 v136, 0x80, v136
	v_lshl_add_u64 v[92:93], v[136:137], 1, s[40:41]
	s_waitcnt vmcnt(10)
	v_cvt_f32_f16_e32 v94, v211
	v_cvt_f32_f16_sdwa v95, v211 dst_sel:DWORD dst_unused:UNUSED_PAD src0_sel:WORD_1
	v_cvt_f32_f16_e32 v96, v209
	v_cvt_f32_f16_sdwa v97, v209 dst_sel:DWORD dst_unused:UNUSED_PAD src0_sel:WORD_1
	v_cvt_f32_f16_e32 v98, v210
	v_cvt_f32_f16_sdwa v99, v210 dst_sel:DWORD dst_unused:UNUSED_PAD src0_sel:WORD_1
	v_cvt_f32_f16_e32 v84, v208
	v_cvt_f32_f16_sdwa v85, v208 dst_sel:DWORD dst_unused:UNUSED_PAD src0_sel:WORD_1
	v_cvt_f32_f16_e32 v82, v215
	v_cvt_f32_f16_sdwa v83, v215 dst_sel:DWORD dst_unused:UNUSED_PAD src0_sel:WORD_1
	v_cvt_f32_f16_e32 v100, v213
	v_cvt_f32_f16_sdwa v101, v213 dst_sel:DWORD dst_unused:UNUSED_PAD src0_sel:WORD_1
	v_cvt_f32_f16_e32 v102, v214
	v_cvt_f32_f16_sdwa v103, v214 dst_sel:DWORD dst_unused:UNUSED_PAD src0_sel:WORD_1
	v_cvt_f32_f16_e32 v88, v212
	v_cvt_f32_f16_sdwa v89, v212 dst_sel:DWORD dst_unused:UNUSED_PAD src0_sel:WORD_1
	v_pk_add_f32 v[76:77], v[76:77], v[84:85]
	v_pk_add_f32 v[84:85], v[72:73], v[98:99]
	v_pk_add_f32 v[78:79], v[78:79], v[96:97]
	v_pk_add_f32 v[74:75], v[74:75], v[94:95]
	v_cvt_pk_f16_f32 v72, v84, v85
	v_cvt_pk_f16_f32 v73, v74, v75
	v_pk_mul_f32 v[86:87], v[76:77], v[76:77]
	v_pk_mul_f32 v[94:95], v[78:79], v[78:79]
	v_pk_fma_f32 v[86:87], v[84:85], v[84:85], v[86:87]
	v_pk_fma_f32 v[94:95], v[74:75], v[74:75], v[94:95]
	v_pk_add_f32 v[88:89], v[68:69], v[88:89]
	v_pk_add_f32 v[96:97], v[64:65], v[102:103]
	v_pk_add_f32 v[98:99], v[70:71], v[100:101]
	v_pk_add_f32 v[64:65], v[66:67], v[82:83]
	v_pk_fma_f32 v[86:87], v[88:89], v[88:89], v[86:87]
	v_pk_fma_f32 v[94:95], v[98:99], v[98:99], v[94:95]
	v_pk_fma_f32 v[86:87], v[96:97], v[96:97], v[86:87]
	v_pk_fma_f32 v[94:95], v[64:65], v[64:65], v[94:95]
	s_waitcnt lgkmcnt(0)
	v_pk_add_f32 v[86:87], v[86:87], v[94:95]
	v_add_f32_e32 v66, v86, v87
	v_mov_b32_e32 v67, v66
	s_nop 1
	v_permlane16_swap_b32_e32 v66, v67
	v_cvt_pk_f16_f32 v69, v64, v65
	v_cvt_pk_f16_f32 v71, v78, v79
	v_cvt_pk_f16_f32 v70, v76, v77
	v_cvt_pk_f16_f32 v68, v96, v97
	s_waitcnt lgkmcnt(0)
	v_add_f32_e32 v64, v66, v67
	v_mov_b32_e32 v65, v64
	s_nop 1
	v_permlane32_swap_b32_e32 v64, v65
	v_cvt_pk_f16_f32 v67, v98, v99
	v_cvt_pk_f16_f32 v66, v88, v89
	global_store_dwordx4 v[90:91], v[70:73], off
	global_store_dwordx4 v[92:93], v[66:69], off
	s_and_saveexec_b64 s[48:49], s[4:5]
	s_cbranch_execz .LBB0_694
	v_lshl_add_u32 v136, v80, 4, s11
	s_waitcnt lgkmcnt(0)
	v_add_f32_e32 v66, v64, v65
	v_lshl_add_u64 v[64:65], v[136:137], 2, s[42:43]
	global_store_dword v[64:65], v66, off
;   __device__ __forceinline__ void operator()(const pg8::f32x4 (&acc)[2][2][4][2], const pg8::Unit& u, int wr, int wc, int fr, int fq) const {
;     ...
;         const int tok = row0 + ai * 128 + m * 16; float ss = 0.f;
; #pragma unroll
;         for (int bj = 0; bj < 2; ++bj) {
;           const unsigned off = (unsigned)tok * DM + colb + 128 * bj;
;           f8_t n = __builtin_convertvector(*(const h8_t*)(x16 + off), f8_t);
; #pragma unroll
;           for (int c = 0; c < 4; ++c) { n[c] += sc * acc[ai][bj][m][0][c]; n[4 + c] += sc * acc[ai][bj][m][1][c]; }
;           if (aux) {
;             *(h8_t*)(x16 + off) = __builtin_convertvector(n, h8_t);
;             ss += ((n[0] * n[0] + n[1] * n[1]) + (n[2] * n[2] + n[3] * n[3])) + ((n[4] * n[4] + n[5] * n[5]) + (n[6] * n[6] + n[7] * n[7]));
;           } else {
;             *(f32x4*)(xout + off) = (f32x4){n[0], n[1], n[2], n[3]}; *(f32x4*)(xout + off + 4) = (f32x4){n[4], n[5], n[6], n[7]};
;           }
;         }
;         if (aux) { ss += __shfl_xor(ss, 16); ss += __shfl_xor(ss, 32); if (fq == 0) ssq[(unsigned)tok * 16 + u.pn * 4 + wc] = ss; }
.LBB0_694:
	s_or_b64 exec, exec, s[48:49]
	v_add_u32_e32 v64, 0x80, v167
	v_lshl_add_u32 v136, v64, 10, v168
	v_lshl_add_u64 v[74:75], v[136:137], 1, s[40:41]
	v_add_u32_e32 v136, 0x80, v136
	v_lshl_add_u64 v[76:77], v[136:137], 1, s[40:41]
	s_waitcnt vmcnt(10)
	v_cvt_f32_f16_e32 v78, v219
	v_cvt_f32_f16_sdwa v79, v219 dst_sel:DWORD dst_unused:UNUSED_PAD src0_sel:WORD_1
	v_cvt_f32_f16_e32 v80, v217
	v_cvt_f32_f16_sdwa v81, v217 dst_sel:DWORD dst_unused:UNUSED_PAD src0_sel:WORD_1
	v_cvt_f32_f16_e32 v82, v218
	v_cvt_f32_f16_sdwa v83, v218 dst_sel:DWORD dst_unused:UNUSED_PAD src0_sel:WORD_1
	v_cvt_f32_f16_e32 v68, v216
	v_cvt_f32_f16_sdwa v69, v216 dst_sel:DWORD dst_unused:UNUSED_PAD src0_sel:WORD_1
	v_cvt_f32_f16_e32 v66, v223
	v_cvt_f32_f16_sdwa v67, v223 dst_sel:DWORD dst_unused:UNUSED_PAD src0_sel:WORD_1
	v_cvt_f32_f16_e32 v84, v221
	v_cvt_f32_f16_sdwa v85, v221 dst_sel:DWORD dst_unused:UNUSED_PAD src0_sel:WORD_1
	v_cvt_f32_f16_e32 v86, v222
	v_cvt_f32_f16_sdwa v87, v222 dst_sel:DWORD dst_unused:UNUSED_PAD src0_sel:WORD_1
	v_cvt_f32_f16_e32 v72, v220
	v_cvt_f32_f16_sdwa v73, v220 dst_sel:DWORD dst_unused:UNUSED_PAD src0_sel:WORD_1
	v_pk_add_f32 v[60:61], v[60:61], v[68:69]
	v_pk_add_f32 v[68:69], v[56:57], v[82:83]
	v_pk_add_f32 v[62:63], v[62:63], v[80:81]
	v_pk_add_f32 v[58:59], v[58:59], v[78:79]
	v_cvt_pk_f16_f32 v56, v68, v69
	v_cvt_pk_f16_f32 v57, v58, v59
	v_pk_mul_f32 v[70:71], v[60:61], v[60:61]
	v_pk_mul_f32 v[78:79], v[62:63], v[62:63]
	v_pk_fma_f32 v[70:71], v[68:69], v[68:69], v[70:71]
	v_pk_fma_f32 v[78:79], v[58:59], v[58:59], v[78:79]
	v_pk_add_f32 v[72:73], v[52:53], v[72:73]
	v_pk_add_f32 v[80:81], v[48:49], v[86:87]
	v_pk_add_f32 v[82:83], v[54:55], v[84:85]
	v_pk_add_f32 v[48:49], v[50:51], v[66:67]
	v_pk_fma_f32 v[70:71], v[72:73], v[72:73], v[70:71]
	v_pk_fma_f32 v[78:79], v[82:83], v[82:83], v[78:79]
	v_pk_fma_f32 v[70:71], v[80:81], v[80:81], v[70:71]
	v_pk_fma_f32 v[78:79], v[48:49], v[48:49], v[78:79]
	s_waitcnt lgkmcnt(0)
	v_pk_add_f32 v[70:71], v[70:71], v[78:79]
	v_add_f32_e32 v50, v70, v71
	v_mov_b32_e32 v51, v50
	s_nop 1
	v_permlane16_swap_b32_e32 v50, v51
	v_cvt_pk_f16_f32 v53, v48, v49
	v_cvt_pk_f16_f32 v55, v62, v63
	v_cvt_pk_f16_f32 v54, v60, v61
	v_cvt_pk_f16_f32 v52, v80, v81
	s_waitcnt lgkmcnt(0)
	v_add_f32_e32 v48, v50, v51
	v_mov_b32_e32 v49, v48
	s_nop 1
	v_permlane32_swap_b32_e32 v48, v49
	v_cvt_pk_f16_f32 v51, v82, v83
	v_cvt_pk_f16_f32 v50, v72, v73
	global_store_dwordx4 v[74:75], v[54:57], off
	global_store_dwordx4 v[76:77], v[50:53], off
	s_and_saveexec_b64 s[48:49], s[4:5]
	s_cbranch_execz .LBB0_696
	v_lshl_add_u32 v136, v64, 4, s11
	s_waitcnt lgkmcnt(0)
	v_add_f32_e32 v50, v48, v49
	v_lshl_add_u64 v[48:49], v[136:137], 2, s[42:43]
	global_store_dword v[48:49], v50, off
.LBB0_696:
	s_or_b64 exec, exec, s[48:49]
	v_add_u32_e32 v48, 0x90, v167
	v_lshl_add_u32 v136, v48, 10, v168
	v_lshl_add_u64 v[58:59], v[136:137], 1, s[40:41]
	v_add_u32_e32 v136, 0x80, v136
	v_lshl_add_u64 v[60:61], v[136:137], 1, s[40:41]
	s_waitcnt vmcnt(10)
	v_cvt_f32_f16_e32 v62, v231
	v_cvt_f32_f16_sdwa v63, v231 dst_sel:DWORD dst_unused:UNUSED_PAD src0_sel:WORD_1
	v_cvt_f32_f16_e32 v64, v229
	v_cvt_f32_f16_sdwa v65, v229 dst_sel:DWORD dst_unused:UNUSED_PAD src0_sel:WORD_1
	v_cvt_f32_f16_e32 v66, v230
	v_cvt_f32_f16_sdwa v67, v230 dst_sel:DWORD dst_unused:UNUSED_PAD src0_sel:WORD_1
	v_cvt_f32_f16_e32 v52, v228
	v_cvt_f32_f16_sdwa v53, v228 dst_sel:DWORD dst_unused:UNUSED_PAD src0_sel:WORD_1
	v_cvt_f32_f16_e32 v50, v247
	v_cvt_f32_f16_sdwa v51, v247 dst_sel:DWORD dst_unused:UNUSED_PAD src0_sel:WORD_1
	v_cvt_f32_f16_e32 v68, v245
	v_cvt_f32_f16_sdwa v69, v245 dst_sel:DWORD dst_unused:UNUSED_PAD src0_sel:WORD_1
	v_cvt_f32_f16_e32 v70, v246
	v_cvt_f32_f16_sdwa v71, v246 dst_sel:DWORD dst_unused:UNUSED_PAD src0_sel:WORD_1
	v_cvt_f32_f16_e32 v56, v244
	v_cvt_f32_f16_sdwa v57, v244 dst_sel:DWORD dst_unused:UNUSED_PAD src0_sel:WORD_1
	v_pk_add_f32 v[44:45], v[44:45], v[52:53]
	v_pk_add_f32 v[52:53], v[40:41], v[66:67]
	v_pk_add_f32 v[46:47], v[46:47], v[64:65]
	v_pk_add_f32 v[42:43], v[42:43], v[62:63]
	v_cvt_pk_f16_f32 v40, v52, v53
	v_cvt_pk_f16_f32 v41, v42, v43
	v_pk_mul_f32 v[54:55], v[44:45], v[44:45]
	v_pk_mul_f32 v[62:63], v[46:47], v[46:47]
	v_pk_fma_f32 v[54:55], v[52:53], v[52:53], v[54:55]
	v_pk_fma_f32 v[62:63], v[42:43], v[42:43], v[62:63]
	v_pk_add_f32 v[56:57], v[36:37], v[56:57]
	v_pk_add_f32 v[64:65], v[32:33], v[70:71]
	v_pk_add_f32 v[66:67], v[38:39], v[68:69]
	v_pk_add_f32 v[32:33], v[34:35], v[50:51]
	v_pk_fma_f32 v[54:55], v[56:57], v[56:57], v[54:55]
	v_pk_fma_f32 v[62:63], v[66:67], v[66:67], v[62:63]
	v_pk_fma_f32 v[54:55], v[64:65], v[64:65], v[54:55]
	v_pk_fma_f32 v[62:63], v[32:33], v[32:33], v[62:63]
	s_waitcnt lgkmcnt(0)
	v_pk_add_f32 v[54:55], v[54:55], v[62:63]
	v_add_f32_e32 v34, v54, v55
	v_mov_b32_e32 v35, v34
	s_nop 1
	v_permlane16_swap_b32_e32 v34, v35
	v_cvt_pk_f16_f32 v37, v32, v33
	v_cvt_pk_f16_f32 v39, v46, v47
	v_cvt_pk_f16_f32 v38, v44, v45
	v_cvt_pk_f16_f32 v36, v64, v65
	s_waitcnt lgkmcnt(0)
	v_add_f32_e32 v32, v34, v35
	v_mov_b32_e32 v33, v32
	s_nop 1
	v_permlane32_swap_b32_e32 v32, v33
	v_cvt_pk_f16_f32 v35, v66, v67
	v_cvt_pk_f16_f32 v34, v56, v57
	global_store_dwordx4 v[58:59], v[38:41], off
	global_store_dwordx4 v[60:61], v[34:37], off
	s_and_saveexec_b64 s[48:49], s[4:5]
	s_cbranch_execz .LBB0_698
	v_lshl_add_u32 v136, v48, 4, s11
	s_waitcnt lgkmcnt(0)
	v_add_f32_e32 v34, v32, v33
	v_lshl_add_u64 v[32:33], v[136:137], 2, s[42:43]
	global_store_dword v[32:33], v34, off
;   __device__ __forceinline__ void operator()(const pg8::f32x4 (&acc)[2][2][4][2], const pg8::Unit& u, int wr, int wc, int fr, int fq) const {
;     ...
;         const int tok = row0 + ai * 128 + m * 16; float ss = 0.f;
; #pragma unroll
;         for (int bj = 0; bj < 2; ++bj) {
;           const unsigned off = (unsigned)tok * DM + colb + 128 * bj;
;           f8_t n = __builtin_convertvector(*(const h8_t*)(x16 + off), f8_t);
; #pragma unroll
;           for (int c = 0; c < 4; ++c) { n[c] += sc * acc[ai][bj][m][0][c]; n[4 + c] += sc * acc[ai][bj][m][1][c]; }
;           if (aux) {
;             *(h8_t*)(x16 + off) = __builtin_convertvector(n, h8_t);
;             ss += ((n[0] * n[0] + n[1] * n[1]) + (n[2] * n[2] + n[3] * n[3])) + ((n[4] * n[4] + n[5] * n[5]) + (n[6] * n[6] + n[7] * n[7]));
;           } else {
;             *(f32x4*)(xout + off) = (f32x4){n[0], n[1], n[2], n[3]}; *(f32x4*)(xout + off + 4) = (f32x4){n[4], n[5], n[6], n[7]};
;           }
;         }
;         if (aux) { ss += __shfl_xor(ss, 16); ss += __shfl_xor(ss, 32); if (fq == 0) ssq[(unsigned)tok * 16 + u.pn * 4 + wc] = ss; }
.LBB0_698:
	s_or_b64 exec, exec, s[48:49]
	v_add_u32_e32 v32, 0xa0, v167
	v_lshl_add_u32 v136, v32, 10, v168
	v_lshl_add_u64 v[42:43], v[136:137], 1, s[40:41]
	v_add_u32_e32 v136, 0x80, v136
	global_load_dwordx4 v[34:37], v[42:43], off
	v_lshl_add_u64 v[44:45], v[136:137], 1, s[40:41]
	global_load_dwordx4 v[38:41], v[44:45], off
	s_waitcnt vmcnt(1)
	v_cvt_f32_f16_e32 v46, v37
	v_cvt_f32_f16_sdwa v47, v37 dst_sel:DWORD dst_unused:UNUSED_PAD src0_sel:WORD_1
	v_cvt_f32_f16_e32 v48, v35
	v_cvt_f32_f16_sdwa v49, v35 dst_sel:DWORD dst_unused:UNUSED_PAD src0_sel:WORD_1
	v_cvt_f32_f16_e32 v50, v36
	v_cvt_f32_f16_sdwa v51, v36 dst_sel:DWORD dst_unused:UNUSED_PAD src0_sel:WORD_1
	v_cvt_f32_f16_e32 v36, v34
	v_cvt_f32_f16_sdwa v37, v34 dst_sel:DWORD dst_unused:UNUSED_PAD src0_sel:WORD_1
	s_waitcnt vmcnt(0)
	v_cvt_f32_f16_e32 v34, v41
	v_cvt_f32_f16_sdwa v35, v41 dst_sel:DWORD dst_unused:UNUSED_PAD src0_sel:WORD_1
	v_cvt_f32_f16_e32 v52, v39
	v_cvt_f32_f16_sdwa v53, v39 dst_sel:DWORD dst_unused:UNUSED_PAD src0_sel:WORD_1
	v_cvt_f32_f16_e32 v54, v40
	v_cvt_f32_f16_sdwa v55, v40 dst_sel:DWORD dst_unused:UNUSED_PAD src0_sel:WORD_1
	v_cvt_f32_f16_e32 v40, v38
	v_cvt_f32_f16_sdwa v41, v38 dst_sel:DWORD dst_unused:UNUSED_PAD src0_sel:WORD_1
	v_pk_add_f32 v[28:29], v[28:29], v[36:37]
	v_pk_add_f32 v[36:37], v[24:25], v[50:51]
	v_pk_add_f32 v[30:31], v[30:31], v[48:49]
	v_pk_add_f32 v[26:27], v[26:27], v[46:47]
	v_cvt_pk_f16_f32 v24, v36, v37
	v_cvt_pk_f16_f32 v25, v26, v27
	v_pk_mul_f32 v[38:39], v[28:29], v[28:29]
	v_pk_mul_f32 v[46:47], v[30:31], v[30:31]
	v_pk_fma_f32 v[38:39], v[36:37], v[36:37], v[38:39]
	v_pk_fma_f32 v[46:47], v[26:27], v[26:27], v[46:47]
	v_pk_add_f32 v[40:41], v[20:21], v[40:41]
	v_pk_add_f32 v[48:49], v[16:17], v[54:55]
	v_pk_add_f32 v[50:51], v[22:23], v[52:53]
	v_pk_add_f32 v[16:17], v[18:19], v[34:35]
	v_pk_fma_f32 v[38:39], v[40:41], v[40:41], v[38:39]
	v_pk_fma_f32 v[46:47], v[50:51], v[50:51], v[46:47]
	v_pk_fma_f32 v[38:39], v[48:49], v[48:49], v[38:39]
	v_pk_fma_f32 v[46:47], v[16:17], v[16:17], v[46:47]
	s_waitcnt lgkmcnt(0)
	v_pk_add_f32 v[38:39], v[38:39], v[46:47]
	v_add_f32_e32 v18, v38, v39
	v_mov_b32_e32 v19, v18
	s_nop 1
	v_permlane16_swap_b32_e32 v18, v19
	v_cvt_pk_f16_f32 v21, v16, v17
	v_cvt_pk_f16_f32 v23, v30, v31
	v_cvt_pk_f16_f32 v22, v28, v29
	v_cvt_pk_f16_f32 v20, v48, v49
	s_waitcnt lgkmcnt(0)
	v_add_f32_e32 v16, v18, v19
	v_mov_b32_e32 v17, v16
	s_nop 1
	v_permlane32_swap_b32_e32 v16, v17
	v_cvt_pk_f16_f32 v19, v50, v51
	v_cvt_pk_f16_f32 v18, v40, v41
	global_store_dwordx4 v[42:43], v[22:25], off
	global_store_dwordx4 v[44:45], v[18:21], off
	s_and_saveexec_b64 s[48:49], s[4:5]
	s_cbranch_execz .LBB0_700
	v_lshl_add_u32 v136, v32, 4, s11
	s_waitcnt lgkmcnt(0)
	v_add_f32_e32 v18, v16, v17
	v_lshl_add_u64 v[16:17], v[136:137], 2, s[42:43]
	global_store_dword v[16:17], v18, off
.LBB0_700:
	s_or_b64 exec, exec, s[48:49]
	v_add_u32_e32 v16, 0xb0, v167
	v_lshl_add_u32 v136, v16, 10, v168
	v_lshl_add_u64 v[26:27], v[136:137], 1, s[40:41]
	v_add_u32_e32 v136, 0x80, v136
	global_load_dwordx4 v[18:21], v[26:27], off
	v_lshl_add_u64 v[28:29], v[136:137], 1, s[40:41]
	global_load_dwordx4 v[22:25], v[28:29], off
	s_waitcnt vmcnt(1)
	v_cvt_f32_f16_e32 v30, v21
	v_cvt_f32_f16_sdwa v31, v21 dst_sel:DWORD dst_unused:UNUSED_PAD src0_sel:WORD_1
	v_cvt_f32_f16_e32 v32, v19
	v_cvt_f32_f16_sdwa v33, v19 dst_sel:DWORD dst_unused:UNUSED_PAD src0_sel:WORD_1
	v_cvt_f32_f16_e32 v34, v20
	v_cvt_f32_f16_sdwa v35, v20 dst_sel:DWORD dst_unused:UNUSED_PAD src0_sel:WORD_1
	v_cvt_f32_f16_e32 v20, v18
	v_cvt_f32_f16_sdwa v21, v18 dst_sel:DWORD dst_unused:UNUSED_PAD src0_sel:WORD_1
	s_waitcnt vmcnt(0)
	v_cvt_f32_f16_e32 v18, v25
	v_cvt_f32_f16_sdwa v19, v25 dst_sel:DWORD dst_unused:UNUSED_PAD src0_sel:WORD_1
	v_cvt_f32_f16_e32 v36, v23
	v_cvt_f32_f16_sdwa v37, v23 dst_sel:DWORD dst_unused:UNUSED_PAD src0_sel:WORD_1
	v_cvt_f32_f16_e32 v38, v24
	v_cvt_f32_f16_sdwa v39, v24 dst_sel:DWORD dst_unused:UNUSED_PAD src0_sel:WORD_1
	v_cvt_f32_f16_e32 v24, v22
	v_cvt_f32_f16_sdwa v25, v22 dst_sel:DWORD dst_unused:UNUSED_PAD src0_sel:WORD_1
	v_pk_add_f32 v[12:13], v[12:13], v[20:21]
	v_pk_add_f32 v[20:21], v[8:9], v[34:35]
	v_pk_add_f32 v[14:15], v[14:15], v[32:33]
	v_pk_add_f32 v[10:11], v[10:11], v[30:31]
	v_cvt_pk_f16_f32 v8, v20, v21
	v_cvt_pk_f16_f32 v9, v10, v11
	v_pk_mul_f32 v[22:23], v[12:13], v[12:13]
	v_pk_mul_f32 v[30:31], v[14:15], v[14:15]
	v_pk_fma_f32 v[22:23], v[20:21], v[20:21], v[22:23]
	v_pk_fma_f32 v[30:31], v[10:11], v[10:11], v[30:31]
	v_pk_add_f32 v[24:25], v[4:5], v[24:25]
	v_pk_add_f32 v[32:33], v[0:1], v[38:39]
	v_pk_add_f32 v[34:35], v[6:7], v[36:37]
	v_pk_add_f32 v[0:1], v[2:3], v[18:19]
	v_pk_fma_f32 v[22:23], v[24:25], v[24:25], v[22:23]
	v_pk_fma_f32 v[30:31], v[34:35], v[34:35], v[30:31]
	v_pk_fma_f32 v[22:23], v[32:33], v[32:33], v[22:23]
	v_pk_fma_f32 v[30:31], v[0:1], v[0:1], v[30:31]
	s_waitcnt lgkmcnt(0)
	v_pk_add_f32 v[22:23], v[22:23], v[30:31]
	v_add_f32_e32 v2, v22, v23
	v_mov_b32_e32 v3, v2
	s_nop 1
	v_permlane16_swap_b32_e32 v2, v3
	v_cvt_pk_f16_f32 v5, v0, v1
	v_cvt_pk_f16_f32 v7, v14, v15
	v_cvt_pk_f16_f32 v6, v12, v13
	v_cvt_pk_f16_f32 v4, v32, v33
	s_waitcnt lgkmcnt(0)
	v_add_f32_e32 v0, v2, v3
	v_mov_b32_e32 v1, v0
	s_nop 1
	v_permlane32_swap_b32_e32 v0, v1
	v_cvt_pk_f16_f32 v3, v34, v35
	v_cvt_pk_f16_f32 v2, v24, v25
	global_store_dwordx4 v[26:27], v[6:9], off
	global_store_dwordx4 v[28:29], v[2:5], off
	s_and_saveexec_b64 s[48:49], s[4:5]
	s_cbranch_execz .LBB0_677
	v_lshl_add_u32 v136, v16, 4, s11
	s_waitcnt lgkmcnt(0)
	v_add_f32_e32 v2, v0, v1
	v_lshl_add_u64 v[0:1], v[136:137], 2, s[42:43]
	global_store_dword v[0:1], v2, off
	s_branch .LBB0_677

; #define PG8_STAGE(bufoff, gbase, voff) do { _Pragma("unroll") for (int _i = 0; _i < 2; ++_i) \
;         __builtin_amdgcn_global_load_lds((const unsigned*)((const char*)(gbase) + (voff)[_i]), (PG8_LAS unsigned*)(lds + (bufoff) + ldsw + _i * 8192), 16, 0, 0); } while (0)
; #define PG8_LDA(dst, b, h) do { _Pragma("unroll") for (int m = 0; m < 4; ++m) _Pragma("unroll") for (int k = 0; k < 2; ++k) dst[m][k] = *(const PG8_LAS bf16x8*)(lds + PG8_SA(b, h) + aoff + m * 2048 + k * 1024); } while (0)
; #define PG8_LDB(dst, b, h) do { _Pragma("unroll") for (int n = 0; n < 2; ++n) _Pragma("unroll") for (int k = 0; k < 2; ++k) dst[n][k] = *(const PG8_LAS bf16x8*)(lds + PG8_SB(b, h) + boff + n * 2048 + k * 1024); } while (0)
; #define PG8_WAIT_V(n) asm volatile("s_waitcnt vmcnt(" #n ")" ::: "memory")
; #define PG8_WAIT_L(n) asm volatile("s_waitcnt lgkmcnt(" #n ")" ::: "memory")
; #define PG8_BAR __builtin_amdgcn_s_barrier()
; #define PG8_SCHED __builtin_amdgcn_sched_barrier(0)
; template <class Epi, class Sched, bool ALIGN_EPI = false, bool SP2 = false, bool F16 = false, bool TOKPERM = false>
; __device__ __forceinline__ void gemm_phase(PG8_LAS unsigned char* lds, const Gemm g, const Sched& S, const Epi& E, int wv) {
;     ...
;         const bool has_next = S.next(ui + 1, nxt);
;         const char* nA = has_next ? (const char*)g.A + (size_t)nxt.pm * tstep : cA; const char* nB = has_next ? (const char*)g.Bt + (size_t)nxt.pn * tstep : cB;
;         for (int t = 0; t < nt; t += 2) {
;             const bool last = (t == nt - 2);
;             const char* a1 = cA + (size_t)(t + 1) * kstep;
;             const char* a2 = last ? nA : cA + (size_t)(t + 2) * kstep; const char* b2 = last ? nB : cB + (size_t)(t + 2) * kstep;
;             const char* a3 = a2 + kstep; const char* b3 = b2 + kstep;
;             if (last && has_next) S.a_ready(nxt);
;             if constexpr (SP2) {
;             PG8_LDB(B0, 0, 0); PG8_LDB(B1, 0, 1); PG8_SCHED; PG8_LDA(At, 0, 0); PG8_STAGE(PG8_SA(1, 1), a1 + hstep, voffA);
;             PG8_WAIT_V(8); PG8_WAIT_L(0); PG8_BAR; PG8_MMA(0, 0, At, B0); PG8_MMA(0, 1, At, B1); PG8_BAR; PG8_SCHED;
;             PG8_LDA(At, 0, 1); PG8_STAGE(PG8_SB(0, 0), b2, voffB); PG8_STAGE(PG8_SB(0, 1), b2 + hstep, voffB); PG8_STAGE(PG8_SA(0, 0), a2, voffA);
;             PG8_WAIT_V(8); PG8_WAIT_L(0); PG8_BAR; PG8_MMA(1, 0, At, B0); PG8_MMA(1, 1, At, B1); PG8_BAR; PG8_SCHED;
.LBB0_867:
	ds_read_b128 v[166:169], v149
	ds_read_b128 v[170:173], v150
	ds_read_b128 v[174:177], v151
	ds_read_b128 v[178:181], v152
	ds_read_b128 v[182:185], v153
	ds_read_b128 v[186:189], v154
	ds_read_b128 v[190:193], v155
	ds_read_b128 v[194:197], v156
	s_add_u32 s18, s16, 0x100
	s_addc_u32 s19, s17, 0
	s_cmp_eq_u32 s67, 40
	s_cselect_b32 s23, s11, s19
	s_cselect_b32 s22, s10, s18
	s_cselect_b32 s21, s13, s66
	s_cselect_b32 s20, s12, s65
	s_mov_b32 m0, s59
	v_lshl_add_u64 v[232:233], s[16:17], 0, v[138:139]
	ds_read_b128 v[198:201], v147
	ds_read_b128 v[202:205], v147 offset:1024
	ds_read_b128 v[206:209], v147 offset:2048
	ds_read_b128 v[210:213], v147 offset:3072
	ds_read_b128 v[214:217], v147 offset:4096
	ds_read_b128 v[218:221], v147 offset:5120
	ds_read_b128 v[222:225], v147 offset:6144
	ds_read_b128 v[228:231], v147 offset:7168
	global_load_lds_dwordx4 v[232:233], off
	v_lshl_add_u64 v[232:233], s[16:17], 0, v[140:141]
	s_mov_b32 m0, s60
	s_nop 0
	global_load_lds_dwordx4 v[232:233], off
	s_waitcnt vmcnt(8)
	s_waitcnt lgkmcnt(0)
	s_barrier
	s_setprio 1
	s_waitcnt lgkmcnt(0)
	v_mfma_f32_16x16x32_bf16 v[124:127], v[166:169], v[198:201], v[124:127]
	v_mfma_f32_16x16x32_bf16 v[120:123], v[174:177], v[198:201], v[120:123]
	v_mfma_f32_16x16x32_bf16 v[108:111], v[166:169], v[206:209], v[108:111]
	v_mfma_f32_16x16x32_bf16 v[104:107], v[174:177], v[206:209], v[104:107]
	v_mfma_f32_16x16x32_bf16 v[92:95], v[166:169], v[214:217], v[92:95]
	v_mfma_f32_16x16x32_bf16 v[88:91], v[174:177], v[214:217], v[88:91]
	v_mfma_f32_16x16x32_bf16 v[76:79], v[166:169], v[222:225], v[76:79]
	v_mfma_f32_16x16x32_bf16 v[72:75], v[174:177], v[222:225], v[72:75]
	v_mfma_f32_16x16x32_bf16 v[124:127], v[170:173], v[202:205], v[124:127]
	v_mfma_f32_16x16x32_bf16 v[120:123], v[178:181], v[202:205], v[120:123]
	v_mfma_f32_16x16x32_bf16 v[108:111], v[170:173], v[210:213], v[108:111]
	v_mfma_f32_16x16x32_bf16 v[104:107], v[178:181], v[210:213], v[104:107]
	v_mfma_f32_16x16x32_bf16 v[92:95], v[170:173], v[218:221], v[92:95]
	v_mfma_f32_16x16x32_bf16 v[88:91], v[178:181], v[218:221], v[88:91]
	v_mfma_f32_16x16x32_bf16 v[76:79], v[170:173], v[228:231], v[76:79]
	v_mfma_f32_16x16x32_bf16 v[72:75], v[178:181], v[228:231], v[72:75]
	s_setprio 0
	s_setprio 1
	v_mfma_f32_16x16x32_bf16 v[116:119], v[182:185], v[198:201], v[116:119]
	v_mfma_f32_16x16x32_bf16 v[112:115], v[190:193], v[198:201], v[112:115]
	v_mfma_f32_16x16x32_bf16 v[100:103], v[182:185], v[206:209], v[100:103]
	v_mfma_f32_16x16x32_bf16 v[96:99], v[190:193], v[206:209], v[96:99]
	v_mfma_f32_16x16x32_bf16 v[84:87], v[182:185], v[214:217], v[84:87]
	v_mfma_f32_16x16x32_bf16 v[80:83], v[190:193], v[214:217], v[80:83]
	v_mfma_f32_16x16x32_bf16 v[68:71], v[182:185], v[222:225], v[68:71]
	v_mfma_f32_16x16x32_bf16 v[64:67], v[190:193], v[222:225], v[64:67]
	v_mfma_f32_16x16x32_bf16 v[116:119], v[186:189], v[202:205], v[116:119]
	v_mfma_f32_16x16x32_bf16 v[112:115], v[194:197], v[202:205], v[112:115]
	v_mfma_f32_16x16x32_bf16 v[100:103], v[186:189], v[210:213], v[100:103]
	v_mfma_f32_16x16x32_bf16 v[96:99], v[194:197], v[210:213], v[96:99]
	v_mfma_f32_16x16x32_bf16 v[84:87], v[186:189], v[218:221], v[84:87]
	v_mfma_f32_16x16x32_bf16 v[80:83], v[194:197], v[218:221], v[80:83]
	v_mfma_f32_16x16x32_bf16 v[68:71], v[186:189], v[228:231], v[68:71]
	v_mfma_f32_16x16x32_bf16 v[64:67], v[194:197], v[228:231], v[64:67]
	s_setprio 0
	s_barrier
	s_mov_b32 m0, s4
	v_lshl_add_u64 v[232:233], s[20:21], 0, v[130:131]
	s_add_u32 s16, s20, 0xb0000
	ds_read_b128 v[198:201], v147 offset:16384
	ds_read_b128 v[202:205], v147 offset:17408
	ds_read_b128 v[206:209], v147 offset:18432
	ds_read_b128 v[210:213], v147 offset:19456
	ds_read_b128 v[214:217], v147 offset:20480
	ds_read_b128 v[218:221], v147 offset:21504
	ds_read_b128 v[222:225], v147 offset:22528
	ds_read_b128 v[228:231], v147 offset:23552
	global_load_lds_dwordx4 v[232:233], off
	v_lshl_add_u64 v[234:235], s[20:21], 0, v[134:135]
	s_mov_b32 m0, s5
	s_addc_u32 s17, s21, 0
	global_load_lds_dwordx4 v[234:235], off
	v_lshl_add_u64 v[236:237], s[16:17], 0, v[130:131]
	s_mov_b32 m0, s33
	v_lshl_add_u64 v[238:239], s[22:23], 0, v[132:133]
	global_load_lds_dwordx4 v[236:237], off
	v_lshl_add_u64 v[236:237], s[16:17], 0, v[134:135]
	s_mov_b32 m0, s36
	s_nop 0
	global_load_lds_dwordx4 v[236:237], off
	v_lshl_add_u64 v[236:237], s[22:23], 0, v[128:129]
	s_mov_b32 m0, s3
	s_nop 0
	global_load_lds_dwordx4 v[236:237], off
	s_mov_b32 m0, s37
	s_nop 0
	global_load_lds_dwordx4 v[238:239], off
	s_waitcnt vmcnt(8)
	s_waitcnt lgkmcnt(0)
	s_barrier
; #define PG8_STAGE(bufoff, gbase, voff) do { _Pragma("unroll") for (int _i = 0; _i < 2; ++_i) \
;         __builtin_amdgcn_global_load_lds((const unsigned*)((const char*)(gbase) + (voff)[_i]), (PG8_LAS unsigned*)(lds + (bufoff) + ldsw + _i * 8192), 16, 0, 0); } while (0)
; #define PG8_LDA(dst, b, h) do { _Pragma("unroll") for (int m = 0; m < 4; ++m) _Pragma("unroll") for (int k = 0; k < 2; ++k) dst[m][k] = *(const PG8_LAS bf16x8*)(lds + PG8_SA(b, h) + aoff + m * 2048 + k * 1024); } while (0)
; #define PG8_LDB(dst, b, h) do { _Pragma("unroll") for (int n = 0; n < 2; ++n) _Pragma("unroll") for (int k = 0; k < 2; ++k) dst[n][k] = *(const PG8_LAS bf16x8*)(lds + PG8_SB(b, h) + boff + n * 2048 + k * 1024); } while (0)
; #define PG8_MMA(ai, bj, At, Bt) do { __builtin_amdgcn_s_setprio(1); _Pragma("unroll") for (int m = 0; m < 4; ++m) _Pragma("unroll") for (int n = 0; n < 2; ++n) _Pragma("unroll") for (int k = 0; k < 2; ++k) \
;         acc[ai][bj][m][n] = mma16<F16>(Bt[n][k], At[m][k], acc[ai][bj][m][n]); __builtin_amdgcn_s_setprio(0); } while (0)
; #define PG8_WAIT_V(n) asm volatile("s_waitcnt vmcnt(" #n ")" ::: "memory")
; #define PG8_WAIT_L(n) asm volatile("s_waitcnt lgkmcnt(" #n ")" ::: "memory")
; #define PG8_BAR __builtin_amdgcn_s_barrier()
; #define PG8_SCHED __builtin_amdgcn_sched_barrier(0)
; template <class Epi, class Sched, bool ALIGN_EPI = false, bool SP2 = false, bool F16 = false, bool TOKPERM = false>
; __device__ __forceinline__ void gemm_phase(PG8_LAS unsigned char* lds, const Gemm g, const Sched& S, const Epi& E, int wv) {
;     ...
;             PG8_WAIT_V(8); PG8_WAIT_L(0); PG8_BAR; PG8_MMA(1, 0, At, B0); PG8_MMA(1, 1, At, B1); PG8_BAR; PG8_SCHED;
;             PG8_LDB(B0, 1, 0); PG8_LDB(B1, 1, 1); PG8_SCHED; PG8_LDA(At, 1, 0); PG8_STAGE(PG8_SA(0, 1), a2 + hstep, voffA);
;             PG8_WAIT_V(8); PG8_WAIT_L(0); PG8_BAR; PG8_MMA(0, 0, At, B0); PG8_MMA(0, 1, At, B1); PG8_BAR; PG8_SCHED;
	s_setprio 1
	s_waitcnt lgkmcnt(0)
	v_mfma_f32_16x16x32_bf16 v[60:63], v[166:169], v[198:201], v[60:63]
	v_mfma_f32_16x16x32_bf16 v[56:59], v[174:177], v[198:201], v[56:59]
	v_mfma_f32_16x16x32_bf16 v[44:47], v[166:169], v[206:209], v[44:47]
	v_mfma_f32_16x16x32_bf16 v[40:43], v[174:177], v[206:209], v[40:43]
	v_mfma_f32_16x16x32_bf16 v[28:31], v[166:169], v[214:217], v[28:31]
	v_mfma_f32_16x16x32_bf16 v[24:27], v[174:177], v[214:217], v[24:27]
	v_mfma_f32_16x16x32_bf16 v[12:15], v[166:169], v[222:225], v[12:15]
	v_mfma_f32_16x16x32_bf16 v[8:11], v[174:177], v[222:225], v[8:11]
	v_mfma_f32_16x16x32_bf16 v[60:63], v[170:173], v[202:205], v[60:63]
	v_mfma_f32_16x16x32_bf16 v[56:59], v[178:181], v[202:205], v[56:59]
	v_mfma_f32_16x16x32_bf16 v[44:47], v[170:173], v[210:213], v[44:47]
	v_mfma_f32_16x16x32_bf16 v[40:43], v[178:181], v[210:213], v[40:43]
	v_mfma_f32_16x16x32_bf16 v[28:31], v[170:173], v[218:221], v[28:31]
	v_mfma_f32_16x16x32_bf16 v[24:27], v[178:181], v[218:221], v[24:27]
	v_mfma_f32_16x16x32_bf16 v[12:15], v[170:173], v[228:231], v[12:15]
	v_mfma_f32_16x16x32_bf16 v[8:11], v[178:181], v[228:231], v[8:11]
	s_setprio 0
	s_setprio 1
	v_mfma_f32_16x16x32_bf16 v[52:55], v[182:185], v[198:201], v[52:55]
	v_mfma_f32_16x16x32_bf16 v[48:51], v[190:193], v[198:201], v[48:51]
	v_mfma_f32_16x16x32_bf16 v[36:39], v[182:185], v[206:209], v[36:39]
	v_mfma_f32_16x16x32_bf16 v[32:35], v[190:193], v[206:209], v[32:35]
	v_mfma_f32_16x16x32_bf16 v[20:23], v[182:185], v[214:217], v[20:23]
	v_mfma_f32_16x16x32_bf16 v[16:19], v[190:193], v[214:217], v[16:19]
	v_mfma_f32_16x16x32_bf16 v[4:7], v[182:185], v[222:225], v[4:7]
	v_mfma_f32_16x16x32_bf16 v[0:3], v[190:193], v[222:225], v[0:3]
	v_mfma_f32_16x16x32_bf16 v[52:55], v[186:189], v[202:205], v[52:55]
	v_mfma_f32_16x16x32_bf16 v[48:51], v[194:197], v[202:205], v[48:51]
	v_mfma_f32_16x16x32_bf16 v[36:39], v[186:189], v[210:213], v[36:39]
	v_mfma_f32_16x16x32_bf16 v[32:35], v[194:197], v[210:213], v[32:35]
	v_mfma_f32_16x16x32_bf16 v[20:23], v[186:189], v[218:221], v[20:23]
	v_mfma_f32_16x16x32_bf16 v[16:19], v[194:197], v[218:221], v[16:19]
	v_mfma_f32_16x16x32_bf16 v[4:7], v[186:189], v[228:231], v[4:7]
	v_mfma_f32_16x16x32_bf16 v[0:3], v[194:197], v[228:231], v[0:3]
	s_setprio 0
	s_barrier
	ds_read_b128 v[166:169], v157
	ds_read_b128 v[170:173], v158
	ds_read_b128 v[174:177], v159
	ds_read_b128 v[178:181], v160
	ds_read_b128 v[182:185], v161
	ds_read_b128 v[186:189], v162
	ds_read_b128 v[190:193], v163
	ds_read_b128 v[194:197], v164
	s_add_u32 s16, s22, 0xb0000
	s_addc_u32 s17, s23, 0
	s_mov_b32 m0, s44
	v_lshl_add_u64 v[240:241], s[16:17], 0, v[128:129]
	ds_read_b128 v[198:201], v147 offset:32768
	ds_read_b128 v[202:205], v147 offset:33792
	ds_read_b128 v[206:209], v147 offset:34816
	ds_read_b128 v[210:213], v147 offset:35840
	ds_read_b128 v[214:217], v147 offset:36864
	ds_read_b128 v[218:221], v147 offset:37888
	ds_read_b128 v[222:225], v147 offset:38912
	ds_read_b128 v[228:231], v147 offset:39936
	global_load_lds_dwordx4 v[240:241], off
	v_lshl_add_u64 v[240:241], s[16:17], 0, v[132:133]
	s_mov_b32 m0, s45
	s_nop 0
	global_load_lds_dwordx4 v[240:241], off
	s_waitcnt vmcnt(8)
	s_waitcnt lgkmcnt(0)
	s_barrier
	s_setprio 1
	s_waitcnt lgkmcnt(0)
	v_mfma_f32_16x16x32_bf16 v[124:127], v[166:169], v[198:201], v[124:127]
	v_mfma_f32_16x16x32_bf16 v[120:123], v[174:177], v[198:201], v[120:123]
	v_mfma_f32_16x16x32_bf16 v[108:111], v[166:169], v[206:209], v[108:111]
	v_mfma_f32_16x16x32_bf16 v[104:107], v[174:177], v[206:209], v[104:107]
	v_mfma_f32_16x16x32_bf16 v[92:95], v[166:169], v[214:217], v[92:95]
	v_mfma_f32_16x16x32_bf16 v[88:91], v[174:177], v[214:217], v[88:91]
	v_mfma_f32_16x16x32_bf16 v[76:79], v[166:169], v[222:225], v[76:79]
	v_mfma_f32_16x16x32_bf16 v[72:75], v[174:177], v[222:225], v[72:75]
	v_mfma_f32_16x16x32_bf16 v[124:127], v[170:173], v[202:205], v[124:127]
	v_mfma_f32_16x16x32_bf16 v[120:123], v[178:181], v[202:205], v[120:123]
	v_mfma_f32_16x16x32_bf16 v[108:111], v[170:173], v[210:213], v[108:111]
	v_mfma_f32_16x16x32_bf16 v[104:107], v[178:181], v[210:213], v[104:107]
	v_mfma_f32_16x16x32_bf16 v[92:95], v[170:173], v[218:221], v[92:95]
	v_mfma_f32_16x16x32_bf16 v[88:91], v[178:181], v[218:221], v[88:91]
	v_mfma_f32_16x16x32_bf16 v[76:79], v[170:173], v[228:231], v[76:79]
	v_mfma_f32_16x16x32_bf16 v[72:75], v[178:181], v[228:231], v[72:75]
	s_setprio 0
	s_setprio 1
	v_mfma_f32_16x16x32_bf16 v[116:119], v[182:185], v[198:201], v[116:119]
	v_mfma_f32_16x16x32_bf16 v[112:115], v[190:193], v[198:201], v[112:115]
	v_mfma_f32_16x16x32_bf16 v[100:103], v[182:185], v[206:209], v[100:103]
	v_mfma_f32_16x16x32_bf16 v[96:99], v[190:193], v[206:209], v[96:99]
	v_mfma_f32_16x16x32_bf16 v[84:87], v[182:185], v[214:217], v[84:87]
	v_mfma_f32_16x16x32_bf16 v[80:83], v[190:193], v[214:217], v[80:83]
	v_mfma_f32_16x16x32_bf16 v[68:71], v[182:185], v[222:225], v[68:71]
	v_mfma_f32_16x16x32_bf16 v[64:67], v[190:193], v[222:225], v[64:67]
	v_mfma_f32_16x16x32_bf16 v[116:119], v[186:189], v[202:205], v[116:119]
	v_mfma_f32_16x16x32_bf16 v[112:115], v[194:197], v[202:205], v[112:115]
	v_mfma_f32_16x16x32_bf16 v[100:103], v[186:189], v[210:213], v[100:103]
	v_mfma_f32_16x16x32_bf16 v[96:99], v[194:197], v[210:213], v[96:99]
	v_mfma_f32_16x16x32_bf16 v[84:87], v[186:189], v[218:221], v[84:87]
	v_mfma_f32_16x16x32_bf16 v[80:83], v[194:197], v[218:221], v[80:83]
	v_mfma_f32_16x16x32_bf16 v[68:71], v[186:189], v[228:231], v[68:71]
	v_mfma_f32_16x16x32_bf16 v[64:67], v[194:197], v[228:231], v[64:67]
	s_setprio 0
	s_barrier
; #define PG8_STAGE(bufoff, gbase, voff) do { _Pragma("unroll") for (int _i = 0; _i < 2; ++_i) \
;         __builtin_amdgcn_global_load_lds((const unsigned*)((const char*)(gbase) + (voff)[_i]), (PG8_LAS unsigned*)(lds + (bufoff) + ldsw + _i * 8192), 16, 0, 0); } while (0)
; #define PG8_LDA(dst, b, h) do { _Pragma("unroll") for (int m = 0; m < 4; ++m) _Pragma("unroll") for (int k = 0; k < 2; ++k) dst[m][k] = *(const PG8_LAS bf16x8*)(lds + PG8_SA(b, h) + aoff + m * 2048 + k * 1024); } while (0)
; #define PG8_MMA(ai, bj, At, Bt) do { __builtin_amdgcn_s_setprio(1); _Pragma("unroll") for (int m = 0; m < 4; ++m) _Pragma("unroll") for (int n = 0; n < 2; ++n) _Pragma("unroll") for (int k = 0; k < 2; ++k) \
;         acc[ai][bj][m][n] = mma16<F16>(Bt[n][k], At[m][k], acc[ai][bj][m][n]); __builtin_amdgcn_s_setprio(0); } while (0)
; #define PG8_WAIT_V(n) asm volatile("s_waitcnt vmcnt(" #n ")" ::: "memory")
; #define PG8_WAIT_L(n) asm volatile("s_waitcnt lgkmcnt(" #n ")" ::: "memory")
; #define PG8_BAR __builtin_amdgcn_s_barrier()
; #define PG8_SCHED __builtin_amdgcn_sched_barrier(0)
; template <class Epi, class Sched, bool ALIGN_EPI = false, bool SP2 = false, bool F16 = false, bool TOKPERM = false>
; __device__ __forceinline__ void gemm_phase(PG8_LAS unsigned char* lds, const Gemm g, const Sched& S, const Epi& E, int wv) {
;     ...
;             PG8_LDA(At, 1, 1); PG8_STAGE(PG8_SB(1, 0), b3, voffB); PG8_STAGE(PG8_SB(1, 1), b3 + hstep, voffB); PG8_STAGE(PG8_SA(1, 0), a3, voffA);
;             PG8_WAIT_V(8); PG8_WAIT_L(0); PG8_BAR; PG8_MMA(1, 0, At, B0); PG8_MMA(1, 1, At, B1); PG8_BAR; PG8_SCHED;
;   __device__ __forceinline__ void operator()(const pg8::f32x4 (&acc)[2][2][4][2], const pg8::Unit& u, int wr, int wc, int fr, int fq) const {
;     ...
;     const int row0 = u.pm * 256 + wr * 64 + fr + z, colb = u.pn * 256 + wc * 32 + 8 * fq + z;
; #pragma unroll
;     for (int ai = 0; ai < 2; ++ai)
; #pragma unroll
;       for (int m = 0; m < 4; ++m) {
;         const int tok = row0 + ai * 128 + m * 16; float ss = 0.f;
; #pragma unroll
;         for (int bj = 0; bj < 2; ++bj) {
;           const unsigned off = (unsigned)tok * DM + colb + 128 * bj;
;           f8_t n = __builtin_convertvector(*(const h8_t*)(x16 + off), f8_t);
	s_mov_b32 m0, s49
	v_lshl_add_u64 v[232:233], v[232:233], 0, s[14:15]
	s_add_u32 s16, s20, 0xb0080
	ds_read_b128 v[198:201], v147 offset:49152
	ds_read_b128 v[202:205], v147 offset:50176
	ds_read_b128 v[206:209], v147 offset:51200
	ds_read_b128 v[210:213], v147 offset:52224
	ds_read_b128 v[214:217], v147 offset:53248
	ds_read_b128 v[218:221], v147 offset:54272
	ds_read_b128 v[222:225], v147 offset:55296
	ds_read_b128 v[228:231], v147 offset:56320
	global_load_lds_dwordx4 v[232:233], off
	v_lshl_add_u64 v[232:233], v[234:235], 0, s[14:15]
	s_mov_b32 m0, s50
	s_addc_u32 s17, s21, 0
	global_load_lds_dwordx4 v[232:233], off
	v_lshl_add_u64 v[232:233], s[16:17], 0, v[130:131]
	s_mov_b32 m0, s53
	s_nop 0
	global_load_lds_dwordx4 v[232:233], off
	v_lshl_add_u64 v[232:233], s[16:17], 0, v[134:135]
	s_mov_b32 m0, s54
	s_nop 0
	global_load_lds_dwordx4 v[232:233], off
	v_lshl_add_u64 v[232:233], v[236:237], 0, s[14:15]
	s_mov_b32 m0, s51
	s_nop 0
	global_load_lds_dwordx4 v[232:233], off
	v_lshl_add_u64 v[232:233], v[238:239], 0, s[14:15]
	s_mov_b32 m0, s52
	s_nop 0
	global_load_lds_dwordx4 v[232:233], off
	s_waitcnt vmcnt(8)
	s_waitcnt lgkmcnt(0)
	s_barrier
	s_setprio 1
	s_waitcnt lgkmcnt(0)
	v_mfma_f32_16x16x32_bf16 v[60:63], v[166:169], v[198:201], v[60:63]
	v_mfma_f32_16x16x32_bf16 v[56:59], v[174:177], v[198:201], v[56:59]
	v_mfma_f32_16x16x32_bf16 v[44:47], v[166:169], v[206:209], v[44:47]
	v_mfma_f32_16x16x32_bf16 v[40:43], v[174:177], v[206:209], v[40:43]
	v_mfma_f32_16x16x32_bf16 v[28:31], v[166:169], v[214:217], v[28:31]
	v_mfma_f32_16x16x32_bf16 v[24:27], v[174:177], v[214:217], v[24:27]
	v_mfma_f32_16x16x32_bf16 v[12:15], v[166:169], v[222:225], v[12:15]
	v_mfma_f32_16x16x32_bf16 v[8:11], v[174:177], v[222:225], v[8:11]
	v_mfma_f32_16x16x32_bf16 v[60:63], v[170:173], v[202:205], v[60:63]
	v_mfma_f32_16x16x32_bf16 v[56:59], v[178:181], v[202:205], v[56:59]
	v_mfma_f32_16x16x32_bf16 v[44:47], v[170:173], v[210:213], v[44:47]
	v_mfma_f32_16x16x32_bf16 v[40:43], v[178:181], v[210:213], v[40:43]
	v_mfma_f32_16x16x32_bf16 v[28:31], v[170:173], v[218:221], v[28:31]
	v_mfma_f32_16x16x32_bf16 v[24:27], v[178:181], v[218:221], v[24:27]
	v_mfma_f32_16x16x32_bf16 v[12:15], v[170:173], v[228:231], v[12:15]
	v_mfma_f32_16x16x32_bf16 v[8:11], v[178:181], v[228:231], v[8:11]
	s_setprio 0
	s_setprio 1
	v_mfma_f32_16x16x32_bf16 v[52:55], v[182:185], v[198:201], v[52:55]
	v_mfma_f32_16x16x32_bf16 v[48:51], v[190:193], v[198:201], v[48:51]
	v_mfma_f32_16x16x32_bf16 v[36:39], v[182:185], v[206:209], v[36:39]
	v_mfma_f32_16x16x32_bf16 v[32:35], v[190:193], v[206:209], v[32:35]
	v_mfma_f32_16x16x32_bf16 v[20:23], v[182:185], v[214:217], v[20:23]
	v_mfma_f32_16x16x32_bf16 v[16:19], v[190:193], v[214:217], v[16:19]
	v_mfma_f32_16x16x32_bf16 v[4:7], v[182:185], v[222:225], v[4:7]
	v_mfma_f32_16x16x32_bf16 v[0:3], v[190:193], v[222:225], v[0:3]
	v_mfma_f32_16x16x32_bf16 v[52:55], v[186:189], v[202:205], v[52:55]
	v_mfma_f32_16x16x32_bf16 v[48:51], v[194:197], v[202:205], v[48:51]
	v_mfma_f32_16x16x32_bf16 v[36:39], v[186:189], v[210:213], v[36:39]
	v_mfma_f32_16x16x32_bf16 v[32:35], v[194:197], v[210:213], v[32:35]
	v_mfma_f32_16x16x32_bf16 v[20:23], v[186:189], v[218:221], v[20:23]
	v_mfma_f32_16x16x32_bf16 v[16:19], v[194:197], v[218:221], v[16:19]
	v_mfma_f32_16x16x32_bf16 v[4:7], v[186:189], v[228:231], v[4:7]
	v_mfma_f32_16x16x32_bf16 v[0:3], v[194:197], v[228:231], v[0:3]
	s_setprio 0
	s_barrier
	s_add_i32 s67, s67, 2
	s_add_u32 s65, s65, 0x100
	s_addc_u32 s66, s66, 0
	s_cmp_gt_u32 s67, 41
	s_mov_b64 s[16:17], s[18:19]
	s_cbranch_scc0 .LBB0_867
	s_lshl_b32 s16, s64, 8
	v_lshl_or_b32 v166, s63, 8, v148
	v_mov_b32 v136, 0
	v_xor_b32_e32 v169, 32, v165
	v_add3_u32 v167, s16, v146, v136
	v_add_u32_e32 v168, v166, v136
	v_lshl_add_u32 v136, v167, 10, v168
	v_lshl_add_u64 v[178:179], v[136:137], 1, s[40:41]
	v_add_u32_e32 v136, 0x80, v136
	global_load_dwordx4 v[170:173], v[178:179], off
	v_lshl_add_u64 v[180:181], v[136:137], 1, s[40:41]
	global_load_dwordx4 v[174:177], v[180:181], off
	v_add_u32_e32 v136, 16, v167
	v_lshl_add_u32 v136, v136, 10, v168
	v_lshl_add_u64 v[224:225], v[136:137], 1, s[40:41]
	v_add_u32_e32 v136, 0x80, v136
	global_load_dwordx4 v[192:195], v[224:225], off
	v_lshl_add_u64 v[248:249], v[136:137], 1, s[40:41]
	global_load_dwordx4 v[196:199], v[248:249], off
	v_add_u32_e32 v136, 32, v167
	v_lshl_add_u32 v136, v136, 10, v168
	v_lshl_add_u64 v[224:225], v[136:137], 1, s[40:41]
	v_add_u32_e32 v136, 0x80, v136
	global_load_dwordx4 v[200:203], v[224:225], off
	v_lshl_add_u64 v[248:249], v[136:137], 1, s[40:41]
	global_load_dwordx4 v[204:207], v[248:249], off
	v_add_u32_e32 v136, 48, v167
	v_lshl_add_u32 v136, v136, 10, v168
	v_lshl_add_u64 v[224:225], v[136:137], 1, s[40:41]
	v_add_u32_e32 v136, 0x80, v136
	global_load_dwordx4 v[208:211], v[224:225], off
	v_lshl_add_u64 v[248:249], v[136:137], 1, s[40:41]
	global_load_dwordx4 v[212:215], v[248:249], off
	v_add_u32_e32 v136, 0x80, v167
	v_lshl_add_u32 v136, v136, 10, v168
	v_lshl_add_u64 v[224:225], v[136:137], 1, s[40:41]
	v_add_u32_e32 v136, 0x80, v136
	global_load_dwordx4 v[216:219], v[224:225], off
	v_lshl_add_u64 v[248:249], v[136:137], 1, s[40:41]
	global_load_dwordx4 v[220:223], v[248:249], off
	v_add_u32_e32 v136, 0x90, v167
	v_lshl_add_u32 v136, v136, 10, v168
	v_lshl_add_u64 v[224:225], v[136:137], 1, s[40:41]
	v_add_u32_e32 v136, 0x80, v136
	global_load_dwordx4 v[228:231], v[224:225], off
	v_lshl_add_u64 v[248:249], v[136:137], 1, s[40:41]
	global_load_dwordx4 v[244:247], v[248:249], off
	v_and_b32_e32 v166, 64, v165
	v_xor_b32_e32 v136, 16, v165
	v_add_u32_e32 v166, 64, v166
	v_cmp_lt_i32_e32 vcc, v136, v166
	s_lshl_b32 s16, s63, 2
	s_or_b32 s18, s16, s48
	v_cndmask_b32_e32 v136, v165, v136, vcc
	v_cmp_lt_i32_e32 vcc, v169, v166
	v_lshlrev_b32_e32 v166, 2, v136
	s_waitcnt vmcnt(10)
;   __device__ __forceinline__ void operator()(const pg8::f32x4 (&acc)[2][2][4][2], const pg8::Unit& u, int wr, int wc, int fr, int fq) const {
;     ...
;         const int tok = row0 + ai * 128 + m * 16; float ss = 0.f;
; #pragma unroll
;         for (int bj = 0; bj < 2; ++bj) {
;           const unsigned off = (unsigned)tok * DM + colb + 128 * bj;
;           f8_t n = __builtin_convertvector(*(const h8_t*)(x16 + off), f8_t);
; #pragma unroll
;           for (int c = 0; c < 4; ++c) { n[c] += sc * acc[ai][bj][m][0][c]; n[4 + c] += sc * acc[ai][bj][m][1][c]; }
;           if (aux) {
;             *(h8_t*)(x16 + off) = __builtin_convertvector(n, h8_t);
;             ss += ((n[0] * n[0] + n[1] * n[1]) + (n[2] * n[2] + n[3] * n[3])) + ((n[4] * n[4] + n[5] * n[5]) + (n[6] * n[6] + n[7] * n[7]));
;           } else {
;             *(f32x4*)(xout + off) = (f32x4){n[0], n[1], n[2], n[3]}; *(f32x4*)(xout + off + 4) = (f32x4){n[4], n[5], n[6], n[7]};
;           }
;         }
;         if (aux) { ss += __shfl_xor(ss, 16); ss += __shfl_xor(ss, 32); if (fq == 0) ssq[(unsigned)tok * 16 + u.pn * 4 + wc] = ss; }
	v_cvt_f32_f16_e32 v182, v173
	v_cvt_f32_f16_sdwa v183, v173 dst_sel:DWORD dst_unused:UNUSED_PAD src0_sel:WORD_1
	v_cvt_f32_f16_e32 v184, v171
	v_cvt_f32_f16_sdwa v185, v171 dst_sel:DWORD dst_unused:UNUSED_PAD src0_sel:WORD_1
	v_cvt_f32_f16_e32 v186, v172
	v_cvt_f32_f16_sdwa v187, v172 dst_sel:DWORD dst_unused:UNUSED_PAD src0_sel:WORD_1
	v_cvt_f32_f16_e32 v172, v170
	v_cvt_f32_f16_sdwa v173, v170 dst_sel:DWORD dst_unused:UNUSED_PAD src0_sel:WORD_1
	v_cvt_f32_f16_e32 v170, v177
	v_cvt_f32_f16_sdwa v171, v177 dst_sel:DWORD dst_unused:UNUSED_PAD src0_sel:WORD_1
	v_cvt_f32_f16_e32 v188, v175
	v_cvt_f32_f16_sdwa v189, v175 dst_sel:DWORD dst_unused:UNUSED_PAD src0_sel:WORD_1
	v_cvt_f32_f16_e32 v190, v176
	v_cvt_f32_f16_sdwa v191, v176 dst_sel:DWORD dst_unused:UNUSED_PAD src0_sel:WORD_1
	v_cvt_f32_f16_e32 v176, v174
	v_cvt_f32_f16_sdwa v177, v174 dst_sel:DWORD dst_unused:UNUSED_PAD src0_sel:WORD_1
	v_pk_fma_f32 v[124:125], v[124:125], 0.5, v[172:173] op_sel_hi:[1,0,1]
	v_pk_fma_f32 v[172:173], v[120:121], 0.5, v[186:187] op_sel_hi:[1,0,1]
	v_pk_fma_f32 v[126:127], v[126:127], 0.5, v[184:185] op_sel_hi:[1,0,1]
	v_pk_fma_f32 v[122:123], v[122:123], 0.5, v[182:183] op_sel_hi:[1,0,1]
	v_cvt_pk_f16_f32 v120, v172, v173
	v_cvt_pk_f16_f32 v121, v122, v123
	v_pk_mul_f32 v[174:175], v[124:125], v[124:125]
	v_pk_mul_f32 v[182:183], v[126:127], v[126:127]
	v_pk_fma_f32 v[174:175], v[172:173], v[172:173], v[174:175]
	v_pk_fma_f32 v[182:183], v[122:123], v[122:123], v[182:183]
	v_pk_fma_f32 v[176:177], v[116:117], 0.5, v[176:177] op_sel_hi:[1,0,1]
	v_pk_fma_f32 v[116:117], v[112:113], 0.5, v[190:191] op_sel_hi:[1,0,1]
	v_pk_fma_f32 v[184:185], v[118:119], 0.5, v[188:189] op_sel_hi:[1,0,1]
	v_pk_fma_f32 v[112:113], v[114:115], 0.5, v[170:171] op_sel_hi:[1,0,1]
	v_pk_fma_f32 v[174:175], v[176:177], v[176:177], v[174:175]
	v_pk_fma_f32 v[182:183], v[184:185], v[184:185], v[182:183]
	v_pk_fma_f32 v[174:175], v[116:117], v[116:117], v[174:175]
	v_pk_fma_f32 v[182:183], v[112:113], v[112:113], v[182:183]
	v_pk_add_f32 v[174:175], v[174:175], v[182:183]
	v_add_f32_e32 v114, v174, v175
	v_mov_b32_e32 v115, v114
	s_nop 1
	v_permlane16_swap_b32_e32 v114, v115
	v_cndmask_b32_e32 v169, v165, v169, vcc
	v_cvt_pk_f16_f32 v119, v126, v127
	v_cvt_pk_f16_f32 v118, v124, v125
	global_store_dwordx4 v[178:179], v[118:121], off
	s_nop 1
	v_cvt_pk_f16_f32 v119, v112, v113
	s_waitcnt lgkmcnt(0)
	v_add_f32_e32 v113, v114, v115
	v_lshlrev_b32_e32 v112, 2, v169
	v_mov_b32_e32 v114, v113
	s_nop 1
	v_permlane32_swap_b32_e32 v113, v114
	v_cvt_pk_f16_f32 v118, v116, v117
	v_cvt_pk_f16_f32 v117, v184, v185
	v_cvt_pk_f16_f32 v116, v176, v177
	global_store_dwordx4 v[180:181], v[116:119], off
	s_and_saveexec_b64 s[16:17], s[6:7]
	s_cbranch_execz .LBB0_870
	v_lshl_add_u32 v136, v167, 4, s18
	s_waitcnt lgkmcnt(0)
	v_add_f32_e32 v113, v113, v114
	v_lshl_add_u64 v[114:115], v[136:137], 2, s[42:43]
	global_store_dword v[114:115], v113, off
.LBB0_870:
	s_or_b64 exec, exec, s[16:17]
	v_add_u32_e32 v113, 16, v167
	v_lshl_add_u32 v136, v113, 10, v168
	v_lshl_add_u64 v[122:123], v[136:137], 1, s[40:41]
	v_add_u32_e32 v136, 0x80, v136
	v_lshl_add_u64 v[124:125], v[136:137], 1, s[40:41]
	s_waitcnt lgkmcnt(0)
	s_waitcnt vmcnt(10)
	v_cvt_f32_f16_e32 v126, v195
	v_cvt_f32_f16_sdwa v127, v195 dst_sel:DWORD dst_unused:UNUSED_PAD src0_sel:WORD_1
	v_cvt_f32_f16_e32 v170, v193
	v_cvt_f32_f16_sdwa v171, v193 dst_sel:DWORD dst_unused:UNUSED_PAD src0_sel:WORD_1
	v_cvt_f32_f16_e32 v172, v194
	v_cvt_f32_f16_sdwa v173, v194 dst_sel:DWORD dst_unused:UNUSED_PAD src0_sel:WORD_1
	v_cvt_f32_f16_e32 v116, v192
	v_cvt_f32_f16_sdwa v117, v192 dst_sel:DWORD dst_unused:UNUSED_PAD src0_sel:WORD_1
	v_cvt_f32_f16_e32 v114, v199
	v_cvt_f32_f16_sdwa v115, v199 dst_sel:DWORD dst_unused:UNUSED_PAD src0_sel:WORD_1
	v_cvt_f32_f16_e32 v174, v197
	v_cvt_f32_f16_sdwa v175, v197 dst_sel:DWORD dst_unused:UNUSED_PAD src0_sel:WORD_1
	v_cvt_f32_f16_e32 v176, v198
	v_cvt_f32_f16_sdwa v177, v198 dst_sel:DWORD dst_unused:UNUSED_PAD src0_sel:WORD_1
	v_cvt_f32_f16_e32 v120, v196
	v_cvt_f32_f16_sdwa v121, v196 dst_sel:DWORD dst_unused:UNUSED_PAD src0_sel:WORD_1
	v_pk_fma_f32 v[108:109], v[108:109], 0.5, v[116:117] op_sel_hi:[1,0,1]
	v_pk_fma_f32 v[116:117], v[104:105], 0.5, v[172:173] op_sel_hi:[1,0,1]
	v_pk_fma_f32 v[110:111], v[110:111], 0.5, v[170:171] op_sel_hi:[1,0,1]
	v_pk_fma_f32 v[106:107], v[106:107], 0.5, v[126:127] op_sel_hi:[1,0,1]
	v_pk_fma_f32 v[120:121], v[100:101], 0.5, v[120:121] op_sel_hi:[1,0,1]
	v_pk_fma_f32 v[170:171], v[96:97], 0.5, v[176:177] op_sel_hi:[1,0,1]
	v_pk_fma_f32 v[172:173], v[102:103], 0.5, v[174:175] op_sel_hi:[1,0,1]
	v_pk_fma_f32 v[96:97], v[98:99], 0.5, v[114:115] op_sel_hi:[1,0,1]
	v_cvt_pk_f16_f32 v105, v106, v107
	v_cvt_pk_f16_f32 v104, v116, v117
	v_pk_mul_f32 v[118:119], v[108:109], v[108:109]
	v_pk_mul_f32 v[126:127], v[110:111], v[110:111]
	v_pk_fma_f32 v[118:119], v[116:117], v[116:117], v[118:119]
	v_pk_fma_f32 v[126:127], v[106:107], v[106:107], v[126:127]
	v_pk_fma_f32 v[118:119], v[120:121], v[120:121], v[118:119]
	v_pk_fma_f32 v[126:127], v[172:173], v[172:173], v[126:127]
	v_pk_fma_f32 v[118:119], v[170:171], v[170:171], v[118:119]
	v_pk_fma_f32 v[126:127], v[96:97], v[96:97], v[126:127]
	v_pk_add_f32 v[118:119], v[118:119], v[126:127]
	v_add_f32_e32 v98, v118, v119
	v_mov_b32_e32 v99, v98
	s_nop 1
	v_permlane16_swap_b32_e32 v98, v99
	v_cvt_pk_f16_f32 v101, v96, v97
	v_cvt_pk_f16_f32 v103, v110, v111
	v_cvt_pk_f16_f32 v102, v108, v109
	v_cvt_pk_f16_f32 v100, v170, v171
	s_waitcnt lgkmcnt(0)
	v_add_f32_e32 v96, v98, v99
	v_mov_b32_e32 v97, v96
	s_nop 1
	v_permlane32_swap_b32_e32 v96, v97
	v_cvt_pk_f16_f32 v99, v172, v173
	v_cvt_pk_f16_f32 v98, v120, v121
	global_store_dwordx4 v[122:123], v[102:105], off
	global_store_dwordx4 v[124:125], v[98:101], off
	s_and_saveexec_b64 s[16:17], s[6:7]
	s_cbranch_execz .LBB0_872
	v_lshl_add_u32 v136, v113, 4, s18
	s_waitcnt lgkmcnt(0)
	v_add_f32_e32 v98, v96, v97
	v_lshl_add_u64 v[96:97], v[136:137], 2, s[42:43]
	global_store_dword v[96:97], v98, off
;   __device__ __forceinline__ void operator()(const pg8::f32x4 (&acc)[2][2][4][2], const pg8::Unit& u, int wr, int wc, int fr, int fq) const {
;     ...
;         const int tok = row0 + ai * 128 + m * 16; float ss = 0.f;
; #pragma unroll
;         for (int bj = 0; bj < 2; ++bj) {
;           const unsigned off = (unsigned)tok * DM + colb + 128 * bj;
;           f8_t n = __builtin_convertvector(*(const h8_t*)(x16 + off), f8_t);
; #pragma unroll
;           for (int c = 0; c < 4; ++c) { n[c] += sc * acc[ai][bj][m][0][c]; n[4 + c] += sc * acc[ai][bj][m][1][c]; }
;           if (aux) {
;             *(h8_t*)(x16 + off) = __builtin_convertvector(n, h8_t);
;             ss += ((n[0] * n[0] + n[1] * n[1]) + (n[2] * n[2] + n[3] * n[3])) + ((n[4] * n[4] + n[5] * n[5]) + (n[6] * n[6] + n[7] * n[7]));
;           } else {
;             *(f32x4*)(xout + off) = (f32x4){n[0], n[1], n[2], n[3]}; *(f32x4*)(xout + off + 4) = (f32x4){n[4], n[5], n[6], n[7]};
;           }
;         }
;         if (aux) { ss += __shfl_xor(ss, 16); ss += __shfl_xor(ss, 32); if (fq == 0) ssq[(unsigned)tok * 16 + u.pn * 4 + wc] = ss; }
.LBB0_872:
	s_or_b64 exec, exec, s[16:17]
	v_add_u32_e32 v96, 32, v167
	v_lshl_add_u32 v136, v96, 10, v168
	v_lshl_add_u64 v[106:107], v[136:137], 1, s[40:41]
	v_add_u32_e32 v136, 0x80, v136
	v_lshl_add_u64 v[108:109], v[136:137], 1, s[40:41]
	s_waitcnt vmcnt(10)
	v_cvt_f32_f16_e32 v110, v203
	v_cvt_f32_f16_sdwa v111, v203 dst_sel:DWORD dst_unused:UNUSED_PAD src0_sel:WORD_1
	v_cvt_f32_f16_e32 v114, v201
	v_cvt_f32_f16_sdwa v115, v201 dst_sel:DWORD dst_unused:UNUSED_PAD src0_sel:WORD_1
	v_cvt_f32_f16_e32 v116, v202
	v_cvt_f32_f16_sdwa v117, v202 dst_sel:DWORD dst_unused:UNUSED_PAD src0_sel:WORD_1
	v_cvt_f32_f16_e32 v100, v200
	v_cvt_f32_f16_sdwa v101, v200 dst_sel:DWORD dst_unused:UNUSED_PAD src0_sel:WORD_1
	v_cvt_f32_f16_e32 v98, v207
	v_cvt_f32_f16_sdwa v99, v207 dst_sel:DWORD dst_unused:UNUSED_PAD src0_sel:WORD_1
	v_cvt_f32_f16_e32 v118, v205
	v_cvt_f32_f16_sdwa v119, v205 dst_sel:DWORD dst_unused:UNUSED_PAD src0_sel:WORD_1
	v_cvt_f32_f16_e32 v120, v206
	v_cvt_f32_f16_sdwa v121, v206 dst_sel:DWORD dst_unused:UNUSED_PAD src0_sel:WORD_1
	v_cvt_f32_f16_e32 v104, v204
	v_cvt_f32_f16_sdwa v105, v204 dst_sel:DWORD dst_unused:UNUSED_PAD src0_sel:WORD_1
	v_pk_fma_f32 v[92:93], v[92:93], 0.5, v[100:101] op_sel_hi:[1,0,1]
	v_pk_fma_f32 v[100:101], v[88:89], 0.5, v[116:117] op_sel_hi:[1,0,1]
	v_pk_fma_f32 v[94:95], v[94:95], 0.5, v[114:115] op_sel_hi:[1,0,1]
	v_pk_fma_f32 v[90:91], v[90:91], 0.5, v[110:111] op_sel_hi:[1,0,1]
	v_cvt_pk_f16_f32 v88, v100, v101
	v_cvt_pk_f16_f32 v89, v90, v91
	v_pk_mul_f32 v[102:103], v[92:93], v[92:93]
	v_pk_mul_f32 v[110:111], v[94:95], v[94:95]
	v_pk_fma_f32 v[102:103], v[100:101], v[100:101], v[102:103]
	v_pk_fma_f32 v[110:111], v[90:91], v[90:91], v[110:111]
	v_pk_fma_f32 v[104:105], v[84:85], 0.5, v[104:105] op_sel_hi:[1,0,1]
	v_pk_fma_f32 v[114:115], v[80:81], 0.5, v[120:121] op_sel_hi:[1,0,1]
	v_pk_fma_f32 v[116:117], v[86:87], 0.5, v[118:119] op_sel_hi:[1,0,1]
	v_pk_fma_f32 v[80:81], v[82:83], 0.5, v[98:99] op_sel_hi:[1,0,1]
	v_pk_fma_f32 v[102:103], v[104:105], v[104:105], v[102:103]
	v_pk_fma_f32 v[110:111], v[116:117], v[116:117], v[110:111]
	v_pk_fma_f32 v[102:103], v[114:115], v[114:115], v[102:103]
	v_pk_fma_f32 v[110:111], v[80:81], v[80:81], v[110:111]
	s_waitcnt lgkmcnt(0)
	v_pk_add_f32 v[102:103], v[102:103], v[110:111]
	v_add_f32_e32 v82, v102, v103
	v_mov_b32_e32 v83, v82
	s_nop 1
	v_permlane16_swap_b32_e32 v82, v83
	v_cvt_pk_f16_f32 v85, v80, v81
	v_cvt_pk_f16_f32 v87, v94, v95
	v_cvt_pk_f16_f32 v86, v92, v93
	v_cvt_pk_f16_f32 v84, v114, v115
	s_waitcnt lgkmcnt(0)
	v_add_f32_e32 v80, v82, v83
	v_mov_b32_e32 v81, v80
	s_nop 1
	v_permlane32_swap_b32_e32 v80, v81
	v_cvt_pk_f16_f32 v83, v116, v117
	v_cvt_pk_f16_f32 v82, v104, v105
	global_store_dwordx4 v[106:107], v[86:89], off
	global_store_dwordx4 v[108:109], v[82:85], off
	s_and_saveexec_b64 s[16:17], s[6:7]
	s_cbranch_execz .LBB0_874
	v_lshl_add_u32 v136, v96, 4, s18
	s_waitcnt lgkmcnt(0)
	v_add_f32_e32 v82, v80, v81
	v_lshl_add_u64 v[80:81], v[136:137], 2, s[42:43]
	global_store_dword v[80:81], v82, off
.LBB0_874:
	s_or_b64 exec, exec, s[16:17]
	v_add_u32_e32 v80, 48, v167
	v_lshl_add_u32 v136, v80, 10, v168
	v_lshl_add_u64 v[90:91], v[136:137], 1, s[40:41]
	v_add_u32_e32 v136, 0x80, v136
	v_lshl_add_u64 v[92:93], v[136:137], 1, s[40:41]
	s_waitcnt vmcnt(10)
	v_cvt_f32_f16_e32 v94, v211
	v_cvt_f32_f16_sdwa v95, v211 dst_sel:DWORD dst_unused:UNUSED_PAD src0_sel:WORD_1
	v_cvt_f32_f16_e32 v96, v209
	v_cvt_f32_f16_sdwa v97, v209 dst_sel:DWORD dst_unused:UNUSED_PAD src0_sel:WORD_1
	v_cvt_f32_f16_e32 v98, v210
	v_cvt_f32_f16_sdwa v99, v210 dst_sel:DWORD dst_unused:UNUSED_PAD src0_sel:WORD_1
	v_cvt_f32_f16_e32 v84, v208
	v_cvt_f32_f16_sdwa v85, v208 dst_sel:DWORD dst_unused:UNUSED_PAD src0_sel:WORD_1
	v_cvt_f32_f16_e32 v82, v215
	v_cvt_f32_f16_sdwa v83, v215 dst_sel:DWORD dst_unused:UNUSED_PAD src0_sel:WORD_1
	v_cvt_f32_f16_e32 v100, v213
	v_cvt_f32_f16_sdwa v101, v213 dst_sel:DWORD dst_unused:UNUSED_PAD src0_sel:WORD_1
	v_cvt_f32_f16_e32 v102, v214
	v_cvt_f32_f16_sdwa v103, v214 dst_sel:DWORD dst_unused:UNUSED_PAD src0_sel:WORD_1
	v_cvt_f32_f16_e32 v88, v212
	v_cvt_f32_f16_sdwa v89, v212 dst_sel:DWORD dst_unused:UNUSED_PAD src0_sel:WORD_1
	v_pk_fma_f32 v[76:77], v[76:77], 0.5, v[84:85] op_sel_hi:[1,0,1]
	v_pk_fma_f32 v[84:85], v[72:73], 0.5, v[98:99] op_sel_hi:[1,0,1]
	v_pk_fma_f32 v[78:79], v[78:79], 0.5, v[96:97] op_sel_hi:[1,0,1]
	v_pk_fma_f32 v[74:75], v[74:75], 0.5, v[94:95] op_sel_hi:[1,0,1]
	v_cvt_pk_f16_f32 v72, v84, v85
	v_cvt_pk_f16_f32 v73, v74, v75
	v_pk_mul_f32 v[86:87], v[76:77], v[76:77]
	v_pk_mul_f32 v[94:95], v[78:79], v[78:79]
	v_pk_fma_f32 v[86:87], v[84:85], v[84:85], v[86:87]
	v_pk_fma_f32 v[94:95], v[74:75], v[74:75], v[94:95]
	v_pk_fma_f32 v[88:89], v[68:69], 0.5, v[88:89] op_sel_hi:[1,0,1]
	v_pk_fma_f32 v[96:97], v[64:65], 0.5, v[102:103] op_sel_hi:[1,0,1]
	v_pk_fma_f32 v[98:99], v[70:71], 0.5, v[100:101] op_sel_hi:[1,0,1]
	v_pk_fma_f32 v[64:65], v[66:67], 0.5, v[82:83] op_sel_hi:[1,0,1]
	v_pk_fma_f32 v[86:87], v[88:89], v[88:89], v[86:87]
	v_pk_fma_f32 v[94:95], v[98:99], v[98:99], v[94:95]
	v_pk_fma_f32 v[86:87], v[96:97], v[96:97], v[86:87]
	v_pk_fma_f32 v[94:95], v[64:65], v[64:65], v[94:95]
	s_waitcnt lgkmcnt(0)
	v_pk_add_f32 v[86:87], v[86:87], v[94:95]
	v_add_f32_e32 v66, v86, v87
	v_mov_b32_e32 v67, v66
	s_nop 1
	v_permlane16_swap_b32_e32 v66, v67
	v_cvt_pk_f16_f32 v69, v64, v65
	v_cvt_pk_f16_f32 v71, v78, v79
	v_cvt_pk_f16_f32 v70, v76, v77
	v_cvt_pk_f16_f32 v68, v96, v97
	s_waitcnt lgkmcnt(0)
	v_add_f32_e32 v64, v66, v67
	v_mov_b32_e32 v65, v64
	s_nop 1
	v_permlane32_swap_b32_e32 v64, v65
	v_cvt_pk_f16_f32 v67, v98, v99
	v_cvt_pk_f16_f32 v66, v88, v89
	global_store_dwordx4 v[90:91], v[70:73], off
	global_store_dwordx4 v[92:93], v[66:69], off
	s_and_saveexec_b64 s[16:17], s[6:7]
	s_cbranch_execz .LBB0_876
	v_lshl_add_u32 v136, v80, 4, s18
	s_waitcnt lgkmcnt(0)
	v_add_f32_e32 v66, v64, v65
	v_lshl_add_u64 v[64:65], v[136:137], 2, s[42:43]
	global_store_dword v[64:65], v66, off
;   __device__ __forceinline__ void operator()(const pg8::f32x4 (&acc)[2][2][4][2], const pg8::Unit& u, int wr, int wc, int fr, int fq) const {
;     ...
;         const int tok = row0 + ai * 128 + m * 16; float ss = 0.f;
; #pragma unroll
;         for (int bj = 0; bj < 2; ++bj) {
;           const unsigned off = (unsigned)tok * DM + colb + 128 * bj;
;           f8_t n = __builtin_convertvector(*(const h8_t*)(x16 + off), f8_t);
; #pragma unroll
;           for (int c = 0; c < 4; ++c) { n[c] += sc * acc[ai][bj][m][0][c]; n[4 + c] += sc * acc[ai][bj][m][1][c]; }
;           if (aux) {
;             *(h8_t*)(x16 + off) = __builtin_convertvector(n, h8_t);
;             ss += ((n[0] * n[0] + n[1] * n[1]) + (n[2] * n[2] + n[3] * n[3])) + ((n[4] * n[4] + n[5] * n[5]) + (n[6] * n[6] + n[7] * n[7]));
;           } else {
;             *(f32x4*)(xout + off) = (f32x4){n[0], n[1], n[2], n[3]}; *(f32x4*)(xout + off + 4) = (f32x4){n[4], n[5], n[6], n[7]};
;           }
;         }
;         if (aux) { ss += __shfl_xor(ss, 16); ss += __shfl_xor(ss, 32); if (fq == 0) ssq[(unsigned)tok * 16 + u.pn * 4 + wc] = ss; }
.LBB0_876:
	s_or_b64 exec, exec, s[16:17]
	v_add_u32_e32 v64, 0x80, v167
	v_lshl_add_u32 v136, v64, 10, v168
	v_lshl_add_u64 v[74:75], v[136:137], 1, s[40:41]
	v_add_u32_e32 v136, 0x80, v136
	v_lshl_add_u64 v[76:77], v[136:137], 1, s[40:41]
	s_waitcnt vmcnt(10)
	v_cvt_f32_f16_e32 v78, v219
	v_cvt_f32_f16_sdwa v79, v219 dst_sel:DWORD dst_unused:UNUSED_PAD src0_sel:WORD_1
	v_cvt_f32_f16_e32 v80, v217
	v_cvt_f32_f16_sdwa v81, v217 dst_sel:DWORD dst_unused:UNUSED_PAD src0_sel:WORD_1
	v_cvt_f32_f16_e32 v82, v218
	v_cvt_f32_f16_sdwa v83, v218 dst_sel:DWORD dst_unused:UNUSED_PAD src0_sel:WORD_1
	v_cvt_f32_f16_e32 v68, v216
	v_cvt_f32_f16_sdwa v69, v216 dst_sel:DWORD dst_unused:UNUSED_PAD src0_sel:WORD_1
	v_cvt_f32_f16_e32 v66, v223
	v_cvt_f32_f16_sdwa v67, v223 dst_sel:DWORD dst_unused:UNUSED_PAD src0_sel:WORD_1
	v_cvt_f32_f16_e32 v84, v221
	v_cvt_f32_f16_sdwa v85, v221 dst_sel:DWORD dst_unused:UNUSED_PAD src0_sel:WORD_1
	v_cvt_f32_f16_e32 v86, v222
	v_cvt_f32_f16_sdwa v87, v222 dst_sel:DWORD dst_unused:UNUSED_PAD src0_sel:WORD_1
	v_cvt_f32_f16_e32 v72, v220
	v_cvt_f32_f16_sdwa v73, v220 dst_sel:DWORD dst_unused:UNUSED_PAD src0_sel:WORD_1
	v_pk_fma_f32 v[60:61], v[60:61], 0.5, v[68:69] op_sel_hi:[1,0,1]
	v_pk_fma_f32 v[68:69], v[56:57], 0.5, v[82:83] op_sel_hi:[1,0,1]
	v_pk_fma_f32 v[62:63], v[62:63], 0.5, v[80:81] op_sel_hi:[1,0,1]
	v_pk_fma_f32 v[58:59], v[58:59], 0.5, v[78:79] op_sel_hi:[1,0,1]
	v_cvt_pk_f16_f32 v56, v68, v69
	v_cvt_pk_f16_f32 v57, v58, v59
	v_pk_mul_f32 v[70:71], v[60:61], v[60:61]
	v_pk_mul_f32 v[78:79], v[62:63], v[62:63]
	v_pk_fma_f32 v[70:71], v[68:69], v[68:69], v[70:71]
	v_pk_fma_f32 v[78:79], v[58:59], v[58:59], v[78:79]
	v_pk_fma_f32 v[72:73], v[52:53], 0.5, v[72:73] op_sel_hi:[1,0,1]
	v_pk_fma_f32 v[80:81], v[48:49], 0.5, v[86:87] op_sel_hi:[1,0,1]
	v_pk_fma_f32 v[82:83], v[54:55], 0.5, v[84:85] op_sel_hi:[1,0,1]
	v_pk_fma_f32 v[48:49], v[50:51], 0.5, v[66:67] op_sel_hi:[1,0,1]
	v_pk_fma_f32 v[70:71], v[72:73], v[72:73], v[70:71]
	v_pk_fma_f32 v[78:79], v[82:83], v[82:83], v[78:79]
	v_pk_fma_f32 v[70:71], v[80:81], v[80:81], v[70:71]
	v_pk_fma_f32 v[78:79], v[48:49], v[48:49], v[78:79]
	s_waitcnt lgkmcnt(0)
	v_pk_add_f32 v[70:71], v[70:71], v[78:79]
	v_add_f32_e32 v50, v70, v71
	v_mov_b32_e32 v51, v50
	s_nop 1
	v_permlane16_swap_b32_e32 v50, v51
	v_cvt_pk_f16_f32 v53, v48, v49
	v_cvt_pk_f16_f32 v55, v62, v63
	v_cvt_pk_f16_f32 v54, v60, v61
	v_cvt_pk_f16_f32 v52, v80, v81
	s_waitcnt lgkmcnt(0)
	v_add_f32_e32 v48, v50, v51
	v_mov_b32_e32 v49, v48
	s_nop 1
	v_permlane32_swap_b32_e32 v48, v49
	v_cvt_pk_f16_f32 v51, v82, v83
	v_cvt_pk_f16_f32 v50, v72, v73
	global_store_dwordx4 v[74:75], v[54:57], off
	global_store_dwordx4 v[76:77], v[50:53], off
	s_and_saveexec_b64 s[16:17], s[6:7]
	s_cbranch_execz .LBB0_878
	v_lshl_add_u32 v136, v64, 4, s18
	s_waitcnt lgkmcnt(0)
	v_add_f32_e32 v50, v48, v49
	v_lshl_add_u64 v[48:49], v[136:137], 2, s[42:43]
	global_store_dword v[48:49], v50, off
.LBB0_878:
	s_or_b64 exec, exec, s[16:17]
	v_add_u32_e32 v48, 0x90, v167
	v_lshl_add_u32 v136, v48, 10, v168
	v_lshl_add_u64 v[58:59], v[136:137], 1, s[40:41]
	v_add_u32_e32 v136, 0x80, v136
	v_lshl_add_u64 v[60:61], v[136:137], 1, s[40:41]
	s_waitcnt vmcnt(10)
	v_cvt_f32_f16_e32 v62, v231
	v_cvt_f32_f16_sdwa v63, v231 dst_sel:DWORD dst_unused:UNUSED_PAD src0_sel:WORD_1
	v_cvt_f32_f16_e32 v64, v229
	v_cvt_f32_f16_sdwa v65, v229 dst_sel:DWORD dst_unused:UNUSED_PAD src0_sel:WORD_1
	v_cvt_f32_f16_e32 v66, v230
	v_cvt_f32_f16_sdwa v67, v230 dst_sel:DWORD dst_unused:UNUSED_PAD src0_sel:WORD_1
	v_cvt_f32_f16_e32 v52, v228
	v_cvt_f32_f16_sdwa v53, v228 dst_sel:DWORD dst_unused:UNUSED_PAD src0_sel:WORD_1
	v_cvt_f32_f16_e32 v50, v247
	v_cvt_f32_f16_sdwa v51, v247 dst_sel:DWORD dst_unused:UNUSED_PAD src0_sel:WORD_1
	v_cvt_f32_f16_e32 v68, v245
	v_cvt_f32_f16_sdwa v69, v245 dst_sel:DWORD dst_unused:UNUSED_PAD src0_sel:WORD_1
	v_cvt_f32_f16_e32 v70, v246
	v_cvt_f32_f16_sdwa v71, v246 dst_sel:DWORD dst_unused:UNUSED_PAD src0_sel:WORD_1
	v_cvt_f32_f16_e32 v56, v244
	v_cvt_f32_f16_sdwa v57, v244 dst_sel:DWORD dst_unused:UNUSED_PAD src0_sel:WORD_1
	v_pk_fma_f32 v[44:45], v[44:45], 0.5, v[52:53] op_sel_hi:[1,0,1]
	v_pk_fma_f32 v[52:53], v[40:41], 0.5, v[66:67] op_sel_hi:[1,0,1]
	v_pk_fma_f32 v[46:47], v[46:47], 0.5, v[64:65] op_sel_hi:[1,0,1]
	v_pk_fma_f32 v[42:43], v[42:43], 0.5, v[62:63] op_sel_hi:[1,0,1]
	v_cvt_pk_f16_f32 v40, v52, v53
	v_cvt_pk_f16_f32 v41, v42, v43
	v_pk_mul_f32 v[54:55], v[44:45], v[44:45]
	v_pk_mul_f32 v[62:63], v[46:47], v[46:47]
	v_pk_fma_f32 v[54:55], v[52:53], v[52:53], v[54:55]
	v_pk_fma_f32 v[62:63], v[42:43], v[42:43], v[62:63]
	v_pk_fma_f32 v[56:57], v[36:37], 0.5, v[56:57] op_sel_hi:[1,0,1]
	v_pk_fma_f32 v[64:65], v[32:33], 0.5, v[70:71] op_sel_hi:[1,0,1]
	v_pk_fma_f32 v[66:67], v[38:39], 0.5, v[68:69] op_sel_hi:[1,0,1]
	v_pk_fma_f32 v[32:33], v[34:35], 0.5, v[50:51] op_sel_hi:[1,0,1]
	v_pk_fma_f32 v[54:55], v[56:57], v[56:57], v[54:55]
	v_pk_fma_f32 v[62:63], v[66:67], v[66:67], v[62:63]
	v_pk_fma_f32 v[54:55], v[64:65], v[64:65], v[54:55]
	v_pk_fma_f32 v[62:63], v[32:33], v[32:33], v[62:63]
	s_waitcnt lgkmcnt(0)
	v_pk_add_f32 v[54:55], v[54:55], v[62:63]
	v_add_f32_e32 v34, v54, v55
	v_mov_b32_e32 v35, v34
	s_nop 1
	v_permlane16_swap_b32_e32 v34, v35
	v_cvt_pk_f16_f32 v37, v32, v33
	v_cvt_pk_f16_f32 v39, v46, v47
	v_cvt_pk_f16_f32 v38, v44, v45
	v_cvt_pk_f16_f32 v36, v64, v65
	s_waitcnt lgkmcnt(0)
	v_add_f32_e32 v32, v34, v35
	v_mov_b32_e32 v33, v32
	s_nop 1
	v_permlane32_swap_b32_e32 v32, v33
	v_cvt_pk_f16_f32 v35, v66, v67
	v_cvt_pk_f16_f32 v34, v56, v57
	global_store_dwordx4 v[58:59], v[38:41], off
	global_store_dwordx4 v[60:61], v[34:37], off
	s_and_saveexec_b64 s[16:17], s[6:7]
	s_cbranch_execz .LBB0_880
	v_lshl_add_u32 v136, v48, 4, s18
	s_waitcnt lgkmcnt(0)
	v_add_f32_e32 v34, v32, v33
	v_lshl_add_u64 v[32:33], v[136:137], 2, s[42:43]
	global_store_dword v[32:33], v34, off
;   __device__ __forceinline__ void operator()(const pg8::f32x4 (&acc)[2][2][4][2], const pg8::Unit& u, int wr, int wc, int fr, int fq) const {
;     ...
;       for (int m = 0; m < 4; ++m) {
;         const int tok = row0 + ai * 128 + m * 16; float ss = 0.f;
; #pragma unroll
;         for (int bj = 0; bj < 2; ++bj) {
;           const unsigned off = (unsigned)tok * DM + colb + 128 * bj;
;           f8_t n = __builtin_convertvector(*(const h8_t*)(x16 + off), f8_t);
; #pragma unroll
;           for (int c = 0; c < 4; ++c) { n[c] += sc * acc[ai][bj][m][0][c]; n[4 + c] += sc * acc[ai][bj][m][1][c]; }
;           if (aux) {
;             *(h8_t*)(x16 + off) = __builtin_convertvector(n, h8_t);
;             ss += ((n[0] * n[0] + n[1] * n[1]) + (n[2] * n[2] + n[3] * n[3])) + ((n[4] * n[4] + n[5] * n[5]) + (n[6] * n[6] + n[7] * n[7]));
;           } else {
;             *(f32x4*)(xout + off) = (f32x4){n[0], n[1], n[2], n[3]}; *(f32x4*)(xout + off + 4) = (f32x4){n[4], n[5], n[6], n[7]};
;           }
;         }
;         if (aux) { ss += __shfl_xor(ss, 16); ss += __shfl_xor(ss, 32); if (fq == 0) ssq[(unsigned)tok * 16 + u.pn * 4 + wc] = ss; }
;         if (m & 1) asm volatile("" ::: "memory");
;       }
.LBB0_880:
	s_or_b64 exec, exec, s[16:17]
	v_add_u32_e32 v32, 0xa0, v167
	v_lshl_add_u32 v136, v32, 10, v168
	v_lshl_add_u64 v[42:43], v[136:137], 1, s[40:41]
	v_add_u32_e32 v136, 0x80, v136
	global_load_dwordx4 v[34:37], v[42:43], off
	v_lshl_add_u64 v[44:45], v[136:137], 1, s[40:41]
	global_load_dwordx4 v[38:41], v[44:45], off
	s_waitcnt vmcnt(1)
	v_cvt_f32_f16_e32 v46, v37
	v_cvt_f32_f16_sdwa v47, v37 dst_sel:DWORD dst_unused:UNUSED_PAD src0_sel:WORD_1
	v_cvt_f32_f16_e32 v48, v35
	v_cvt_f32_f16_sdwa v49, v35 dst_sel:DWORD dst_unused:UNUSED_PAD src0_sel:WORD_1
	v_cvt_f32_f16_e32 v50, v36
	v_cvt_f32_f16_sdwa v51, v36 dst_sel:DWORD dst_unused:UNUSED_PAD src0_sel:WORD_1
	v_cvt_f32_f16_e32 v36, v34
	v_cvt_f32_f16_sdwa v37, v34 dst_sel:DWORD dst_unused:UNUSED_PAD src0_sel:WORD_1
	s_waitcnt vmcnt(0)
	v_cvt_f32_f16_e32 v34, v41
	v_cvt_f32_f16_sdwa v35, v41 dst_sel:DWORD dst_unused:UNUSED_PAD src0_sel:WORD_1
	v_cvt_f32_f16_e32 v52, v39
	v_cvt_f32_f16_sdwa v53, v39 dst_sel:DWORD dst_unused:UNUSED_PAD src0_sel:WORD_1
	v_cvt_f32_f16_e32 v54, v40
	v_cvt_f32_f16_sdwa v55, v40 dst_sel:DWORD dst_unused:UNUSED_PAD src0_sel:WORD_1
	v_cvt_f32_f16_e32 v40, v38
	v_cvt_f32_f16_sdwa v41, v38 dst_sel:DWORD dst_unused:UNUSED_PAD src0_sel:WORD_1
	v_pk_fma_f32 v[28:29], v[28:29], 0.5, v[36:37] op_sel_hi:[1,0,1]
	v_pk_fma_f32 v[36:37], v[24:25], 0.5, v[50:51] op_sel_hi:[1,0,1]
	v_pk_fma_f32 v[30:31], v[30:31], 0.5, v[48:49] op_sel_hi:[1,0,1]
	v_pk_fma_f32 v[26:27], v[26:27], 0.5, v[46:47] op_sel_hi:[1,0,1]
	v_cvt_pk_f16_f32 v24, v36, v37
	v_cvt_pk_f16_f32 v25, v26, v27
	v_pk_mul_f32 v[38:39], v[28:29], v[28:29]
	v_pk_mul_f32 v[46:47], v[30:31], v[30:31]
	v_pk_fma_f32 v[38:39], v[36:37], v[36:37], v[38:39]
	v_pk_fma_f32 v[46:47], v[26:27], v[26:27], v[46:47]
	v_pk_fma_f32 v[40:41], v[20:21], 0.5, v[40:41] op_sel_hi:[1,0,1]
	v_pk_fma_f32 v[48:49], v[16:17], 0.5, v[54:55] op_sel_hi:[1,0,1]
	v_pk_fma_f32 v[50:51], v[22:23], 0.5, v[52:53] op_sel_hi:[1,0,1]
	v_pk_fma_f32 v[16:17], v[18:19], 0.5, v[34:35] op_sel_hi:[1,0,1]
	v_pk_fma_f32 v[38:39], v[40:41], v[40:41], v[38:39]
	v_pk_fma_f32 v[46:47], v[50:51], v[50:51], v[46:47]
	v_pk_fma_f32 v[38:39], v[48:49], v[48:49], v[38:39]
	v_pk_fma_f32 v[46:47], v[16:17], v[16:17], v[46:47]
	s_waitcnt lgkmcnt(0)
	v_pk_add_f32 v[38:39], v[38:39], v[46:47]
	v_add_f32_e32 v18, v38, v39
	v_mov_b32_e32 v19, v18
	s_nop 1
	v_permlane16_swap_b32_e32 v18, v19
	v_cvt_pk_f16_f32 v21, v16, v17
	v_cvt_pk_f16_f32 v23, v30, v31
	v_cvt_pk_f16_f32 v22, v28, v29
	v_cvt_pk_f16_f32 v20, v48, v49
	s_waitcnt lgkmcnt(0)
	v_add_f32_e32 v16, v18, v19
	v_mov_b32_e32 v17, v16
	s_nop 1
	v_permlane32_swap_b32_e32 v16, v17
	v_cvt_pk_f16_f32 v19, v50, v51
	v_cvt_pk_f16_f32 v18, v40, v41
	global_store_dwordx4 v[42:43], v[22:25], off
	global_store_dwordx4 v[44:45], v[18:21], off
	s_and_saveexec_b64 s[16:17], s[6:7]
	s_cbranch_execz .LBB0_882
	v_lshl_add_u32 v136, v32, 4, s18
	s_waitcnt lgkmcnt(0)
	v_add_f32_e32 v18, v16, v17
	v_lshl_add_u64 v[16:17], v[136:137], 2, s[42:43]
	global_store_dword v[16:17], v18, off
.LBB0_882:
	s_or_b64 exec, exec, s[16:17]
	v_add_u32_e32 v16, 0xb0, v167
	v_lshl_add_u32 v136, v16, 10, v168
	v_lshl_add_u64 v[26:27], v[136:137], 1, s[40:41]
	v_add_u32_e32 v136, 0x80, v136
	global_load_dwordx4 v[18:21], v[26:27], off
	v_lshl_add_u64 v[28:29], v[136:137], 1, s[40:41]
	global_load_dwordx4 v[22:25], v[28:29], off
	s_waitcnt vmcnt(1)
	v_cvt_f32_f16_e32 v30, v21
	v_cvt_f32_f16_sdwa v31, v21 dst_sel:DWORD dst_unused:UNUSED_PAD src0_sel:WORD_1
	v_cvt_f32_f16_e32 v32, v19
	v_cvt_f32_f16_sdwa v33, v19 dst_sel:DWORD dst_unused:UNUSED_PAD src0_sel:WORD_1
	v_cvt_f32_f16_e32 v34, v20
	v_cvt_f32_f16_sdwa v35, v20 dst_sel:DWORD dst_unused:UNUSED_PAD src0_sel:WORD_1
	v_cvt_f32_f16_e32 v20, v18
	v_cvt_f32_f16_sdwa v21, v18 dst_sel:DWORD dst_unused:UNUSED_PAD src0_sel:WORD_1
	s_waitcnt vmcnt(0)
	v_cvt_f32_f16_e32 v18, v25
	v_cvt_f32_f16_sdwa v19, v25 dst_sel:DWORD dst_unused:UNUSED_PAD src0_sel:WORD_1
	v_cvt_f32_f16_e32 v36, v23
	v_cvt_f32_f16_sdwa v37, v23 dst_sel:DWORD dst_unused:UNUSED_PAD src0_sel:WORD_1
	v_cvt_f32_f16_e32 v38, v24
	v_cvt_f32_f16_sdwa v39, v24 dst_sel:DWORD dst_unused:UNUSED_PAD src0_sel:WORD_1
	v_cvt_f32_f16_e32 v24, v22
	v_cvt_f32_f16_sdwa v25, v22 dst_sel:DWORD dst_unused:UNUSED_PAD src0_sel:WORD_1
	v_pk_fma_f32 v[12:13], v[12:13], 0.5, v[20:21] op_sel_hi:[1,0,1]
	v_pk_fma_f32 v[20:21], v[8:9], 0.5, v[34:35] op_sel_hi:[1,0,1]
	v_pk_fma_f32 v[14:15], v[14:15], 0.5, v[32:33] op_sel_hi:[1,0,1]
	v_pk_fma_f32 v[10:11], v[10:11], 0.5, v[30:31] op_sel_hi:[1,0,1]
	v_cvt_pk_f16_f32 v8, v20, v21
	v_cvt_pk_f16_f32 v9, v10, v11
	v_pk_mul_f32 v[22:23], v[12:13], v[12:13]
	v_pk_mul_f32 v[30:31], v[14:15], v[14:15]
	v_pk_fma_f32 v[22:23], v[20:21], v[20:21], v[22:23]
	v_pk_fma_f32 v[30:31], v[10:11], v[10:11], v[30:31]
	v_pk_fma_f32 v[24:25], v[4:5], 0.5, v[24:25] op_sel_hi:[1,0,1]
	v_pk_fma_f32 v[32:33], v[0:1], 0.5, v[38:39] op_sel_hi:[1,0,1]
	v_pk_fma_f32 v[34:35], v[6:7], 0.5, v[36:37] op_sel_hi:[1,0,1]
	v_pk_fma_f32 v[0:1], v[2:3], 0.5, v[18:19] op_sel_hi:[1,0,1]
	v_pk_fma_f32 v[22:23], v[24:25], v[24:25], v[22:23]
	v_pk_fma_f32 v[30:31], v[34:35], v[34:35], v[30:31]
	v_pk_fma_f32 v[22:23], v[32:33], v[32:33], v[22:23]
	v_pk_fma_f32 v[30:31], v[0:1], v[0:1], v[30:31]
	s_waitcnt lgkmcnt(0)
	v_pk_add_f32 v[22:23], v[22:23], v[30:31]
	v_add_f32_e32 v2, v22, v23
	v_mov_b32_e32 v3, v2
	s_nop 1
	v_permlane16_swap_b32_e32 v2, v3
	v_cvt_pk_f16_f32 v5, v0, v1
	v_cvt_pk_f16_f32 v7, v14, v15
	v_cvt_pk_f16_f32 v6, v12, v13
	v_cvt_pk_f16_f32 v4, v32, v33
	s_waitcnt lgkmcnt(0)
	v_add_f32_e32 v0, v2, v3
	v_mov_b32_e32 v1, v0
	s_nop 1
	v_permlane32_swap_b32_e32 v0, v1
	v_cvt_pk_f16_f32 v3, v34, v35
	v_cvt_pk_f16_f32 v2, v24, v25
	global_store_dwordx4 v[26:27], v[6:9], off
	global_store_dwordx4 v[28:29], v[2:5], off
	s_and_saveexec_b64 s[16:17], s[6:7]
	s_cbranch_execz .LBB0_855
	v_lshl_add_u32 v136, v16, 4, s18
	s_waitcnt lgkmcnt(0)
	v_add_f32_e32 v2, v0, v1
	v_lshl_add_u64 v[0:1], v[136:137], 2, s[42:43]
	global_store_dword v[0:1], v2, off
	s_branch .LBB0_855

; #define PG8_STAGE(bufoff, gbase, voff) do { _Pragma("unroll") for (int _i = 0; _i < 2; ++_i) \
;         __builtin_amdgcn_global_load_lds((const unsigned*)((const char*)(gbase) + (voff)[_i]), (PG8_LAS unsigned*)(lds + (bufoff) + ldsw + _i * 8192), 16, 0, 0); } while (0)
; #define PG8_LDA(dst, b, h) do { _Pragma("unroll") for (int m = 0; m < 4; ++m) _Pragma("unroll") for (int k = 0; k < 2; ++k) dst[m][k] = *(const PG8_LAS bf16x8*)(lds + PG8_SA(b, h) + aoff + m * 2048 + k * 1024); } while (0)
; #define PG8_LDB(dst, b, h) do { _Pragma("unroll") for (int n = 0; n < 2; ++n) _Pragma("unroll") for (int k = 0; k < 2; ++k) dst[n][k] = *(const PG8_LAS bf16x8*)(lds + PG8_SB(b, h) + boff + n * 2048 + k * 1024); } while (0)
; #define PG8_MMA(ai, bj, At, Bt) do { __builtin_amdgcn_s_setprio(1); _Pragma("unroll") for (int m = 0; m < 4; ++m) _Pragma("unroll") for (int n = 0; n < 2; ++n) _Pragma("unroll") for (int k = 0; k < 2; ++k) \
;         acc[ai][bj][m][n] = mma16<F16>(Bt[n][k], At[m][k], acc[ai][bj][m][n]); __builtin_amdgcn_s_setprio(0); } while (0)
; #define PG8_WAIT_V(n) asm volatile("s_waitcnt vmcnt(" #n ")" ::: "memory")
; #define PG8_WAIT_L(n) asm volatile("s_waitcnt lgkmcnt(" #n ")" ::: "memory")
; #define PG8_BAR __builtin_amdgcn_s_barrier()
; #define PG8_SCHED __builtin_amdgcn_sched_barrier(0)
; template <class Epi, class Sched, bool ALIGN_EPI = false, bool SP2 = false, bool F16 = false, bool TOKPERM = false>
; __device__ __forceinline__ void gemm_phase(PG8_LAS unsigned char* lds, const Gemm g, const Sched& S, const Epi& E, int wv) {
;     ...
;             PG8_LDB(B0, 0, 0); PG8_LDB(B1, 0, 1); PG8_SCHED; PG8_LDA(At, 0, 0); PG8_STAGE(PG8_SA(1, 1), a1 + hstep, voffA);
;             PG8_WAIT_V(8); PG8_WAIT_L(0); PG8_BAR; PG8_MMA(0, 0, At, B0); PG8_MMA(0, 1, At, B1); PG8_BAR; PG8_SCHED;
;             PG8_LDA(At, 0, 1); PG8_STAGE(PG8_SB(0, 0), b2, voffB); PG8_STAGE(PG8_SB(0, 1), b2 + hstep, voffB); PG8_STAGE(PG8_SA(0, 0), a2, voffA);
;             PG8_WAIT_V(8); PG8_WAIT_L(0); PG8_BAR; PG8_MMA(1, 0, At, B0); PG8_MMA(1, 1, At, B1); PG8_BAR; PG8_SCHED;
.LBB0_1524:
	ds_read_b128 v[166:169], v149
	ds_read_b128 v[170:173], v150
	ds_read_b128 v[174:177], v151
	ds_read_b128 v[178:181], v152
	ds_read_b128 v[182:185], v153
	ds_read_b128 v[186:189], v154
	ds_read_b128 v[190:193], v155
	ds_read_b128 v[194:197], v156
	s_add_u32 s44, s24, 0xfffc0080
	s_addc_u32 s45, s25, -1
	s_cmp_eq_u32 s65, 12
	s_cselect_b32 s47, s15, s45
	s_cselect_b32 s46, s21, s44
	s_cselect_b32 s45, s13, s64
	s_cselect_b32 s44, s62, s63
	s_mov_b32 m0, s60
	v_lshl_add_u64 v[232:233], s[24:25], 0, v[138:139]
	ds_read_b128 v[198:201], v147
	ds_read_b128 v[202:205], v147 offset:1024
	ds_read_b128 v[206:209], v147 offset:2048
	ds_read_b128 v[210:213], v147 offset:3072
	ds_read_b128 v[214:217], v147 offset:4096
	ds_read_b128 v[218:221], v147 offset:5120
	ds_read_b128 v[222:225], v147 offset:6144
	ds_read_b128 v[228:231], v147 offset:7168
	global_load_lds_dwordx4 v[232:233], off
	v_lshl_add_u64 v[232:233], s[24:25], 0, v[140:141]
	s_mov_b32 m0, s61
	s_nop 0
	global_load_lds_dwordx4 v[232:233], off
	s_waitcnt vmcnt(8)
	s_waitcnt lgkmcnt(0)
	s_barrier
	s_setprio 1
	s_waitcnt lgkmcnt(0)
	v_mfma_f32_16x16x32_bf16 v[124:127], v[166:169], v[198:201], v[124:127]
	v_mfma_f32_16x16x32_bf16 v[120:123], v[174:177], v[198:201], v[120:123]
	v_mfma_f32_16x16x32_bf16 v[108:111], v[166:169], v[206:209], v[108:111]
	v_mfma_f32_16x16x32_bf16 v[104:107], v[174:177], v[206:209], v[104:107]
	v_mfma_f32_16x16x32_bf16 v[92:95], v[166:169], v[214:217], v[92:95]
	v_mfma_f32_16x16x32_bf16 v[88:91], v[174:177], v[214:217], v[88:91]
	v_mfma_f32_16x16x32_bf16 v[76:79], v[166:169], v[222:225], v[76:79]
	v_mfma_f32_16x16x32_bf16 v[72:75], v[174:177], v[222:225], v[72:75]
	v_mfma_f32_16x16x32_bf16 v[124:127], v[170:173], v[202:205], v[124:127]
	v_mfma_f32_16x16x32_bf16 v[120:123], v[178:181], v[202:205], v[120:123]
	v_mfma_f32_16x16x32_bf16 v[108:111], v[170:173], v[210:213], v[108:111]
	v_mfma_f32_16x16x32_bf16 v[104:107], v[178:181], v[210:213], v[104:107]
	v_mfma_f32_16x16x32_bf16 v[92:95], v[170:173], v[218:221], v[92:95]
	v_mfma_f32_16x16x32_bf16 v[88:91], v[178:181], v[218:221], v[88:91]
	v_mfma_f32_16x16x32_bf16 v[76:79], v[170:173], v[228:231], v[76:79]
	v_mfma_f32_16x16x32_bf16 v[72:75], v[178:181], v[228:231], v[72:75]
	s_setprio 0
	s_setprio 1
	v_mfma_f32_16x16x32_bf16 v[116:119], v[182:185], v[198:201], v[116:119]
	v_mfma_f32_16x16x32_bf16 v[112:115], v[190:193], v[198:201], v[112:115]
	v_mfma_f32_16x16x32_bf16 v[100:103], v[182:185], v[206:209], v[100:103]
	v_mfma_f32_16x16x32_bf16 v[96:99], v[190:193], v[206:209], v[96:99]
	v_mfma_f32_16x16x32_bf16 v[84:87], v[182:185], v[214:217], v[84:87]
	v_mfma_f32_16x16x32_bf16 v[80:83], v[190:193], v[214:217], v[80:83]
	v_mfma_f32_16x16x32_bf16 v[68:71], v[182:185], v[222:225], v[68:71]
	v_mfma_f32_16x16x32_bf16 v[64:67], v[190:193], v[222:225], v[64:67]
	v_mfma_f32_16x16x32_bf16 v[116:119], v[186:189], v[202:205], v[116:119]
	v_mfma_f32_16x16x32_bf16 v[112:115], v[194:197], v[202:205], v[112:115]
	v_mfma_f32_16x16x32_bf16 v[100:103], v[186:189], v[210:213], v[100:103]
	v_mfma_f32_16x16x32_bf16 v[96:99], v[194:197], v[210:213], v[96:99]
	v_mfma_f32_16x16x32_bf16 v[84:87], v[186:189], v[218:221], v[84:87]
	v_mfma_f32_16x16x32_bf16 v[80:83], v[194:197], v[218:221], v[80:83]
	v_mfma_f32_16x16x32_bf16 v[68:71], v[186:189], v[228:231], v[68:71]
	v_mfma_f32_16x16x32_bf16 v[64:67], v[194:197], v[228:231], v[64:67]
	s_setprio 0
	s_barrier
	s_mov_b32 m0, s4
	v_lshl_add_u64 v[232:233], s[44:45], 0, v[130:131]
	s_add_u32 s66, s44, 0x40000
	ds_read_b128 v[198:201], v147 offset:16384
	ds_read_b128 v[202:205], v147 offset:17408
	ds_read_b128 v[206:209], v147 offset:18432
	ds_read_b128 v[210:213], v147 offset:19456
	ds_read_b128 v[214:217], v147 offset:20480
	ds_read_b128 v[218:221], v147 offset:21504
	ds_read_b128 v[222:225], v147 offset:22528
	ds_read_b128 v[228:231], v147 offset:23552
	global_load_lds_dwordx4 v[232:233], off
	v_lshl_add_u64 v[234:235], s[44:45], 0, v[134:135]
	s_mov_b32 m0, s5
	s_addc_u32 s67, s45, 0
	global_load_lds_dwordx4 v[234:235], off
	v_lshl_add_u64 v[236:237], s[66:67], 0, v[130:131]
	s_mov_b32 m0, s23
	v_lshl_add_u64 v[238:239], s[46:47], 0, v[132:133]
	global_load_lds_dwordx4 v[236:237], off
	v_lshl_add_u64 v[236:237], s[66:67], 0, v[134:135]
	s_mov_b32 m0, s33
	s_nop 0
	global_load_lds_dwordx4 v[236:237], off
	v_lshl_add_u64 v[236:237], s[46:47], 0, v[128:129]
	s_mov_b32 m0, s3
	s_nop 0
	global_load_lds_dwordx4 v[236:237], off
	s_mov_b32 m0, s36
	s_nop 0
	global_load_lds_dwordx4 v[238:239], off
	s_waitcnt vmcnt(8)
	s_waitcnt lgkmcnt(0)
	s_barrier
; #define PG8_STAGE(bufoff, gbase, voff) do { _Pragma("unroll") for (int _i = 0; _i < 2; ++_i) \
;         __builtin_amdgcn_global_load_lds((const unsigned*)((const char*)(gbase) + (voff)[_i]), (PG8_LAS unsigned*)(lds + (bufoff) + ldsw + _i * 8192), 16, 0, 0); } while (0)
; #define PG8_LDA(dst, b, h) do { _Pragma("unroll") for (int m = 0; m < 4; ++m) _Pragma("unroll") for (int k = 0; k < 2; ++k) dst[m][k] = *(const PG8_LAS bf16x8*)(lds + PG8_SA(b, h) + aoff + m * 2048 + k * 1024); } while (0)
; #define PG8_LDB(dst, b, h) do { _Pragma("unroll") for (int n = 0; n < 2; ++n) _Pragma("unroll") for (int k = 0; k < 2; ++k) dst[n][k] = *(const PG8_LAS bf16x8*)(lds + PG8_SB(b, h) + boff + n * 2048 + k * 1024); } while (0)
; #define PG8_MMA(ai, bj, At, Bt) do { __builtin_amdgcn_s_setprio(1); _Pragma("unroll") for (int m = 0; m < 4; ++m) _Pragma("unroll") for (int n = 0; n < 2; ++n) _Pragma("unroll") for (int k = 0; k < 2; ++k) \
;         acc[ai][bj][m][n] = mma16<F16>(Bt[n][k], At[m][k], acc[ai][bj][m][n]); __builtin_amdgcn_s_setprio(0); } while (0)
; #define PG8_WAIT_V(n) asm volatile("s_waitcnt vmcnt(" #n ")" ::: "memory")
; #define PG8_WAIT_L(n) asm volatile("s_waitcnt lgkmcnt(" #n ")" ::: "memory")
; #define PG8_BAR __builtin_amdgcn_s_barrier()
; #define PG8_SCHED __builtin_amdgcn_sched_barrier(0)
; template <class Epi, class Sched, bool ALIGN_EPI = false, bool SP2 = false, bool F16 = false, bool TOKPERM = false>
; __device__ __forceinline__ void gemm_phase(PG8_LAS unsigned char* lds, const Gemm g, const Sched& S, const Epi& E, int wv) {
;     ...
;             PG8_WAIT_V(8); PG8_WAIT_L(0); PG8_BAR; PG8_MMA(1, 0, At, B0); PG8_MMA(1, 1, At, B1); PG8_BAR; PG8_SCHED;
;             PG8_LDB(B0, 1, 0); PG8_LDB(B1, 1, 1); PG8_SCHED; PG8_LDA(At, 1, 0); PG8_STAGE(PG8_SA(0, 1), a2 + hstep, voffA);
;             PG8_WAIT_V(8); PG8_WAIT_L(0); PG8_BAR; PG8_MMA(0, 0, At, B0); PG8_MMA(0, 1, At, B1); PG8_BAR; PG8_SCHED;
;             PG8_LDA(At, 1, 1); PG8_STAGE(PG8_SB(1, 0), b3, voffB); PG8_STAGE(PG8_SB(1, 1), b3 + hstep, voffB); PG8_STAGE(PG8_SA(1, 0), a3, voffA);
;             PG8_WAIT_V(8); PG8_WAIT_L(0); PG8_BAR; PG8_MMA(1, 0, At, B0); PG8_MMA(1, 1, At, B1); PG8_BAR; PG8_SCHED;
	s_setprio 1
	s_waitcnt lgkmcnt(0)
	v_mfma_f32_16x16x32_bf16 v[60:63], v[166:169], v[198:201], v[60:63]
	v_mfma_f32_16x16x32_bf16 v[56:59], v[174:177], v[198:201], v[56:59]
	v_mfma_f32_16x16x32_bf16 v[44:47], v[166:169], v[206:209], v[44:47]
	v_mfma_f32_16x16x32_bf16 v[40:43], v[174:177], v[206:209], v[40:43]
	v_mfma_f32_16x16x32_bf16 v[28:31], v[166:169], v[214:217], v[28:31]
	v_mfma_f32_16x16x32_bf16 v[24:27], v[174:177], v[214:217], v[24:27]
	v_mfma_f32_16x16x32_bf16 v[12:15], v[166:169], v[222:225], v[12:15]
	v_mfma_f32_16x16x32_bf16 v[8:11], v[174:177], v[222:225], v[8:11]
	v_mfma_f32_16x16x32_bf16 v[60:63], v[170:173], v[202:205], v[60:63]
	v_mfma_f32_16x16x32_bf16 v[56:59], v[178:181], v[202:205], v[56:59]
	v_mfma_f32_16x16x32_bf16 v[44:47], v[170:173], v[210:213], v[44:47]
	v_mfma_f32_16x16x32_bf16 v[40:43], v[178:181], v[210:213], v[40:43]
	v_mfma_f32_16x16x32_bf16 v[28:31], v[170:173], v[218:221], v[28:31]
	v_mfma_f32_16x16x32_bf16 v[24:27], v[178:181], v[218:221], v[24:27]
	v_mfma_f32_16x16x32_bf16 v[12:15], v[170:173], v[228:231], v[12:15]
	v_mfma_f32_16x16x32_bf16 v[8:11], v[178:181], v[228:231], v[8:11]
	s_setprio 0
	s_setprio 1
	v_mfma_f32_16x16x32_bf16 v[52:55], v[182:185], v[198:201], v[52:55]
	v_mfma_f32_16x16x32_bf16 v[48:51], v[190:193], v[198:201], v[48:51]
	v_mfma_f32_16x16x32_bf16 v[36:39], v[182:185], v[206:209], v[36:39]
	v_mfma_f32_16x16x32_bf16 v[32:35], v[190:193], v[206:209], v[32:35]
	v_mfma_f32_16x16x32_bf16 v[20:23], v[182:185], v[214:217], v[20:23]
	v_mfma_f32_16x16x32_bf16 v[16:19], v[190:193], v[214:217], v[16:19]
	v_mfma_f32_16x16x32_bf16 v[4:7], v[182:185], v[222:225], v[4:7]
	v_mfma_f32_16x16x32_bf16 v[0:3], v[190:193], v[222:225], v[0:3]
	v_mfma_f32_16x16x32_bf16 v[52:55], v[186:189], v[202:205], v[52:55]
	v_mfma_f32_16x16x32_bf16 v[48:51], v[194:197], v[202:205], v[48:51]
	v_mfma_f32_16x16x32_bf16 v[36:39], v[186:189], v[210:213], v[36:39]
	v_mfma_f32_16x16x32_bf16 v[32:35], v[194:197], v[210:213], v[32:35]
	v_mfma_f32_16x16x32_bf16 v[20:23], v[186:189], v[218:221], v[20:23]
	v_mfma_f32_16x16x32_bf16 v[16:19], v[194:197], v[218:221], v[16:19]
	v_mfma_f32_16x16x32_bf16 v[4:7], v[186:189], v[228:231], v[4:7]
	v_mfma_f32_16x16x32_bf16 v[0:3], v[194:197], v[228:231], v[0:3]
	s_setprio 0
	s_barrier
	ds_read_b128 v[166:169], v157
	ds_read_b128 v[170:173], v158
	ds_read_b128 v[174:177], v159
	ds_read_b128 v[178:181], v160
	ds_read_b128 v[182:185], v161
	ds_read_b128 v[186:189], v162
	ds_read_b128 v[190:193], v163
	ds_read_b128 v[194:197], v164
	s_add_u32 s46, s46, 0x40000
	s_addc_u32 s47, s47, 0
	s_mov_b32 m0, s37
	v_lshl_add_u64 v[240:241], s[46:47], 0, v[128:129]
	ds_read_b128 v[198:201], v147 offset:32768
	ds_read_b128 v[202:205], v147 offset:33792
	ds_read_b128 v[206:209], v147 offset:34816
	ds_read_b128 v[210:213], v147 offset:35840
	ds_read_b128 v[214:217], v147 offset:36864
	ds_read_b128 v[218:221], v147 offset:37888
	ds_read_b128 v[222:225], v147 offset:38912
	ds_read_b128 v[228:231], v147 offset:39936
	global_load_lds_dwordx4 v[240:241], off
	v_lshl_add_u64 v[240:241], s[46:47], 0, v[132:133]
	s_mov_b32 m0, s48
	s_nop 0
	global_load_lds_dwordx4 v[240:241], off
	s_waitcnt vmcnt(8)
	s_waitcnt lgkmcnt(0)
	s_barrier
	s_setprio 1
	s_waitcnt lgkmcnt(0)
	v_mfma_f32_16x16x32_bf16 v[124:127], v[166:169], v[198:201], v[124:127]
	v_mfma_f32_16x16x32_bf16 v[120:123], v[174:177], v[198:201], v[120:123]
	v_mfma_f32_16x16x32_bf16 v[108:111], v[166:169], v[206:209], v[108:111]
	v_mfma_f32_16x16x32_bf16 v[104:107], v[174:177], v[206:209], v[104:107]
	v_mfma_f32_16x16x32_bf16 v[92:95], v[166:169], v[214:217], v[92:95]
	v_mfma_f32_16x16x32_bf16 v[88:91], v[174:177], v[214:217], v[88:91]
	v_mfma_f32_16x16x32_bf16 v[76:79], v[166:169], v[222:225], v[76:79]
	v_mfma_f32_16x16x32_bf16 v[72:75], v[174:177], v[222:225], v[72:75]
	v_mfma_f32_16x16x32_bf16 v[124:127], v[170:173], v[202:205], v[124:127]
	v_mfma_f32_16x16x32_bf16 v[120:123], v[178:181], v[202:205], v[120:123]
	v_mfma_f32_16x16x32_bf16 v[108:111], v[170:173], v[210:213], v[108:111]
	v_mfma_f32_16x16x32_bf16 v[104:107], v[178:181], v[210:213], v[104:107]
	v_mfma_f32_16x16x32_bf16 v[92:95], v[170:173], v[218:221], v[92:95]
	v_mfma_f32_16x16x32_bf16 v[88:91], v[178:181], v[218:221], v[88:91]
	v_mfma_f32_16x16x32_bf16 v[76:79], v[170:173], v[228:231], v[76:79]
	v_mfma_f32_16x16x32_bf16 v[72:75], v[178:181], v[228:231], v[72:75]
	s_setprio 0
	s_setprio 1
	v_mfma_f32_16x16x32_bf16 v[116:119], v[182:185], v[198:201], v[116:119]
	v_mfma_f32_16x16x32_bf16 v[112:115], v[190:193], v[198:201], v[112:115]
	v_mfma_f32_16x16x32_bf16 v[100:103], v[182:185], v[206:209], v[100:103]
	v_mfma_f32_16x16x32_bf16 v[96:99], v[190:193], v[206:209], v[96:99]
	v_mfma_f32_16x16x32_bf16 v[84:87], v[182:185], v[214:217], v[84:87]
	v_mfma_f32_16x16x32_bf16 v[80:83], v[190:193], v[214:217], v[80:83]
	v_mfma_f32_16x16x32_bf16 v[68:71], v[182:185], v[222:225], v[68:71]
	v_mfma_f32_16x16x32_bf16 v[64:67], v[190:193], v[222:225], v[64:67]
	v_mfma_f32_16x16x32_bf16 v[116:119], v[186:189], v[202:205], v[116:119]
	v_mfma_f32_16x16x32_bf16 v[112:115], v[194:197], v[202:205], v[112:115]
	v_mfma_f32_16x16x32_bf16 v[100:103], v[186:189], v[210:213], v[100:103]
	v_mfma_f32_16x16x32_bf16 v[96:99], v[194:197], v[210:213], v[96:99]
	v_mfma_f32_16x16x32_bf16 v[84:87], v[186:189], v[218:221], v[84:87]
	v_mfma_f32_16x16x32_bf16 v[80:83], v[194:197], v[218:221], v[80:83]
	v_mfma_f32_16x16x32_bf16 v[68:71], v[186:189], v[228:231], v[68:71]
	v_mfma_f32_16x16x32_bf16 v[64:67], v[194:197], v[228:231], v[64:67]
	s_setprio 0
	s_barrier
; #define PG8_STAGE(bufoff, gbase, voff) do { _Pragma("unroll") for (int _i = 0; _i < 2; ++_i) \
;         __builtin_amdgcn_global_load_lds((const unsigned*)((const char*)(gbase) + (voff)[_i]), (PG8_LAS unsigned*)(lds + (bufoff) + ldsw + _i * 8192), 16, 0, 0); } while (0)
; #define PG8_LDA(dst, b, h) do { _Pragma("unroll") for (int m = 0; m < 4; ++m) _Pragma("unroll") for (int k = 0; k < 2; ++k) dst[m][k] = *(const PG8_LAS bf16x8*)(lds + PG8_SA(b, h) + aoff + m * 2048 + k * 1024); } while (0)
; #define PG8_LDB(dst, b, h) do { _Pragma("unroll") for (int n = 0; n < 2; ++n) _Pragma("unroll") for (int k = 0; k < 2; ++k) dst[n][k] = *(const PG8_LAS bf16x8*)(lds + PG8_SB(b, h) + boff + n * 2048 + k * 1024); } while (0)
; #define PG8_WAIT_V(n) asm volatile("s_waitcnt vmcnt(" #n ")" ::: "memory")
; #define PG8_WAIT_L(n) asm volatile("s_waitcnt lgkmcnt(" #n ")" ::: "memory")
; #define PG8_BAR __builtin_amdgcn_s_barrier()
; #define PG8_SCHED __builtin_amdgcn_sched_barrier(0)
; template <class Epi, class Sched, bool ALIGN_EPI = false, bool SP2 = false, bool F16 = false, bool TOKPERM = false>
; __device__ __forceinline__ void gemm_phase(PG8_LAS unsigned char* lds, const Gemm g, const Sched& S, const Epi& E, int wv) {
;     ...
;             PG8_LDB(B0, 1, 0); PG8_LDB(B1, 1, 1); PG8_SCHED; PG8_LDA(At, 1, 0); PG8_STAGE(PG8_SA(0, 1), a2 + hstep, voffA);
;             PG8_WAIT_V(8); PG8_WAIT_L(0); PG8_BAR; PG8_MMA(0, 0, At, B0); PG8_MMA(0, 1, At, B1); PG8_BAR; PG8_SCHED;
;             PG8_LDA(At, 1, 1); PG8_STAGE(PG8_SB(1, 0), b3, voffB); PG8_STAGE(PG8_SB(1, 1), b3 + hstep, voffB); PG8_STAGE(PG8_SA(1, 0), a3, voffA);
;             PG8_WAIT_V(8); PG8_WAIT_L(0); PG8_BAR; PG8_MMA(1, 0, At, B0); PG8_MMA(1, 1, At, B1); PG8_BAR; PG8_SCHED;
;   __device__ __forceinline__ void operator()(const pg8::f32x4 (&acc)[2][2][4][2], const pg8::Unit& u, int wr, int wc, int fr, int fq) const {
;     ...
;     const int row0 = u.pm * 256 + wr * 64 + fr + z, colb = u.pn * 256 + wc * 32 + 8 * fq + z;
; #pragma unroll
;     for (int ai = 0; ai < 2; ++ai)
; #pragma unroll
;       for (int m = 0; m < 4; ++m) {
;         const int tok = row0 + ai * 128 + m * 16; float ss = 0.f;
; #pragma unroll
;         for (int bj = 0; bj < 2; ++bj) {
;           const unsigned off = (unsigned)tok * DM + colb + 128 * bj;
;           f8_t n = __builtin_convertvector(*(const h8_t*)(x16 + off), f8_t);
	s_mov_b32 m0, s50
	v_lshl_add_u64 v[232:233], v[232:233], 0, s[10:11]
	s_add_u32 s44, s44, 0x40080
	ds_read_b128 v[198:201], v147 offset:49152
	ds_read_b128 v[202:205], v147 offset:50176
	ds_read_b128 v[206:209], v147 offset:51200
	ds_read_b128 v[210:213], v147 offset:52224
	ds_read_b128 v[214:217], v147 offset:53248
	ds_read_b128 v[218:221], v147 offset:54272
	ds_read_b128 v[222:225], v147 offset:55296
	ds_read_b128 v[228:231], v147 offset:56320
	global_load_lds_dwordx4 v[232:233], off
	v_lshl_add_u64 v[232:233], v[234:235], 0, s[10:11]
	s_mov_b32 m0, s51
	s_addc_u32 s45, s45, 0
	global_load_lds_dwordx4 v[232:233], off
	v_lshl_add_u64 v[232:233], s[44:45], 0, v[130:131]
	s_mov_b32 m0, s54
	s_nop 0
	global_load_lds_dwordx4 v[232:233], off
	v_lshl_add_u64 v[232:233], s[44:45], 0, v[134:135]
	s_mov_b32 m0, s55
	s_nop 0
	global_load_lds_dwordx4 v[232:233], off
	v_lshl_add_u64 v[232:233], v[236:237], 0, s[10:11]
	s_mov_b32 m0, s52
	s_nop 0
	global_load_lds_dwordx4 v[232:233], off
	v_lshl_add_u64 v[232:233], v[238:239], 0, s[10:11]
	s_mov_b32 m0, s53
	s_nop 0
	global_load_lds_dwordx4 v[232:233], off
	s_waitcnt vmcnt(8)
	s_waitcnt lgkmcnt(0)
	s_barrier
	s_setprio 1
	s_waitcnt lgkmcnt(0)
	v_mfma_f32_16x16x32_bf16 v[60:63], v[166:169], v[198:201], v[60:63]
	v_mfma_f32_16x16x32_bf16 v[56:59], v[174:177], v[198:201], v[56:59]
	v_mfma_f32_16x16x32_bf16 v[44:47], v[166:169], v[206:209], v[44:47]
	v_mfma_f32_16x16x32_bf16 v[40:43], v[174:177], v[206:209], v[40:43]
	v_mfma_f32_16x16x32_bf16 v[28:31], v[166:169], v[214:217], v[28:31]
	v_mfma_f32_16x16x32_bf16 v[24:27], v[174:177], v[214:217], v[24:27]
	v_mfma_f32_16x16x32_bf16 v[12:15], v[166:169], v[222:225], v[12:15]
	v_mfma_f32_16x16x32_bf16 v[8:11], v[174:177], v[222:225], v[8:11]
	v_mfma_f32_16x16x32_bf16 v[60:63], v[170:173], v[202:205], v[60:63]
	v_mfma_f32_16x16x32_bf16 v[56:59], v[178:181], v[202:205], v[56:59]
	v_mfma_f32_16x16x32_bf16 v[44:47], v[170:173], v[210:213], v[44:47]
	v_mfma_f32_16x16x32_bf16 v[40:43], v[178:181], v[210:213], v[40:43]
	v_mfma_f32_16x16x32_bf16 v[28:31], v[170:173], v[218:221], v[28:31]
	v_mfma_f32_16x16x32_bf16 v[24:27], v[178:181], v[218:221], v[24:27]
	v_mfma_f32_16x16x32_bf16 v[12:15], v[170:173], v[228:231], v[12:15]
	v_mfma_f32_16x16x32_bf16 v[8:11], v[178:181], v[228:231], v[8:11]
	s_setprio 0
	s_setprio 1
	v_mfma_f32_16x16x32_bf16 v[52:55], v[182:185], v[198:201], v[52:55]
	v_mfma_f32_16x16x32_bf16 v[48:51], v[190:193], v[198:201], v[48:51]
	v_mfma_f32_16x16x32_bf16 v[36:39], v[182:185], v[206:209], v[36:39]
	v_mfma_f32_16x16x32_bf16 v[32:35], v[190:193], v[206:209], v[32:35]
	v_mfma_f32_16x16x32_bf16 v[20:23], v[182:185], v[214:217], v[20:23]
	v_mfma_f32_16x16x32_bf16 v[16:19], v[190:193], v[214:217], v[16:19]
	v_mfma_f32_16x16x32_bf16 v[4:7], v[182:185], v[222:225], v[4:7]
	v_mfma_f32_16x16x32_bf16 v[0:3], v[190:193], v[222:225], v[0:3]
	v_mfma_f32_16x16x32_bf16 v[52:55], v[186:189], v[202:205], v[52:55]
	v_mfma_f32_16x16x32_bf16 v[48:51], v[194:197], v[202:205], v[48:51]
	v_mfma_f32_16x16x32_bf16 v[36:39], v[186:189], v[210:213], v[36:39]
	v_mfma_f32_16x16x32_bf16 v[32:35], v[194:197], v[210:213], v[32:35]
	v_mfma_f32_16x16x32_bf16 v[20:23], v[186:189], v[218:221], v[20:23]
	v_mfma_f32_16x16x32_bf16 v[16:19], v[194:197], v[218:221], v[16:19]
	v_mfma_f32_16x16x32_bf16 v[4:7], v[186:189], v[228:231], v[4:7]
	v_mfma_f32_16x16x32_bf16 v[0:3], v[194:197], v[228:231], v[0:3]
	s_setprio 0
	s_barrier
	s_add_i32 s65, s65, 2
	s_add_u32 s24, s24, 0x100
	s_addc_u32 s25, s25, 0
	s_add_u32 s63, s63, 0x100
	s_addc_u32 s64, s64, 0
	s_cmp_gt_u32 s65, 13
	s_cbranch_scc0 .LBB0_1524
	s_lshl_b32 s13, s22, 8
	v_lshl_or_b32 v166, s20, 8, v148
	v_mov_b32 v136, 0
	v_xor_b32_e32 v169, 32, v165
	v_add3_u32 v167, s13, v146, v136
	v_add_u32_e32 v168, v166, v136
	v_lshl_add_u32 v136, v167, 10, v168
	v_lshl_add_u64 v[178:179], v[136:137], 1, s[40:41]
	v_add_u32_e32 v136, 0x80, v136
	global_load_dwordx4 v[170:173], v[178:179], off
	v_lshl_add_u64 v[180:181], v[136:137], 1, s[40:41]
	global_load_dwordx4 v[174:177], v[180:181], off
	v_add_u32_e32 v136, 16, v167
	v_lshl_add_u32 v136, v136, 10, v168
	v_lshl_add_u64 v[224:225], v[136:137], 1, s[40:41]
	v_add_u32_e32 v136, 0x80, v136
	global_load_dwordx4 v[192:195], v[224:225], off
	v_lshl_add_u64 v[248:249], v[136:137], 1, s[40:41]
	global_load_dwordx4 v[196:199], v[248:249], off
	v_add_u32_e32 v136, 32, v167
	v_lshl_add_u32 v136, v136, 10, v168
	v_lshl_add_u64 v[224:225], v[136:137], 1, s[40:41]
	v_add_u32_e32 v136, 0x80, v136
	global_load_dwordx4 v[200:203], v[224:225], off
	v_lshl_add_u64 v[248:249], v[136:137], 1, s[40:41]
	global_load_dwordx4 v[204:207], v[248:249], off
	v_add_u32_e32 v136, 48, v167
	v_lshl_add_u32 v136, v136, 10, v168
	v_lshl_add_u64 v[224:225], v[136:137], 1, s[40:41]
	v_add_u32_e32 v136, 0x80, v136
	global_load_dwordx4 v[208:211], v[224:225], off
	v_lshl_add_u64 v[248:249], v[136:137], 1, s[40:41]
	global_load_dwordx4 v[212:215], v[248:249], off
	v_add_u32_e32 v136, 0x80, v167
	v_lshl_add_u32 v136, v136, 10, v168
	v_lshl_add_u64 v[224:225], v[136:137], 1, s[40:41]
	v_add_u32_e32 v136, 0x80, v136
	global_load_dwordx4 v[216:219], v[224:225], off
	v_lshl_add_u64 v[248:249], v[136:137], 1, s[40:41]
	global_load_dwordx4 v[220:223], v[248:249], off
	v_add_u32_e32 v136, 0x90, v167
	v_lshl_add_u32 v136, v136, 10, v168
	v_lshl_add_u64 v[224:225], v[136:137], 1, s[40:41]
	v_add_u32_e32 v136, 0x80, v136
	global_load_dwordx4 v[228:231], v[224:225], off
	v_lshl_add_u64 v[248:249], v[136:137], 1, s[40:41]
	global_load_dwordx4 v[244:247], v[248:249], off
	v_and_b32_e32 v166, 64, v165
	v_xor_b32_e32 v136, 16, v165
	v_add_u32_e32 v166, 64, v166
	v_cmp_lt_i32_e32 vcc, v136, v166
	s_lshl_b32 s13, s20, 2
	s_or_b32 s13, s13, s49
	v_cndmask_b32_e32 v136, v165, v136, vcc
	v_cmp_lt_i32_e32 vcc, v169, v166
	v_lshlrev_b32_e32 v166, 2, v136
	s_waitcnt vmcnt(10)
;   __device__ __forceinline__ void operator()(const pg8::f32x4 (&acc)[2][2][4][2], const pg8::Unit& u, int wr, int wc, int fr, int fq) const {
;     ...
;       for (int m = 0; m < 4; ++m) {
;         const int tok = row0 + ai * 128 + m * 16; float ss = 0.f;
; #pragma unroll
;         for (int bj = 0; bj < 2; ++bj) {
;           const unsigned off = (unsigned)tok * DM + colb + 128 * bj;
;           f8_t n = __builtin_convertvector(*(const h8_t*)(x16 + off), f8_t);
; #pragma unroll
;           for (int c = 0; c < 4; ++c) { n[c] += sc * acc[ai][bj][m][0][c]; n[4 + c] += sc * acc[ai][bj][m][1][c]; }
;           if (aux) {
;             *(h8_t*)(x16 + off) = __builtin_convertvector(n, h8_t);
;             ss += ((n[0] * n[0] + n[1] * n[1]) + (n[2] * n[2] + n[3] * n[3])) + ((n[4] * n[4] + n[5] * n[5]) + (n[6] * n[6] + n[7] * n[7]));
;           } else {
;             *(f32x4*)(xout + off) = (f32x4){n[0], n[1], n[2], n[3]}; *(f32x4*)(xout + off + 4) = (f32x4){n[4], n[5], n[6], n[7]};
;           }
;         }
;         if (aux) { ss += __shfl_xor(ss, 16); ss += __shfl_xor(ss, 32); if (fq == 0) ssq[(unsigned)tok * 16 + u.pn * 4 + wc] = ss; }
;         if (m & 1) asm volatile("" ::: "memory");
;       }
	v_cvt_f32_f16_e32 v182, v173
	v_cvt_f32_f16_sdwa v183, v173 dst_sel:DWORD dst_unused:UNUSED_PAD src0_sel:WORD_1
	v_cvt_f32_f16_e32 v184, v171
	v_cvt_f32_f16_sdwa v185, v171 dst_sel:DWORD dst_unused:UNUSED_PAD src0_sel:WORD_1
	v_cvt_f32_f16_e32 v186, v172
	v_cvt_f32_f16_sdwa v187, v172 dst_sel:DWORD dst_unused:UNUSED_PAD src0_sel:WORD_1
	v_cvt_f32_f16_e32 v172, v170
	v_cvt_f32_f16_sdwa v173, v170 dst_sel:DWORD dst_unused:UNUSED_PAD src0_sel:WORD_1
	v_cvt_f32_f16_e32 v170, v177
	v_cvt_f32_f16_sdwa v171, v177 dst_sel:DWORD dst_unused:UNUSED_PAD src0_sel:WORD_1
	v_cvt_f32_f16_e32 v188, v175
	v_cvt_f32_f16_sdwa v189, v175 dst_sel:DWORD dst_unused:UNUSED_PAD src0_sel:WORD_1
	v_cvt_f32_f16_e32 v190, v176
	v_cvt_f32_f16_sdwa v191, v176 dst_sel:DWORD dst_unused:UNUSED_PAD src0_sel:WORD_1
	v_cvt_f32_f16_e32 v176, v174
	v_cvt_f32_f16_sdwa v177, v174 dst_sel:DWORD dst_unused:UNUSED_PAD src0_sel:WORD_1
	v_pk_add_f32 v[124:125], v[124:125], v[172:173]
	v_pk_add_f32 v[172:173], v[120:121], v[186:187]
	v_pk_add_f32 v[126:127], v[126:127], v[184:185]
	v_pk_add_f32 v[122:123], v[122:123], v[182:183]
	v_cvt_pk_f16_f32 v120, v172, v173
	v_cvt_pk_f16_f32 v121, v122, v123
	v_pk_mul_f32 v[174:175], v[124:125], v[124:125]
	v_pk_mul_f32 v[182:183], v[126:127], v[126:127]
	v_pk_fma_f32 v[174:175], v[172:173], v[172:173], v[174:175]
	v_pk_fma_f32 v[182:183], v[122:123], v[122:123], v[182:183]
	v_pk_add_f32 v[176:177], v[116:117], v[176:177]
	v_pk_add_f32 v[116:117], v[112:113], v[190:191]
	v_pk_add_f32 v[184:185], v[118:119], v[188:189]
	v_pk_add_f32 v[112:113], v[114:115], v[170:171]
	v_pk_fma_f32 v[174:175], v[176:177], v[176:177], v[174:175]
	v_pk_fma_f32 v[182:183], v[184:185], v[184:185], v[182:183]
	v_pk_fma_f32 v[174:175], v[116:117], v[116:117], v[174:175]
	v_pk_fma_f32 v[182:183], v[112:113], v[112:113], v[182:183]
	v_pk_add_f32 v[174:175], v[174:175], v[182:183]
	v_add_f32_e32 v114, v174, v175
	v_mov_b32_e32 v115, v114
	s_nop 1
	v_permlane16_swap_b32_e32 v114, v115
	v_cndmask_b32_e32 v169, v165, v169, vcc
	v_cvt_pk_f16_f32 v119, v126, v127
	v_cvt_pk_f16_f32 v118, v124, v125
	global_store_dwordx4 v[178:179], v[118:121], off
	s_nop 1
	v_cvt_pk_f16_f32 v119, v112, v113
	s_waitcnt lgkmcnt(0)
	v_add_f32_e32 v113, v114, v115
	v_lshlrev_b32_e32 v112, 2, v169
	v_mov_b32_e32 v114, v113
	s_nop 1
	v_permlane32_swap_b32_e32 v113, v114
	v_cvt_pk_f16_f32 v118, v116, v117
	v_cvt_pk_f16_f32 v117, v184, v185
	v_cvt_pk_f16_f32 v116, v176, v177
	global_store_dwordx4 v[180:181], v[116:119], off
	s_and_saveexec_b64 s[20:21], s[6:7]
	s_cbranch_execz .LBB0_1527
	v_lshl_add_u32 v136, v167, 4, s13
	s_waitcnt lgkmcnt(0)
	v_add_f32_e32 v113, v113, v114
	v_lshl_add_u64 v[114:115], v[136:137], 2, s[42:43]
	global_store_dword v[114:115], v113, off
.LBB0_1527:
	s_or_b64 exec, exec, s[20:21]
	v_add_u32_e32 v113, 16, v167
	v_lshl_add_u32 v136, v113, 10, v168
	v_lshl_add_u64 v[122:123], v[136:137], 1, s[40:41]
	v_add_u32_e32 v136, 0x80, v136
	v_lshl_add_u64 v[124:125], v[136:137], 1, s[40:41]
	s_waitcnt lgkmcnt(0)
	s_waitcnt vmcnt(10)
	v_cvt_f32_f16_e32 v126, v195
	v_cvt_f32_f16_sdwa v127, v195 dst_sel:DWORD dst_unused:UNUSED_PAD src0_sel:WORD_1
	v_cvt_f32_f16_e32 v170, v193
	v_cvt_f32_f16_sdwa v171, v193 dst_sel:DWORD dst_unused:UNUSED_PAD src0_sel:WORD_1
	v_cvt_f32_f16_e32 v172, v194
	v_cvt_f32_f16_sdwa v173, v194 dst_sel:DWORD dst_unused:UNUSED_PAD src0_sel:WORD_1
	v_cvt_f32_f16_e32 v116, v192
	v_cvt_f32_f16_sdwa v117, v192 dst_sel:DWORD dst_unused:UNUSED_PAD src0_sel:WORD_1
	v_cvt_f32_f16_e32 v114, v199
	v_cvt_f32_f16_sdwa v115, v199 dst_sel:DWORD dst_unused:UNUSED_PAD src0_sel:WORD_1
	v_cvt_f32_f16_e32 v174, v197
	v_cvt_f32_f16_sdwa v175, v197 dst_sel:DWORD dst_unused:UNUSED_PAD src0_sel:WORD_1
	v_cvt_f32_f16_e32 v176, v198
	v_cvt_f32_f16_sdwa v177, v198 dst_sel:DWORD dst_unused:UNUSED_PAD src0_sel:WORD_1
	v_cvt_f32_f16_e32 v120, v196
	v_cvt_f32_f16_sdwa v121, v196 dst_sel:DWORD dst_unused:UNUSED_PAD src0_sel:WORD_1
	v_pk_add_f32 v[108:109], v[108:109], v[116:117]
	v_pk_add_f32 v[116:117], v[104:105], v[172:173]
	v_pk_add_f32 v[110:111], v[110:111], v[170:171]
	v_pk_add_f32 v[106:107], v[106:107], v[126:127]
	v_pk_add_f32 v[120:121], v[100:101], v[120:121]
	v_pk_add_f32 v[170:171], v[96:97], v[176:177]
	v_pk_add_f32 v[172:173], v[102:103], v[174:175]
	v_pk_add_f32 v[96:97], v[98:99], v[114:115]
	v_cvt_pk_f16_f32 v105, v106, v107
	v_cvt_pk_f16_f32 v104, v116, v117
	v_pk_mul_f32 v[118:119], v[108:109], v[108:109]
	v_pk_mul_f32 v[126:127], v[110:111], v[110:111]
	v_pk_fma_f32 v[118:119], v[116:117], v[116:117], v[118:119]
	v_pk_fma_f32 v[126:127], v[106:107], v[106:107], v[126:127]
	v_pk_fma_f32 v[118:119], v[120:121], v[120:121], v[118:119]
	v_pk_fma_f32 v[126:127], v[172:173], v[172:173], v[126:127]
	v_pk_fma_f32 v[118:119], v[170:171], v[170:171], v[118:119]
	v_pk_fma_f32 v[126:127], v[96:97], v[96:97], v[126:127]
	v_pk_add_f32 v[118:119], v[118:119], v[126:127]
	v_add_f32_e32 v98, v118, v119
	v_mov_b32_e32 v99, v98
	s_nop 1
	v_permlane16_swap_b32_e32 v98, v99
	v_cvt_pk_f16_f32 v101, v96, v97
	v_cvt_pk_f16_f32 v103, v110, v111
	v_cvt_pk_f16_f32 v102, v108, v109
	v_cvt_pk_f16_f32 v100, v170, v171
	s_waitcnt lgkmcnt(0)
	v_add_f32_e32 v96, v98, v99
	v_mov_b32_e32 v97, v96
	s_nop 1
	v_permlane32_swap_b32_e32 v96, v97
	v_cvt_pk_f16_f32 v99, v172, v173
	v_cvt_pk_f16_f32 v98, v120, v121
	global_store_dwordx4 v[122:123], v[102:105], off
	global_store_dwordx4 v[124:125], v[98:101], off
	s_and_saveexec_b64 s[20:21], s[6:7]
	s_cbranch_execz .LBB0_1529
	v_lshl_add_u32 v136, v113, 4, s13
	s_waitcnt lgkmcnt(0)
	v_add_f32_e32 v98, v96, v97
	v_lshl_add_u64 v[96:97], v[136:137], 2, s[42:43]
	global_store_dword v[96:97], v98, off
;   __device__ __forceinline__ void operator()(const pg8::f32x4 (&acc)[2][2][4][2], const pg8::Unit& u, int wr, int wc, int fr, int fq) const {
;     ...
;       for (int m = 0; m < 4; ++m) {
;         const int tok = row0 + ai * 128 + m * 16; float ss = 0.f;
; #pragma unroll
;         for (int bj = 0; bj < 2; ++bj) {
;           const unsigned off = (unsigned)tok * DM + colb + 128 * bj;
;           f8_t n = __builtin_convertvector(*(const h8_t*)(x16 + off), f8_t);
; #pragma unroll
;           for (int c = 0; c < 4; ++c) { n[c] += sc * acc[ai][bj][m][0][c]; n[4 + c] += sc * acc[ai][bj][m][1][c]; }
;           if (aux) {
;             *(h8_t*)(x16 + off) = __builtin_convertvector(n, h8_t);
;             ss += ((n[0] * n[0] + n[1] * n[1]) + (n[2] * n[2] + n[3] * n[3])) + ((n[4] * n[4] + n[5] * n[5]) + (n[6] * n[6] + n[7] * n[7]));
;           } else {
;             *(f32x4*)(xout + off) = (f32x4){n[0], n[1], n[2], n[3]}; *(f32x4*)(xout + off + 4) = (f32x4){n[4], n[5], n[6], n[7]};
;           }
;         }
;         if (aux) { ss += __shfl_xor(ss, 16); ss += __shfl_xor(ss, 32); if (fq == 0) ssq[(unsigned)tok * 16 + u.pn * 4 + wc] = ss; }
;         if (m & 1) asm volatile("" ::: "memory");
;       }
.LBB0_1529:
	s_or_b64 exec, exec, s[20:21]
	v_add_u32_e32 v96, 32, v167
	v_lshl_add_u32 v136, v96, 10, v168
	v_lshl_add_u64 v[106:107], v[136:137], 1, s[40:41]
	v_add_u32_e32 v136, 0x80, v136
	v_lshl_add_u64 v[108:109], v[136:137], 1, s[40:41]
	s_waitcnt vmcnt(10)
	v_cvt_f32_f16_e32 v110, v203
	v_cvt_f32_f16_sdwa v111, v203 dst_sel:DWORD dst_unused:UNUSED_PAD src0_sel:WORD_1
	v_cvt_f32_f16_e32 v114, v201
	v_cvt_f32_f16_sdwa v115, v201 dst_sel:DWORD dst_unused:UNUSED_PAD src0_sel:WORD_1
	v_cvt_f32_f16_e32 v116, v202
	v_cvt_f32_f16_sdwa v117, v202 dst_sel:DWORD dst_unused:UNUSED_PAD src0_sel:WORD_1
	v_cvt_f32_f16_e32 v100, v200
	v_cvt_f32_f16_sdwa v101, v200 dst_sel:DWORD dst_unused:UNUSED_PAD src0_sel:WORD_1
	v_cvt_f32_f16_e32 v98, v207
	v_cvt_f32_f16_sdwa v99, v207 dst_sel:DWORD dst_unused:UNUSED_PAD src0_sel:WORD_1
	v_cvt_f32_f16_e32 v118, v205
	v_cvt_f32_f16_sdwa v119, v205 dst_sel:DWORD dst_unused:UNUSED_PAD src0_sel:WORD_1
	v_cvt_f32_f16_e32 v120, v206
	v_cvt_f32_f16_sdwa v121, v206 dst_sel:DWORD dst_unused:UNUSED_PAD src0_sel:WORD_1
	v_cvt_f32_f16_e32 v104, v204
	v_cvt_f32_f16_sdwa v105, v204 dst_sel:DWORD dst_unused:UNUSED_PAD src0_sel:WORD_1
	v_pk_add_f32 v[92:93], v[92:93], v[100:101]
	v_pk_add_f32 v[100:101], v[88:89], v[116:117]
	v_pk_add_f32 v[94:95], v[94:95], v[114:115]
	v_pk_add_f32 v[90:91], v[90:91], v[110:111]
	v_cvt_pk_f16_f32 v88, v100, v101
	v_cvt_pk_f16_f32 v89, v90, v91
	v_pk_mul_f32 v[102:103], v[92:93], v[92:93]
	v_pk_mul_f32 v[110:111], v[94:95], v[94:95]
	v_pk_fma_f32 v[102:103], v[100:101], v[100:101], v[102:103]
	v_pk_fma_f32 v[110:111], v[90:91], v[90:91], v[110:111]
	v_pk_add_f32 v[104:105], v[84:85], v[104:105]
	v_pk_add_f32 v[114:115], v[80:81], v[120:121]
	v_pk_add_f32 v[116:117], v[86:87], v[118:119]
	v_pk_add_f32 v[80:81], v[82:83], v[98:99]
	v_pk_fma_f32 v[102:103], v[104:105], v[104:105], v[102:103]
	v_pk_fma_f32 v[110:111], v[116:117], v[116:117], v[110:111]
	v_pk_fma_f32 v[102:103], v[114:115], v[114:115], v[102:103]
	v_pk_fma_f32 v[110:111], v[80:81], v[80:81], v[110:111]
	s_waitcnt lgkmcnt(0)
	v_pk_add_f32 v[102:103], v[102:103], v[110:111]
	v_add_f32_e32 v82, v102, v103
	v_mov_b32_e32 v83, v82
	s_nop 1
	v_permlane16_swap_b32_e32 v82, v83
	v_cvt_pk_f16_f32 v85, v80, v81
	v_cvt_pk_f16_f32 v87, v94, v95
	v_cvt_pk_f16_f32 v86, v92, v93
	v_cvt_pk_f16_f32 v84, v114, v115
	s_waitcnt lgkmcnt(0)
	v_add_f32_e32 v80, v82, v83
	v_mov_b32_e32 v81, v80
	s_nop 1
	v_permlane32_swap_b32_e32 v80, v81
	v_cvt_pk_f16_f32 v83, v116, v117
	v_cvt_pk_f16_f32 v82, v104, v105
	global_store_dwordx4 v[106:107], v[86:89], off
	global_store_dwordx4 v[108:109], v[82:85], off
	s_and_saveexec_b64 s[20:21], s[6:7]
	s_cbranch_execz .LBB0_1531
	v_lshl_add_u32 v136, v96, 4, s13
	s_waitcnt lgkmcnt(0)
	v_add_f32_e32 v82, v80, v81
	v_lshl_add_u64 v[80:81], v[136:137], 2, s[42:43]
	global_store_dword v[80:81], v82, off
.LBB0_1531:
	s_or_b64 exec, exec, s[20:21]
	v_add_u32_e32 v80, 48, v167
	v_lshl_add_u32 v136, v80, 10, v168
	v_lshl_add_u64 v[90:91], v[136:137], 1, s[40:41]
	v_add_u32_e32 v136, 0x80, v136
	v_lshl_add_u64 v[92:93], v[136:137], 1, s[40:41]
	s_waitcnt vmcnt(10)
	v_cvt_f32_f16_e32 v94, v211
	v_cvt_f32_f16_sdwa v95, v211 dst_sel:DWORD dst_unused:UNUSED_PAD src0_sel:WORD_1
	v_cvt_f32_f16_e32 v96, v209
	v_cvt_f32_f16_sdwa v97, v209 dst_sel:DWORD dst_unused:UNUSED_PAD src0_sel:WORD_1
	v_cvt_f32_f16_e32 v98, v210
	v_cvt_f32_f16_sdwa v99, v210 dst_sel:DWORD dst_unused:UNUSED_PAD src0_sel:WORD_1
	v_cvt_f32_f16_e32 v84, v208
	v_cvt_f32_f16_sdwa v85, v208 dst_sel:DWORD dst_unused:UNUSED_PAD src0_sel:WORD_1
	v_cvt_f32_f16_e32 v82, v215
	v_cvt_f32_f16_sdwa v83, v215 dst_sel:DWORD dst_unused:UNUSED_PAD src0_sel:WORD_1
	v_cvt_f32_f16_e32 v100, v213
	v_cvt_f32_f16_sdwa v101, v213 dst_sel:DWORD dst_unused:UNUSED_PAD src0_sel:WORD_1
	v_cvt_f32_f16_e32 v102, v214
	v_cvt_f32_f16_sdwa v103, v214 dst_sel:DWORD dst_unused:UNUSED_PAD src0_sel:WORD_1
	v_cvt_f32_f16_e32 v88, v212
	v_cvt_f32_f16_sdwa v89, v212 dst_sel:DWORD dst_unused:UNUSED_PAD src0_sel:WORD_1
	v_pk_add_f32 v[76:77], v[76:77], v[84:85]
	v_pk_add_f32 v[84:85], v[72:73], v[98:99]
	v_pk_add_f32 v[78:79], v[78:79], v[96:97]
	v_pk_add_f32 v[74:75], v[74:75], v[94:95]
	v_cvt_pk_f16_f32 v72, v84, v85
	v_cvt_pk_f16_f32 v73, v74, v75
	v_pk_mul_f32 v[86:87], v[76:77], v[76:77]
	v_pk_mul_f32 v[94:95], v[78:79], v[78:79]
	v_pk_fma_f32 v[86:87], v[84:85], v[84:85], v[86:87]
	v_pk_fma_f32 v[94:95], v[74:75], v[74:75], v[94:95]
	v_pk_add_f32 v[88:89], v[68:69], v[88:89]
	v_pk_add_f32 v[96:97], v[64:65], v[102:103]
	v_pk_add_f32 v[98:99], v[70:71], v[100:101]
	v_pk_add_f32 v[64:65], v[66:67], v[82:83]
	v_pk_fma_f32 v[86:87], v[88:89], v[88:89], v[86:87]
	v_pk_fma_f32 v[94:95], v[98:99], v[98:99], v[94:95]
	v_pk_fma_f32 v[86:87], v[96:97], v[96:97], v[86:87]
	v_pk_fma_f32 v[94:95], v[64:65], v[64:65], v[94:95]
	s_waitcnt lgkmcnt(0)
	v_pk_add_f32 v[86:87], v[86:87], v[94:95]
	v_add_f32_e32 v66, v86, v87
	v_mov_b32_e32 v67, v66
	s_nop 1
	v_permlane16_swap_b32_e32 v66, v67
	v_cvt_pk_f16_f32 v69, v64, v65
	v_cvt_pk_f16_f32 v71, v78, v79
	v_cvt_pk_f16_f32 v70, v76, v77
	v_cvt_pk_f16_f32 v68, v96, v97
	s_waitcnt lgkmcnt(0)
	v_add_f32_e32 v64, v66, v67
	v_mov_b32_e32 v65, v64
	s_nop 1
	v_permlane32_swap_b32_e32 v64, v65
	v_cvt_pk_f16_f32 v67, v98, v99
	v_cvt_pk_f16_f32 v66, v88, v89
	global_store_dwordx4 v[90:91], v[70:73], off
	global_store_dwordx4 v[92:93], v[66:69], off
	s_and_saveexec_b64 s[20:21], s[6:7]
	s_cbranch_execz .LBB0_1533
	v_lshl_add_u32 v136, v80, 4, s13
	s_waitcnt lgkmcnt(0)
	v_add_f32_e32 v66, v64, v65
	v_lshl_add_u64 v[64:65], v[136:137], 2, s[42:43]
	global_store_dword v[64:65], v66, off
;   __device__ __forceinline__ void operator()(const pg8::f32x4 (&acc)[2][2][4][2], const pg8::Unit& u, int wr, int wc, int fr, int fq) const {
;     ...
;       for (int m = 0; m < 4; ++m) {
;         const int tok = row0 + ai * 128 + m * 16; float ss = 0.f;
; #pragma unroll
;         for (int bj = 0; bj < 2; ++bj) {
;           const unsigned off = (unsigned)tok * DM + colb + 128 * bj;
;           f8_t n = __builtin_convertvector(*(const h8_t*)(x16 + off), f8_t);
; #pragma unroll
;           for (int c = 0; c < 4; ++c) { n[c] += sc * acc[ai][bj][m][0][c]; n[4 + c] += sc * acc[ai][bj][m][1][c]; }
;           if (aux) {
;             *(h8_t*)(x16 + off) = __builtin_convertvector(n, h8_t);
;             ss += ((n[0] * n[0] + n[1] * n[1]) + (n[2] * n[2] + n[3] * n[3])) + ((n[4] * n[4] + n[5] * n[5]) + (n[6] * n[6] + n[7] * n[7]));
;           } else {
;             *(f32x4*)(xout + off) = (f32x4){n[0], n[1], n[2], n[3]}; *(f32x4*)(xout + off + 4) = (f32x4){n[4], n[5], n[6], n[7]};
;           }
;         }
;         if (aux) { ss += __shfl_xor(ss, 16); ss += __shfl_xor(ss, 32); if (fq == 0) ssq[(unsigned)tok * 16 + u.pn * 4 + wc] = ss; }
;         if (m & 1) asm volatile("" ::: "memory");
;       }
.LBB0_1533:
	s_or_b64 exec, exec, s[20:21]
	v_add_u32_e32 v64, 0x80, v167
	v_lshl_add_u32 v136, v64, 10, v168
	v_lshl_add_u64 v[74:75], v[136:137], 1, s[40:41]
	v_add_u32_e32 v136, 0x80, v136
	v_lshl_add_u64 v[76:77], v[136:137], 1, s[40:41]
	s_waitcnt vmcnt(10)
	v_cvt_f32_f16_e32 v78, v219
	v_cvt_f32_f16_sdwa v79, v219 dst_sel:DWORD dst_unused:UNUSED_PAD src0_sel:WORD_1
	v_cvt_f32_f16_e32 v80, v217
	v_cvt_f32_f16_sdwa v81, v217 dst_sel:DWORD dst_unused:UNUSED_PAD src0_sel:WORD_1
	v_cvt_f32_f16_e32 v82, v218
	v_cvt_f32_f16_sdwa v83, v218 dst_sel:DWORD dst_unused:UNUSED_PAD src0_sel:WORD_1
	v_cvt_f32_f16_e32 v68, v216
	v_cvt_f32_f16_sdwa v69, v216 dst_sel:DWORD dst_unused:UNUSED_PAD src0_sel:WORD_1
	v_cvt_f32_f16_e32 v66, v223
	v_cvt_f32_f16_sdwa v67, v223 dst_sel:DWORD dst_unused:UNUSED_PAD src0_sel:WORD_1
	v_cvt_f32_f16_e32 v84, v221
	v_cvt_f32_f16_sdwa v85, v221 dst_sel:DWORD dst_unused:UNUSED_PAD src0_sel:WORD_1
	v_cvt_f32_f16_e32 v86, v222
	v_cvt_f32_f16_sdwa v87, v222 dst_sel:DWORD dst_unused:UNUSED_PAD src0_sel:WORD_1
	v_cvt_f32_f16_e32 v72, v220
	v_cvt_f32_f16_sdwa v73, v220 dst_sel:DWORD dst_unused:UNUSED_PAD src0_sel:WORD_1
	v_pk_add_f32 v[60:61], v[60:61], v[68:69]
	v_pk_add_f32 v[68:69], v[56:57], v[82:83]
	v_pk_add_f32 v[62:63], v[62:63], v[80:81]
	v_pk_add_f32 v[58:59], v[58:59], v[78:79]
	v_cvt_pk_f16_f32 v56, v68, v69
	v_cvt_pk_f16_f32 v57, v58, v59
	v_pk_mul_f32 v[70:71], v[60:61], v[60:61]
	v_pk_mul_f32 v[78:79], v[62:63], v[62:63]
	v_pk_fma_f32 v[70:71], v[68:69], v[68:69], v[70:71]
	v_pk_fma_f32 v[78:79], v[58:59], v[58:59], v[78:79]
	v_pk_add_f32 v[72:73], v[52:53], v[72:73]
	v_pk_add_f32 v[80:81], v[48:49], v[86:87]
	v_pk_add_f32 v[82:83], v[54:55], v[84:85]
	v_pk_add_f32 v[48:49], v[50:51], v[66:67]
	v_pk_fma_f32 v[70:71], v[72:73], v[72:73], v[70:71]
	v_pk_fma_f32 v[78:79], v[82:83], v[82:83], v[78:79]
	v_pk_fma_f32 v[70:71], v[80:81], v[80:81], v[70:71]
	v_pk_fma_f32 v[78:79], v[48:49], v[48:49], v[78:79]
	s_waitcnt lgkmcnt(0)
	v_pk_add_f32 v[70:71], v[70:71], v[78:79]
	v_add_f32_e32 v50, v70, v71
	v_mov_b32_e32 v51, v50
	s_nop 1
	v_permlane16_swap_b32_e32 v50, v51
	v_cvt_pk_f16_f32 v53, v48, v49
	v_cvt_pk_f16_f32 v55, v62, v63
	v_cvt_pk_f16_f32 v54, v60, v61
	v_cvt_pk_f16_f32 v52, v80, v81
	s_waitcnt lgkmcnt(0)
	v_add_f32_e32 v48, v50, v51
	v_mov_b32_e32 v49, v48
	s_nop 1
	v_permlane32_swap_b32_e32 v48, v49
	v_cvt_pk_f16_f32 v51, v82, v83
	v_cvt_pk_f16_f32 v50, v72, v73
	global_store_dwordx4 v[74:75], v[54:57], off
	global_store_dwordx4 v[76:77], v[50:53], off
	s_and_saveexec_b64 s[20:21], s[6:7]
	s_cbranch_execz .LBB0_1535
	v_lshl_add_u32 v136, v64, 4, s13
	s_waitcnt lgkmcnt(0)
	v_add_f32_e32 v50, v48, v49
	v_lshl_add_u64 v[48:49], v[136:137], 2, s[42:43]
	global_store_dword v[48:49], v50, off
.LBB0_1535:
	s_or_b64 exec, exec, s[20:21]
	v_add_u32_e32 v48, 0x90, v167
	v_lshl_add_u32 v136, v48, 10, v168
	v_lshl_add_u64 v[58:59], v[136:137], 1, s[40:41]
	v_add_u32_e32 v136, 0x80, v136
	v_lshl_add_u64 v[60:61], v[136:137], 1, s[40:41]
	s_waitcnt vmcnt(10)
	v_cvt_f32_f16_e32 v62, v231
	v_cvt_f32_f16_sdwa v63, v231 dst_sel:DWORD dst_unused:UNUSED_PAD src0_sel:WORD_1
	v_cvt_f32_f16_e32 v64, v229
	v_cvt_f32_f16_sdwa v65, v229 dst_sel:DWORD dst_unused:UNUSED_PAD src0_sel:WORD_1
	v_cvt_f32_f16_e32 v66, v230
	v_cvt_f32_f16_sdwa v67, v230 dst_sel:DWORD dst_unused:UNUSED_PAD src0_sel:WORD_1
	v_cvt_f32_f16_e32 v52, v228
	v_cvt_f32_f16_sdwa v53, v228 dst_sel:DWORD dst_unused:UNUSED_PAD src0_sel:WORD_1
	v_cvt_f32_f16_e32 v50, v247
	v_cvt_f32_f16_sdwa v51, v247 dst_sel:DWORD dst_unused:UNUSED_PAD src0_sel:WORD_1
	v_cvt_f32_f16_e32 v68, v245
	v_cvt_f32_f16_sdwa v69, v245 dst_sel:DWORD dst_unused:UNUSED_PAD src0_sel:WORD_1
	v_cvt_f32_f16_e32 v70, v246
	v_cvt_f32_f16_sdwa v71, v246 dst_sel:DWORD dst_unused:UNUSED_PAD src0_sel:WORD_1
	v_cvt_f32_f16_e32 v56, v244
	v_cvt_f32_f16_sdwa v57, v244 dst_sel:DWORD dst_unused:UNUSED_PAD src0_sel:WORD_1
	v_pk_add_f32 v[44:45], v[44:45], v[52:53]
	v_pk_add_f32 v[52:53], v[40:41], v[66:67]
	v_pk_add_f32 v[46:47], v[46:47], v[64:65]
	v_pk_add_f32 v[42:43], v[42:43], v[62:63]
	v_cvt_pk_f16_f32 v40, v52, v53
	v_cvt_pk_f16_f32 v41, v42, v43
	v_pk_mul_f32 v[54:55], v[44:45], v[44:45]
	v_pk_mul_f32 v[62:63], v[46:47], v[46:47]
	v_pk_fma_f32 v[54:55], v[52:53], v[52:53], v[54:55]
	v_pk_fma_f32 v[62:63], v[42:43], v[42:43], v[62:63]
	v_pk_add_f32 v[56:57], v[36:37], v[56:57]
	v_pk_add_f32 v[64:65], v[32:33], v[70:71]
	v_pk_add_f32 v[66:67], v[38:39], v[68:69]
	v_pk_add_f32 v[32:33], v[34:35], v[50:51]
	v_pk_fma_f32 v[54:55], v[56:57], v[56:57], v[54:55]
	v_pk_fma_f32 v[62:63], v[66:67], v[66:67], v[62:63]
	v_pk_fma_f32 v[54:55], v[64:65], v[64:65], v[54:55]
	v_pk_fma_f32 v[62:63], v[32:33], v[32:33], v[62:63]
	s_waitcnt lgkmcnt(0)
	v_pk_add_f32 v[54:55], v[54:55], v[62:63]
	v_add_f32_e32 v34, v54, v55
	v_mov_b32_e32 v35, v34
	s_nop 1
	v_permlane16_swap_b32_e32 v34, v35
	v_cvt_pk_f16_f32 v37, v32, v33
	v_cvt_pk_f16_f32 v39, v46, v47
	v_cvt_pk_f16_f32 v38, v44, v45
	v_cvt_pk_f16_f32 v36, v64, v65
	s_waitcnt lgkmcnt(0)
	v_add_f32_e32 v32, v34, v35
	v_mov_b32_e32 v33, v32
	s_nop 1
	v_permlane32_swap_b32_e32 v32, v33
	v_cvt_pk_f16_f32 v35, v66, v67
	v_cvt_pk_f16_f32 v34, v56, v57
	global_store_dwordx4 v[58:59], v[38:41], off
	global_store_dwordx4 v[60:61], v[34:37], off
	s_and_saveexec_b64 s[20:21], s[6:7]
	s_cbranch_execz .LBB0_1537
	v_lshl_add_u32 v136, v48, 4, s13
	s_waitcnt lgkmcnt(0)
	v_add_f32_e32 v34, v32, v33
	v_lshl_add_u64 v[32:33], v[136:137], 2, s[42:43]
	global_store_dword v[32:33], v34, off
;   __device__ __forceinline__ void operator()(const pg8::f32x4 (&acc)[2][2][4][2], const pg8::Unit& u, int wr, int wc, int fr, int fq) const {
;     ...
;       for (int m = 0; m < 4; ++m) {
;         const int tok = row0 + ai * 128 + m * 16; float ss = 0.f;
; #pragma unroll
;         for (int bj = 0; bj < 2; ++bj) {
;           const unsigned off = (unsigned)tok * DM + colb + 128 * bj;
;           f8_t n = __builtin_convertvector(*(const h8_t*)(x16 + off), f8_t);
; #pragma unroll
;           for (int c = 0; c < 4; ++c) { n[c] += sc * acc[ai][bj][m][0][c]; n[4 + c] += sc * acc[ai][bj][m][1][c]; }
;           if (aux) {
;             *(h8_t*)(x16 + off) = __builtin_convertvector(n, h8_t);
;             ss += ((n[0] * n[0] + n[1] * n[1]) + (n[2] * n[2] + n[3] * n[3])) + ((n[4] * n[4] + n[5] * n[5]) + (n[6] * n[6] + n[7] * n[7]));
;           } else {
;             *(f32x4*)(xout + off) = (f32x4){n[0], n[1], n[2], n[3]}; *(f32x4*)(xout + off + 4) = (f32x4){n[4], n[5], n[6], n[7]};
;           }
;         }
;         if (aux) { ss += __shfl_xor(ss, 16); ss += __shfl_xor(ss, 32); if (fq == 0) ssq[(unsigned)tok * 16 + u.pn * 4 + wc] = ss; }
;         if (m & 1) asm volatile("" ::: "memory");
;       }
.LBB0_1537:
	s_or_b64 exec, exec, s[20:21]
	v_add_u32_e32 v32, 0xa0, v167
	v_lshl_add_u32 v136, v32, 10, v168
	v_lshl_add_u64 v[42:43], v[136:137], 1, s[40:41]
	v_add_u32_e32 v136, 0x80, v136
	global_load_dwordx4 v[34:37], v[42:43], off
	v_lshl_add_u64 v[44:45], v[136:137], 1, s[40:41]
	global_load_dwordx4 v[38:41], v[44:45], off
	s_waitcnt vmcnt(1)
	v_cvt_f32_f16_e32 v46, v37
	v_cvt_f32_f16_sdwa v47, v37 dst_sel:DWORD dst_unused:UNUSED_PAD src0_sel:WORD_1
	v_cvt_f32_f16_e32 v48, v35
	v_cvt_f32_f16_sdwa v49, v35 dst_sel:DWORD dst_unused:UNUSED_PAD src0_sel:WORD_1
	v_cvt_f32_f16_e32 v50, v36
	v_cvt_f32_f16_sdwa v51, v36 dst_sel:DWORD dst_unused:UNUSED_PAD src0_sel:WORD_1
	v_cvt_f32_f16_e32 v36, v34
	v_cvt_f32_f16_sdwa v37, v34 dst_sel:DWORD dst_unused:UNUSED_PAD src0_sel:WORD_1
	s_waitcnt vmcnt(0)
	v_cvt_f32_f16_e32 v34, v41
	v_cvt_f32_f16_sdwa v35, v41 dst_sel:DWORD dst_unused:UNUSED_PAD src0_sel:WORD_1
	v_cvt_f32_f16_e32 v52, v39
	v_cvt_f32_f16_sdwa v53, v39 dst_sel:DWORD dst_unused:UNUSED_PAD src0_sel:WORD_1
	v_cvt_f32_f16_e32 v54, v40
	v_cvt_f32_f16_sdwa v55, v40 dst_sel:DWORD dst_unused:UNUSED_PAD src0_sel:WORD_1
	v_cvt_f32_f16_e32 v40, v38
	v_cvt_f32_f16_sdwa v41, v38 dst_sel:DWORD dst_unused:UNUSED_PAD src0_sel:WORD_1
	v_pk_add_f32 v[28:29], v[28:29], v[36:37]
	v_pk_add_f32 v[36:37], v[24:25], v[50:51]
	v_pk_add_f32 v[30:31], v[30:31], v[48:49]
	v_pk_add_f32 v[26:27], v[26:27], v[46:47]
	v_cvt_pk_f16_f32 v24, v36, v37
	v_cvt_pk_f16_f32 v25, v26, v27
	v_pk_mul_f32 v[38:39], v[28:29], v[28:29]
	v_pk_mul_f32 v[46:47], v[30:31], v[30:31]
	v_pk_fma_f32 v[38:39], v[36:37], v[36:37], v[38:39]
	v_pk_fma_f32 v[46:47], v[26:27], v[26:27], v[46:47]
	v_pk_add_f32 v[40:41], v[20:21], v[40:41]
	v_pk_add_f32 v[48:49], v[16:17], v[54:55]
	v_pk_add_f32 v[50:51], v[22:23], v[52:53]
	v_pk_add_f32 v[16:17], v[18:19], v[34:35]
	v_pk_fma_f32 v[38:39], v[40:41], v[40:41], v[38:39]
	v_pk_fma_f32 v[46:47], v[50:51], v[50:51], v[46:47]
	v_pk_fma_f32 v[38:39], v[48:49], v[48:49], v[38:39]
	v_pk_fma_f32 v[46:47], v[16:17], v[16:17], v[46:47]
	s_waitcnt lgkmcnt(0)
	v_pk_add_f32 v[38:39], v[38:39], v[46:47]
	v_add_f32_e32 v18, v38, v39
	v_mov_b32_e32 v19, v18
	s_nop 1
	v_permlane16_swap_b32_e32 v18, v19
	v_cvt_pk_f16_f32 v21, v16, v17
	v_cvt_pk_f16_f32 v23, v30, v31
	v_cvt_pk_f16_f32 v22, v28, v29
	v_cvt_pk_f16_f32 v20, v48, v49
	s_waitcnt lgkmcnt(0)
	v_add_f32_e32 v16, v18, v19
	v_mov_b32_e32 v17, v16
	s_nop 1
	v_permlane32_swap_b32_e32 v16, v17
	v_cvt_pk_f16_f32 v19, v50, v51
	v_cvt_pk_f16_f32 v18, v40, v41
	global_store_dwordx4 v[42:43], v[22:25], off
	global_store_dwordx4 v[44:45], v[18:21], off
	s_and_saveexec_b64 s[20:21], s[6:7]
	s_cbranch_execz .LBB0_1539
	v_lshl_add_u32 v136, v32, 4, s13
	s_waitcnt lgkmcnt(0)
	v_add_f32_e32 v18, v16, v17
	v_lshl_add_u64 v[16:17], v[136:137], 2, s[42:43]
	global_store_dword v[16:17], v18, off
.LBB0_1539:
	s_or_b64 exec, exec, s[20:21]
	v_add_u32_e32 v16, 0xb0, v167
	v_lshl_add_u32 v136, v16, 10, v168
	v_lshl_add_u64 v[26:27], v[136:137], 1, s[40:41]
	v_add_u32_e32 v136, 0x80, v136
	global_load_dwordx4 v[18:21], v[26:27], off
	v_lshl_add_u64 v[28:29], v[136:137], 1, s[40:41]
	global_load_dwordx4 v[22:25], v[28:29], off
	s_waitcnt vmcnt(1)
	v_cvt_f32_f16_e32 v30, v21
	v_cvt_f32_f16_sdwa v31, v21 dst_sel:DWORD dst_unused:UNUSED_PAD src0_sel:WORD_1
	v_cvt_f32_f16_e32 v32, v19
	v_cvt_f32_f16_sdwa v33, v19 dst_sel:DWORD dst_unused:UNUSED_PAD src0_sel:WORD_1
	v_cvt_f32_f16_e32 v34, v20
	v_cvt_f32_f16_sdwa v35, v20 dst_sel:DWORD dst_unused:UNUSED_PAD src0_sel:WORD_1
	v_cvt_f32_f16_e32 v20, v18
	v_cvt_f32_f16_sdwa v21, v18 dst_sel:DWORD dst_unused:UNUSED_PAD src0_sel:WORD_1
	s_waitcnt vmcnt(0)
	v_cvt_f32_f16_e32 v18, v25
	v_cvt_f32_f16_sdwa v19, v25 dst_sel:DWORD dst_unused:UNUSED_PAD src0_sel:WORD_1
	v_cvt_f32_f16_e32 v36, v23
	v_cvt_f32_f16_sdwa v37, v23 dst_sel:DWORD dst_unused:UNUSED_PAD src0_sel:WORD_1
	v_cvt_f32_f16_e32 v38, v24
	v_cvt_f32_f16_sdwa v39, v24 dst_sel:DWORD dst_unused:UNUSED_PAD src0_sel:WORD_1
	v_cvt_f32_f16_e32 v24, v22
	v_cvt_f32_f16_sdwa v25, v22 dst_sel:DWORD dst_unused:UNUSED_PAD src0_sel:WORD_1
	v_pk_add_f32 v[12:13], v[12:13], v[20:21]
	v_pk_add_f32 v[20:21], v[8:9], v[34:35]
	v_pk_add_f32 v[14:15], v[14:15], v[32:33]
	v_pk_add_f32 v[10:11], v[10:11], v[30:31]
	v_cvt_pk_f16_f32 v8, v20, v21
	v_cvt_pk_f16_f32 v9, v10, v11
	v_pk_mul_f32 v[22:23], v[12:13], v[12:13]
	v_pk_mul_f32 v[30:31], v[14:15], v[14:15]
	v_pk_fma_f32 v[22:23], v[20:21], v[20:21], v[22:23]
	v_pk_fma_f32 v[30:31], v[10:11], v[10:11], v[30:31]
	v_pk_add_f32 v[24:25], v[4:5], v[24:25]
	v_pk_add_f32 v[32:33], v[0:1], v[38:39]
	v_pk_add_f32 v[34:35], v[6:7], v[36:37]
	v_pk_add_f32 v[0:1], v[2:3], v[18:19]
	v_pk_fma_f32 v[22:23], v[24:25], v[24:25], v[22:23]
	v_pk_fma_f32 v[30:31], v[34:35], v[34:35], v[30:31]
	v_pk_fma_f32 v[22:23], v[32:33], v[32:33], v[22:23]
	v_pk_fma_f32 v[30:31], v[0:1], v[0:1], v[30:31]
	s_waitcnt lgkmcnt(0)
	v_pk_add_f32 v[22:23], v[22:23], v[30:31]
	v_add_f32_e32 v2, v22, v23
	v_mov_b32_e32 v3, v2
	s_nop 1
	v_permlane16_swap_b32_e32 v2, v3
	v_cvt_pk_f16_f32 v5, v0, v1
	v_cvt_pk_f16_f32 v7, v14, v15
	v_cvt_pk_f16_f32 v6, v12, v13
	v_cvt_pk_f16_f32 v4, v32, v33
	s_waitcnt lgkmcnt(0)
	v_add_f32_e32 v0, v2, v3
	v_mov_b32_e32 v1, v0
	s_nop 1
	v_permlane32_swap_b32_e32 v0, v1
	v_cvt_pk_f16_f32 v3, v34, v35
	v_cvt_pk_f16_f32 v2, v24, v25
	global_store_dwordx4 v[26:27], v[6:9], off
	global_store_dwordx4 v[28:29], v[2:5], off
	s_and_saveexec_b64 s[20:21], s[6:7]
	s_cbranch_execz .LBB0_1516
	v_lshl_add_u32 v136, v16, 4, s13
	s_waitcnt lgkmcnt(0)
	v_add_f32_e32 v2, v0, v1
	v_lshl_add_u64 v[0:1], v[136:137], 2, s[42:43]
	global_store_dword v[0:1], v2, off
	s_branch .LBB0_1516
